# P1 conv epilogue: store pairs merged into dwordx4
# baseline (speedup 1.0000x reference)
; #define LAS __attribute__((address_space(3)))
;     __device__ __forceinline__ void operator()(const f32x4 (&acc)[2][2][4][2], const Unit& u, int wr, int wc, int fr, int fq, LAS unsigned char* hb) const {
;     ...
;         asm volatile("s_waitcnt lgkmcnt(0)" ::: "memory"); __builtin_amdgcn_s_barrier(); asm volatile("" ::: "memory");
;         const int hr1 = H - 1, hr2 = (H - 2 + fr) < (H - 1) ? (H - 2 + fr) : (H - 1), hr3 = (H - 3 + fr) < (H - 1) ? (H - 3 + fr) : (H - 1);
;         const int ch0 = (u.pn - 4) * BM + chl;
; #pragma unroll
;         for (int ai = 0; ai < 2; ++ai)
; #pragma unroll
;             for (int m = 0; m < 4; ++m) { asm volatile("" ::: "memory"); __builtin_amdgcn_sched_barrier(0);
;                 const int q = 8 * ai + 4 * wr + m, prev = q > 0 ? q - 1 : 0; const int lr = ai * HALF + wr * 64 + m * 16 + fr, R = R0 + lr;
;                 const int Rc = R < 0 ? 0 : R; const int b = Rc / LL, p = Rc - b * LL;
;                 const bool ok = (lr >= H && R < TT);
;                 const unsigned ooff = ((unsigned)Rc * (unsigned)LDP + (unsigned)(OFF_XBC + ch0)) * 2u;
; #pragma unroll
;                 for (int bn = 0; bn < 4; ++bn) { const int bj = bn >> 1, n = bn & 1; const int co = bj * HALF + 4 * n;
;                     const unsigned woff = (unsigned)(ch0 + co) * 4u;
;                     const f32x4 w0 = *(const f32x4*)((const char*)cw + woff), w1 = *(const f32x4*)((const char*)cw + woff + XBCW * 4), w2 = *(const f32x4*)((const char*)cw + woff + 2 * XBCW * 4), w3 = *(const f32x4*)((const char*)cw + woff + 3 * XBCW * 4), bs = *(const f32x4*)((const char*)cb + woff);
;                     const LAS unsigned char* hp = hb + (prev * H * NCH + chl + co) * 2;
;                     const u32x2 q1 = *(const LAS u32x2*)(hp + hr1 * NCH * 2), q2 = *(const LAS u32x2*)(hp + hr2 * NCH * 2), q3 = *(const LAS u32x2*)(hp + hr3 * NCH * 2);
;                     const float h1[4] = {__builtin_bit_cast(float, q1.x << 16), __builtin_bit_cast(float, q1.x & 0xffff0000u), __builtin_bit_cast(float, q1.y << 16), __builtin_bit_cast(float, q1.y & 0xffff0000u)};
;                     const float h2[4] = {__builtin_bit_cast(float, q2.x << 16), __builtin_bit_cast(float, q2.x & 0xffff0000u), __builtin_bit_cast(float, q2.y << 16), __builtin_bit_cast(float, q2.y & 0xffff0000u)};
.Lp1w_skipstore:
	s_waitcnt lgkmcnt(0)
	s_barrier
	v_min_i32_e32 v136, 1, v149
	v_min_i32_e32 v146, 2, v149
	s_lshl_b32 s2, s2, 8
	s_add_i32 s22, s2, 0x3ffffc00
	v_add_u32_e32 v164, s2, v148
	v_add_u32_e32 v165, 0xfffffd00, v148
	v_lshlrev_b32_e32 v163, 9, v136
	v_lshlrev_b32_e32 v162, 9, v146
	v_add_u32_e32 v136, s17, v161
	v_max_i32_e32 v146, 0, v136
	v_mul_hi_u32 v147, v146, s56
	v_lshrrev_b32_e32 v147, 11, v147
	v_mul_u32_u24_e32 v147, 0x1010, v147
	v_sub_u32_e32 v147, v146, v147
	v_cmp_gt_i32_e64 s[4:5], s50, v136
	v_mul_lo_u32 v136, v146, s51
	v_add_u32_e32 v146, s37, v165
	v_lshl_add_u32 v166, v146, 1, s53
	v_cmp_lt_i32_e32 vcc, 2, v161
	v_add_u32_e32 v167, v166, v163
	s_and_b64 s[2:3], vcc, s[4:5]
	v_add_lshl_u32 v150, v136, v164, 1
	v_cmp_eq_u32_e64 s[8:9], 0, v147
	v_cmp_lt_u32_e64 s[6:7], 1, v147
	v_cmp_lt_u32_e64 s[4:5], 2, v147
	v_add_lshl_u32 v136, s22, v148, 2
	ds_read_b64 v[146:147], v166 offset:1024
	v_add_u32_e32 v168, v166, v162
	ds_read_b64 v[148:149], v167 offset:512
	ds_read_b64 v[184:185], v168
	v_readlane_b32 s22, v237, 58
	v_mov_b32_e32 v151, v137
	s_waitcnt lgkmcnt(0)
	v_lshlrev_b32_e32 v179, 16, v146
	v_and_b32_e32 v182, 0xffff0000, v146
	v_lshlrev_b32_e32 v173, 16, v147
	v_and_b32_e32 v174, 0xffff0000, v147
	v_lshlrev_b32_e32 v177, 16, v148
	v_and_b32_e32 v178, 0xffff0000, v148
	v_lshlrev_b32_e32 v171, 16, v149
	v_and_b32_e32 v172, 0xffff0000, v149
	v_lshlrev_b32_e32 v175, 16, v184
	v_and_b32_e32 v176, 0xffff0000, v184
	v_lshlrev_b32_e32 v169, 16, v185
	v_and_b32_e32 v170, 0xffff0000, v185
	v_readlane_b32 s23, v237, 59
	v_mov_b32_dpp v179, v124 row_shr:1 row_mask:0xf bank_mask:0xf
	v_mov_b32_dpp v177, v124 row_shr:2 row_mask:0xf bank_mask:0xf
	v_mov_b32_dpp v175, v124 row_shr:3 row_mask:0xf bank_mask:0xf
	v_mov_b32_dpp v182, v125 row_shr:1 row_mask:0xf bank_mask:0xf
	v_mov_b32_dpp v178, v125 row_shr:2 row_mask:0xf bank_mask:0xf
	v_mov_b32_dpp v176, v125 row_shr:3 row_mask:0xf bank_mask:0xf
	v_mov_b32_dpp v173, v126 row_shr:1 row_mask:0xf bank_mask:0xf
	v_mov_b32_dpp v171, v126 row_shr:2 row_mask:0xf bank_mask:0xf
	v_mov_b32_dpp v169, v126 row_shr:3 row_mask:0xf bank_mask:0xf
	v_mov_b32_dpp v174, v127 row_shr:1 row_mask:0xf bank_mask:0xf
	v_mov_b32_dpp v172, v127 row_shr:2 row_mask:0xf bank_mask:0xf
	v_mov_b32_dpp v170, v127 row_shr:3 row_mask:0xf bank_mask:0xf
	v_lshl_add_u64 v[150:151], s[22:23], 0, v[150:151]
	s_and_saveexec_b64 s[22:23], s[2:3]
	s_cbranch_execz .LBB0_185
	ds_read_b128 v[184:187], v238 offset:4096
	ds_read_b128 v[188:191], v238 offset:3072
	ds_read_b128 v[192:195], v238 offset:2048
	v_cndmask_b32_e64 v183, v182, 0, s[8:9]
	ds_read_b128 v[196:199], v238 offset:1024
	s_nop 0
	ds_read_b128 v[200:203], v238
	v_cndmask_b32_e64 v182, v179, 0, s[8:9]
	v_cndmask_b32_e64 v179, 0, v178, s[6:7]
	v_cndmask_b32_e64 v178, 0, v177, s[6:7]
	v_cndmask_b32_e64 v177, 0, v176, s[4:5]
	v_cndmask_b32_e64 v176, 0, v175, s[4:5]
	s_waitcnt lgkmcnt(0)
	v_pk_fma_f32 v[124:125], v[124:125], v[188:189], v[184:185]
	v_pk_fma_f32 v[126:127], v[126:127], v[190:191], v[186:187]
	v_pk_fma_f32 v[124:125], v[182:183], v[192:193], v[124:125]
	s_nop 0
	v_pk_fma_f32 v[124:125], v[178:179], v[196:197], v[124:125]
	s_nop 0
	v_pk_fma_f32 v[124:125], v[176:177], v[200:201], v[124:125]
	s_nop 0
	v_mul_f32_e32 v175, 0xbfb8aa3b, v125
	v_exp_f32_e32 v175, v175
	s_nop 0
	v_add_f32_e32 v175, 1.0, v175
	v_rcp_f32_e32 v177, v175
	v_mul_f32_e32 v175, 0xbfb8aa3b, v124
	v_exp_f32_e32 v175, v175
	s_nop 0
	v_add_f32_e32 v175, 1.0, v175
	v_rcp_f32_e32 v176, v175
	v_cndmask_b32_e64 v175, v174, 0, s[8:9]
	v_cndmask_b32_e64 v174, v173, 0, s[8:9]
	v_pk_fma_f32 v[126:127], v[174:175], v[194:195], v[126:127]
	v_cndmask_b32_e64 v173, 0, v172, s[6:7]
	v_cndmask_b32_e64 v172, 0, v171, s[6:7]
	v_pk_fma_f32 v[126:127], v[172:173], v[198:199], v[126:127]
	v_cndmask_b32_e64 v171, 0, v170, s[4:5]
	v_cndmask_b32_e64 v170, 0, v169, s[4:5]
	v_pk_mul_f32 v[124:125], v[124:125], v[176:177]
	v_pk_fma_f32 v[126:127], v[170:171], v[202:203], v[126:127]
	v_cvt_pk_bf16_f32 v204, v124, v125
	v_mul_f32_e32 v125, 0xbfb8aa3b, v127
	v_exp_f32_e32 v125, v125
	s_nop 0
	v_add_f32_e32 v125, 1.0, v125
	v_rcp_f32_e32 v171, v125
	v_mul_f32_e32 v125, 0xbfb8aa3b, v126
	v_exp_f32_e32 v125, v125
	s_nop 0
	v_add_f32_e32 v125, 1.0, v125
	v_rcp_f32_e32 v170, v125
	s_nop 0
	v_pk_mul_f32 v[126:127], v[126:127], v[170:171]
	s_nop 0
	v_cvt_pk_bf16_f32 v205, v126, v127
;     __device__ __forceinline__ void operator()(const f32x4 (&acc)[2][2][4][2], const Unit& u, int wr, int wc, int fr, int fq, LAS unsigned char* hb) const {
;     ...
;             for (int m = 0; m < 4; ++m) { asm volatile("" ::: "memory"); __builtin_amdgcn_sched_barrier(0);
;                 const int q = 8 * ai + 4 * wr + m, prev = q > 0 ? q - 1 : 0; const int lr = ai * HALF + wr * 64 + m * 16 + fr, R = R0 + lr;
;                 const int Rc = R < 0 ? 0 : R; const int b = Rc / LL, p = Rc - b * LL;
;                 const bool ok = (lr >= H && R < TT);
;                 const unsigned ooff = ((unsigned)Rc * (unsigned)LDP + (unsigned)(OFF_XBC + ch0)) * 2u;
; #pragma unroll
;                 for (int bn = 0; bn < 4; ++bn) { const int bj = bn >> 1, n = bn & 1; const int co = bj * HALF + 4 * n;
;                     const unsigned woff = (unsigned)(ch0 + co) * 4u;
;                     const f32x4 w0 = *(const f32x4*)((const char*)cw + woff), w1 = *(const f32x4*)((const char*)cw + woff + XBCW * 4), w2 = *(const f32x4*)((const char*)cw + woff + 2 * XBCW * 4), w3 = *(const f32x4*)((const char*)cw + woff + 3 * XBCW * 4), bs = *(const f32x4*)((const char*)cb + woff);
;                     const LAS unsigned char* hp = hb + (prev * H * NCH + chl + co) * 2;
;                     const u32x2 q1 = *(const LAS u32x2*)(hp + hr1 * NCH * 2), q2 = *(const LAS u32x2*)(hp + hr2 * NCH * 2), q3 = *(const LAS u32x2*)(hp + hr3 * NCH * 2);
;                     const float h1[4] = {__builtin_bit_cast(float, q1.x << 16), __builtin_bit_cast(float, q1.x & 0xffff0000u), __builtin_bit_cast(float, q1.y << 16), __builtin_bit_cast(float, q1.y & 0xffff0000u)};
;                     const float h2[4] = {__builtin_bit_cast(float, q2.x << 16), __builtin_bit_cast(float, q2.x & 0xffff0000u), __builtin_bit_cast(float, q2.y << 16), __builtin_bit_cast(float, q2.y & 0xffff0000u)};
;                     const float h3[4] = {__builtin_bit_cast(float, q3.x << 16), __builtin_bit_cast(float, q3.x & 0xffff0000u), __builtin_bit_cast(float, q3.y << 16), __builtin_bit_cast(float, q3.y & 0xffff0000u)};
;                     const f32x4 gv = acc[ai][bj][m][n];
;                     float o[4];
; #pragma unroll
;                     for (int j = 0; j < 4; ++j) { const float g = gv[j];
;                         float g1 = dpp_row_shr<1>(h1[j], g), g2 = dpp_row_shr<2>(h2[j], g), g3 = dpp_row_shr<3>(h3[j], g);
.LBB0_185:
	s_or_b64 exec, exec, s[22:23]
	ds_read_b64 v[124:125], v166 offset:1032
	ds_read_b64 v[126:127], v167 offset:520
	ds_read_b64 v[186:187], v168 offset:8
	v_add_u32_e32 v184, 16, v136
	v_mov_b32_e32 v185, v137
	s_waitcnt lgkmcnt(0)
	v_lshlrev_b32_e32 v179, 16, v124
	v_and_b32_e32 v182, 0xffff0000, v124
	v_lshlrev_b32_e32 v173, 16, v125
	v_and_b32_e32 v174, 0xffff0000, v125
	v_lshlrev_b32_e32 v177, 16, v126
	v_and_b32_e32 v178, 0xffff0000, v126
	v_lshlrev_b32_e32 v171, 16, v127
	v_and_b32_e32 v172, 0xffff0000, v127
	v_lshlrev_b32_e32 v175, 16, v186
	v_and_b32_e32 v176, 0xffff0000, v186
	v_lshlrev_b32_e32 v169, 16, v187
	v_and_b32_e32 v170, 0xffff0000, v187
	v_mov_b32_dpp v179, v120 row_shr:1 row_mask:0xf bank_mask:0xf
	v_mov_b32_dpp v177, v120 row_shr:2 row_mask:0xf bank_mask:0xf
	v_mov_b32_dpp v175, v120 row_shr:3 row_mask:0xf bank_mask:0xf
	v_mov_b32_dpp v182, v121 row_shr:1 row_mask:0xf bank_mask:0xf
	v_mov_b32_dpp v178, v121 row_shr:2 row_mask:0xf bank_mask:0xf
	v_mov_b32_dpp v176, v121 row_shr:3 row_mask:0xf bank_mask:0xf
	v_mov_b32_dpp v173, v122 row_shr:1 row_mask:0xf bank_mask:0xf
	v_mov_b32_dpp v171, v122 row_shr:2 row_mask:0xf bank_mask:0xf
	v_mov_b32_dpp v169, v122 row_shr:3 row_mask:0xf bank_mask:0xf
	v_mov_b32_dpp v174, v123 row_shr:1 row_mask:0xf bank_mask:0xf
	v_mov_b32_dpp v172, v123 row_shr:2 row_mask:0xf bank_mask:0xf
	v_mov_b32_dpp v170, v123 row_shr:3 row_mask:0xf bank_mask:0xf
	s_and_saveexec_b64 s[22:23], s[2:3]
	s_cbranch_execz .LBB0_187
	ds_read_b128 v[184:187], v238 offset:4112
	ds_read_b128 v[188:191], v238 offset:3088
	ds_read_b128 v[192:195], v238 offset:2064
	v_cndmask_b32_e64 v183, v182, 0, s[8:9]
	ds_read_b128 v[196:199], v238 offset:1040
	s_nop 0
	ds_read_b128 v[200:203], v238 offset:16
	v_cndmask_b32_e64 v182, v179, 0, s[8:9]
	v_cndmask_b32_e64 v179, 0, v178, s[6:7]
	v_cndmask_b32_e64 v178, 0, v177, s[6:7]
	v_cndmask_b32_e64 v177, 0, v176, s[4:5]
	v_cndmask_b32_e64 v176, 0, v175, s[4:5]
	s_waitcnt lgkmcnt(0)
	v_pk_fma_f32 v[120:121], v[120:121], v[188:189], v[184:185]
	v_pk_fma_f32 v[122:123], v[122:123], v[190:191], v[186:187]
	v_pk_fma_f32 v[120:121], v[182:183], v[192:193], v[120:121]
	s_nop 0
	v_pk_fma_f32 v[120:121], v[178:179], v[196:197], v[120:121]
	s_nop 0
	v_pk_fma_f32 v[120:121], v[176:177], v[200:201], v[120:121]
	s_nop 0
	v_mul_f32_e32 v175, 0xbfb8aa3b, v121
	v_exp_f32_e32 v175, v175
	s_nop 0
	v_add_f32_e32 v175, 1.0, v175
	v_rcp_f32_e32 v177, v175
	v_mul_f32_e32 v175, 0xbfb8aa3b, v120
	v_exp_f32_e32 v175, v175
	s_nop 0
	v_add_f32_e32 v175, 1.0, v175
	v_rcp_f32_e32 v176, v175
	v_cndmask_b32_e64 v175, v174, 0, s[8:9]
	v_cndmask_b32_e64 v174, v173, 0, s[8:9]
	v_pk_fma_f32 v[122:123], v[174:175], v[194:195], v[122:123]
	v_cndmask_b32_e64 v173, 0, v172, s[6:7]
	v_cndmask_b32_e64 v172, 0, v171, s[6:7]
	v_pk_fma_f32 v[122:123], v[172:173], v[198:199], v[122:123]
	v_cndmask_b32_e64 v171, 0, v170, s[4:5]
	v_cndmask_b32_e64 v170, 0, v169, s[4:5]
	v_pk_mul_f32 v[120:121], v[120:121], v[176:177]
	v_pk_fma_f32 v[122:123], v[170:171], v[202:203], v[122:123]
	v_cvt_pk_bf16_f32 v206, v120, v121
	v_mul_f32_e32 v121, 0xbfb8aa3b, v123
	v_exp_f32_e32 v121, v121
	s_nop 0
	v_add_f32_e32 v121, 1.0, v121
	v_rcp_f32_e32 v171, v121
	v_mul_f32_e32 v121, 0xbfb8aa3b, v122
	v_exp_f32_e32 v121, v121
	s_nop 0
	v_add_f32_e32 v121, 1.0, v121
	v_rcp_f32_e32 v170, v121
	s_nop 0
	v_pk_mul_f32 v[122:123], v[122:123], v[170:171]
	s_nop 0
	v_cvt_pk_bf16_f32 v207, v122, v123
	global_store_dwordx4 v[150:151], v[204:207], off
.LBB0_187:
	s_or_b64 exec, exec, s[22:23]
	ds_read_b64 v[120:121], v166 offset:1280
	ds_read_b64 v[122:123], v167 offset:768
	ds_read_b64 v[186:187], v168 offset:256
	v_add_u32_e32 v184, 0x200, v136
	v_mov_b32_e32 v185, v137
	s_waitcnt lgkmcnt(0)
	v_lshlrev_b32_e32 v179, 16, v120
	v_and_b32_e32 v182, 0xffff0000, v120
	v_lshlrev_b32_e32 v173, 16, v121
	v_and_b32_e32 v174, 0xffff0000, v121
	v_lshlrev_b32_e32 v177, 16, v122
	v_and_b32_e32 v178, 0xffff0000, v122
	v_lshlrev_b32_e32 v171, 16, v123
	v_and_b32_e32 v172, 0xffff0000, v123
	v_lshlrev_b32_e32 v175, 16, v186
	v_and_b32_e32 v176, 0xffff0000, v186
	v_lshlrev_b32_e32 v169, 16, v187
	v_and_b32_e32 v170, 0xffff0000, v187
	v_mov_b32_dpp v179, v116 row_shr:1 row_mask:0xf bank_mask:0xf
	v_mov_b32_dpp v177, v116 row_shr:2 row_mask:0xf bank_mask:0xf
	v_mov_b32_dpp v175, v116 row_shr:3 row_mask:0xf bank_mask:0xf
	v_mov_b32_dpp v182, v117 row_shr:1 row_mask:0xf bank_mask:0xf
	v_mov_b32_dpp v178, v117 row_shr:2 row_mask:0xf bank_mask:0xf
	v_mov_b32_dpp v176, v117 row_shr:3 row_mask:0xf bank_mask:0xf
	v_mov_b32_dpp v173, v118 row_shr:1 row_mask:0xf bank_mask:0xf
	v_mov_b32_dpp v171, v118 row_shr:2 row_mask:0xf bank_mask:0xf
	v_mov_b32_dpp v169, v118 row_shr:3 row_mask:0xf bank_mask:0xf
	v_mov_b32_dpp v174, v119 row_shr:1 row_mask:0xf bank_mask:0xf
	v_mov_b32_dpp v172, v119 row_shr:2 row_mask:0xf bank_mask:0xf
	v_mov_b32_dpp v170, v119 row_shr:3 row_mask:0xf bank_mask:0xf
	s_and_saveexec_b64 s[22:23], s[2:3]
	s_cbranch_execz .LBB0_189
	ds_read_b128 v[184:187], v238 offset:4608
	ds_read_b128 v[188:191], v238 offset:3584
	ds_read_b128 v[192:195], v238 offset:2560
	v_cndmask_b32_e64 v183, v182, 0, s[8:9]
	ds_read_b128 v[196:199], v238 offset:1536
	s_nop 0
	ds_read_b128 v[200:203], v238 offset:512
	v_cndmask_b32_e64 v182, v179, 0, s[8:9]
	v_cndmask_b32_e64 v179, 0, v178, s[6:7]
	v_cndmask_b32_e64 v178, 0, v177, s[6:7]
	v_cndmask_b32_e64 v177, 0, v176, s[4:5]
	v_cndmask_b32_e64 v176, 0, v175, s[4:5]
	s_waitcnt lgkmcnt(0)
	v_pk_fma_f32 v[116:117], v[116:117], v[188:189], v[184:185]
	v_pk_fma_f32 v[118:119], v[118:119], v[190:191], v[186:187]
	v_pk_fma_f32 v[116:117], v[182:183], v[192:193], v[116:117]
	s_nop 0
	v_pk_fma_f32 v[116:117], v[178:179], v[196:197], v[116:117]
	s_nop 0
	v_pk_fma_f32 v[116:117], v[176:177], v[200:201], v[116:117]
	s_nop 0
	v_mul_f32_e32 v175, 0xbfb8aa3b, v117
	v_exp_f32_e32 v175, v175
	s_nop 0
	v_add_f32_e32 v175, 1.0, v175
	v_rcp_f32_e32 v177, v175
	v_mul_f32_e32 v175, 0xbfb8aa3b, v116
	v_exp_f32_e32 v175, v175
	s_nop 0
	v_add_f32_e32 v175, 1.0, v175
	v_rcp_f32_e32 v176, v175
	v_cndmask_b32_e64 v175, v174, 0, s[8:9]
	v_cndmask_b32_e64 v174, v173, 0, s[8:9]
	v_pk_fma_f32 v[118:119], v[174:175], v[194:195], v[118:119]
	v_cndmask_b32_e64 v173, 0, v172, s[6:7]
	v_cndmask_b32_e64 v172, 0, v171, s[6:7]
	v_pk_fma_f32 v[118:119], v[172:173], v[198:199], v[118:119]
	v_cndmask_b32_e64 v171, 0, v170, s[4:5]
	v_cndmask_b32_e64 v170, 0, v169, s[4:5]
	v_pk_mul_f32 v[116:117], v[116:117], v[176:177]
	v_pk_fma_f32 v[118:119], v[170:171], v[202:203], v[118:119]
	v_cvt_pk_bf16_f32 v204, v116, v117
	v_mul_f32_e32 v117, 0xbfb8aa3b, v119
	v_exp_f32_e32 v117, v117
	s_nop 0
	v_add_f32_e32 v117, 1.0, v117
	v_rcp_f32_e32 v171, v117
	v_mul_f32_e32 v117, 0xbfb8aa3b, v118
	v_exp_f32_e32 v117, v117
	s_nop 0
	v_add_f32_e32 v117, 1.0, v117
	v_rcp_f32_e32 v170, v117
	s_nop 0
	v_pk_mul_f32 v[118:119], v[118:119], v[170:171]
	s_nop 0
	v_cvt_pk_bf16_f32 v205, v118, v119
;     __device__ __forceinline__ void operator()(const f32x4 (&acc)[2][2][4][2], const Unit& u, int wr, int wc, int fr, int fq, LAS unsigned char* hb) const {
;     ...
;             for (int m = 0; m < 4; ++m) { asm volatile("" ::: "memory"); __builtin_amdgcn_sched_barrier(0);
;                 const int q = 8 * ai + 4 * wr + m, prev = q > 0 ? q - 1 : 0; const int lr = ai * HALF + wr * 64 + m * 16 + fr, R = R0 + lr;
;                 const int Rc = R < 0 ? 0 : R; const int b = Rc / LL, p = Rc - b * LL;
;                 const bool ok = (lr >= H && R < TT);
;                 const unsigned ooff = ((unsigned)Rc * (unsigned)LDP + (unsigned)(OFF_XBC + ch0)) * 2u;
; #pragma unroll
;                 for (int bn = 0; bn < 4; ++bn) { const int bj = bn >> 1, n = bn & 1; const int co = bj * HALF + 4 * n;
;                     const unsigned woff = (unsigned)(ch0 + co) * 4u;
;                     const f32x4 w0 = *(const f32x4*)((const char*)cw + woff), w1 = *(const f32x4*)((const char*)cw + woff + XBCW * 4), w2 = *(const f32x4*)((const char*)cw + woff + 2 * XBCW * 4), w3 = *(const f32x4*)((const char*)cw + woff + 3 * XBCW * 4), bs = *(const f32x4*)((const char*)cb + woff);
;                     const LAS unsigned char* hp = hb + (prev * H * NCH + chl + co) * 2;
;                     const u32x2 q1 = *(const LAS u32x2*)(hp + hr1 * NCH * 2), q2 = *(const LAS u32x2*)(hp + hr2 * NCH * 2), q3 = *(const LAS u32x2*)(hp + hr3 * NCH * 2);
;                     const float h1[4] = {__builtin_bit_cast(float, q1.x << 16), __builtin_bit_cast(float, q1.x & 0xffff0000u), __builtin_bit_cast(float, q1.y << 16), __builtin_bit_cast(float, q1.y & 0xffff0000u)};
;                     const float h2[4] = {__builtin_bit_cast(float, q2.x << 16), __builtin_bit_cast(float, q2.x & 0xffff0000u), __builtin_bit_cast(float, q2.y << 16), __builtin_bit_cast(float, q2.y & 0xffff0000u)};
;                     const float h3[4] = {__builtin_bit_cast(float, q3.x << 16), __builtin_bit_cast(float, q3.x & 0xffff0000u), __builtin_bit_cast(float, q3.y << 16), __builtin_bit_cast(float, q3.y & 0xffff0000u)};
;                     const f32x4 gv = acc[ai][bj][m][n];
;                     float o[4];
; #pragma unroll
;                     for (int j = 0; j < 4; ++j) { const float g = gv[j];
;                         float g1 = dpp_row_shr<1>(h1[j], g), g2 = dpp_row_shr<2>(h2[j], g), g3 = dpp_row_shr<3>(h3[j], g);
.LBB0_189:
	s_or_b64 exec, exec, s[22:23]
	ds_read_b64 v[116:117], v166 offset:1288
	ds_read_b64 v[118:119], v167 offset:776
	ds_read_b64 v[166:167], v168 offset:264
	v_add_u32_e32 v136, 0x210, v136
	s_waitcnt lgkmcnt(0)
	v_lshlrev_b32_e32 v176, 16, v116
	v_and_b32_e32 v177, 0xffff0000, v116
	v_lshlrev_b32_e32 v170, 16, v117
	v_and_b32_e32 v171, 0xffff0000, v117
	v_lshlrev_b32_e32 v174, 16, v118
	v_and_b32_e32 v175, 0xffff0000, v118
	v_lshlrev_b32_e32 v168, 16, v119
	v_and_b32_e32 v169, 0xffff0000, v119
	v_lshlrev_b32_e32 v172, 16, v166
	v_and_b32_e32 v173, 0xffff0000, v166
	v_lshlrev_b32_e32 v166, 16, v167
	v_and_b32_e32 v167, 0xffff0000, v167
	v_mov_b32_dpp v176, v112 row_shr:1 row_mask:0xf bank_mask:0xf
	v_mov_b32_dpp v174, v112 row_shr:2 row_mask:0xf bank_mask:0xf
	v_mov_b32_dpp v172, v112 row_shr:3 row_mask:0xf bank_mask:0xf
	v_mov_b32_dpp v177, v113 row_shr:1 row_mask:0xf bank_mask:0xf
	v_mov_b32_dpp v175, v113 row_shr:2 row_mask:0xf bank_mask:0xf
	v_mov_b32_dpp v173, v113 row_shr:3 row_mask:0xf bank_mask:0xf
	v_mov_b32_dpp v170, v114 row_shr:1 row_mask:0xf bank_mask:0xf
	v_mov_b32_dpp v168, v114 row_shr:2 row_mask:0xf bank_mask:0xf
	v_mov_b32_dpp v166, v114 row_shr:3 row_mask:0xf bank_mask:0xf
	v_mov_b32_dpp v171, v115 row_shr:1 row_mask:0xf bank_mask:0xf
	v_mov_b32_dpp v169, v115 row_shr:2 row_mask:0xf bank_mask:0xf
	v_mov_b32_dpp v167, v115 row_shr:3 row_mask:0xf bank_mask:0xf
	s_and_saveexec_b64 s[22:23], s[2:3]
	s_cbranch_execz .LBB0_191
	ds_read_b128 v[182:185], v238 offset:4624
	ds_read_b128 v[186:189], v238 offset:3600
	v_cndmask_b32_e64 v177, v177, 0, s[8:9]
	ds_read_b128 v[190:193], v238 offset:2576
	v_cndmask_b32_e64 v176, v176, 0, s[8:9]
	ds_read_b128 v[194:197], v238 offset:1552
	ds_read_b128 v[198:201], v238 offset:528
	v_cndmask_b32_e64 v175, 0, v175, s[6:7]
	v_cndmask_b32_e64 v174, 0, v174, s[6:7]
	v_cndmask_b32_e64 v173, 0, v173, s[4:5]
	v_cndmask_b32_e64 v172, 0, v172, s[4:5]
	v_cndmask_b32_e64 v171, v171, 0, s[8:9]
	v_cndmask_b32_e64 v170, v170, 0, s[8:9]
	v_cndmask_b32_e64 v169, 0, v169, s[6:7]
	v_cndmask_b32_e64 v168, 0, v168, s[6:7]
	v_cndmask_b32_e64 v167, 0, v167, s[4:5]
	v_cndmask_b32_e64 v166, 0, v166, s[4:5]
	s_waitcnt lgkmcnt(0)
	v_pk_fma_f32 v[112:113], v[112:113], v[186:187], v[182:183]
	v_pk_fma_f32 v[114:115], v[114:115], v[188:189], v[184:185]
	v_pk_fma_f32 v[112:113], v[176:177], v[190:191], v[112:113]
	v_pk_fma_f32 v[114:115], v[170:171], v[192:193], v[114:115]
	v_pk_fma_f32 v[112:113], v[174:175], v[194:195], v[112:113]
	s_nop 0
	v_pk_fma_f32 v[112:113], v[172:173], v[198:199], v[112:113]
	v_pk_fma_f32 v[114:115], v[168:169], v[196:197], v[114:115]
	v_mul_f32_e32 v136, 0xbfb8aa3b, v113
	v_exp_f32_e32 v136, v136
	v_pk_fma_f32 v[114:115], v[166:167], v[200:201], v[114:115]
	v_add_f32_e32 v136, 1.0, v136
	v_rcp_f32_e32 v173, v136
	v_mul_f32_e32 v136, 0xbfb8aa3b, v112
	v_exp_f32_e32 v136, v136
	s_nop 0
	v_add_f32_e32 v136, 1.0, v136
	v_rcp_f32_e32 v172, v136
	s_nop 0
	v_pk_mul_f32 v[112:113], v[112:113], v[172:173]
	s_nop 0
	v_cvt_pk_bf16_f32 v206, v112, v113
	v_mul_f32_e32 v113, 0xbfb8aa3b, v115
	v_exp_f32_e32 v113, v113
	s_nop 0
	v_add_f32_e32 v113, 1.0, v113
	v_rcp_f32_e32 v167, v113
	v_mul_f32_e32 v113, 0xbfb8aa3b, v114
	v_exp_f32_e32 v113, v113
	s_nop 0
	v_add_f32_e32 v113, 1.0, v113
	v_rcp_f32_e32 v166, v113
	s_nop 0
	v_pk_mul_f32 v[114:115], v[114:115], v[166:167]
	s_nop 0
	v_cvt_pk_bf16_f32 v207, v114, v115
	global_store_dwordx4 v[150:151], v[204:207], off offset:256
.LBB0_191:
	s_or_b64 exec, exec, s[22:23]
	v_add_u32_e32 v112, 16, v161
	v_add_u32_e32 v113, s17, v112
	v_max_i32_e32 v114, 0, v113
	v_mul_hi_u32 v115, v114, s56
	v_lshrrev_b32_e32 v115, 11, v115
	v_cmp_lt_i32_e32 vcc, 2, v112
	v_mul_lo_u32 v112, v114, s51
	v_mul_u32_u24_e32 v115, 0x1010, v115
	v_add_lshl_u32 v136, v112, v164, 1
	v_add_u32_e32 v112, s38, v165
	v_sub_u32_e32 v115, v114, v115
	v_cmp_gt_i32_e64 s[4:5], s50, v113
	v_lshl_add_u32 v114, v112, 1, s53
	s_and_b64 s[2:3], vcc, s[4:5]
	v_cmp_eq_u32_e64 s[8:9], 0, v115
	v_cmp_lt_u32_e64 s[6:7], 1, v115
	v_cmp_lt_u32_e64 s[4:5], 2, v115
	v_add_u32_e32 v115, v114, v163
	ds_read_b64 v[112:113], v114 offset:1024
	v_add_u32_e32 v150, v114, v162
	ds_read_b64 v[178:179], v115 offset:512
	ds_read_b64 v[182:183], v150
	v_readlane_b32 s22, v237, 58
	v_readlane_b32 s23, v237, 59
	s_waitcnt lgkmcnt(0)
	v_lshlrev_b32_e32 v175, 16, v112
	v_and_b32_e32 v176, 0xffff0000, v112
	v_lshlrev_b32_e32 v169, 16, v113
	v_and_b32_e32 v170, 0xffff0000, v113
	v_lshlrev_b32_e32 v173, 16, v178
	v_and_b32_e32 v174, 0xffff0000, v178
	v_lshlrev_b32_e32 v167, 16, v179
	v_and_b32_e32 v168, 0xffff0000, v179
	v_lshlrev_b32_e32 v171, 16, v182
	v_and_b32_e32 v172, 0xffff0000, v182
	v_lshlrev_b32_e32 v151, 16, v183
	v_and_b32_e32 v166, 0xffff0000, v183
	v_mov_b32_dpp v175, v108 row_shr:1 row_mask:0xf bank_mask:0xf
	v_mov_b32_dpp v173, v108 row_shr:2 row_mask:0xf bank_mask:0xf
	v_mov_b32_dpp v171, v108 row_shr:3 row_mask:0xf bank_mask:0xf
	v_mov_b32_dpp v176, v109 row_shr:1 row_mask:0xf bank_mask:0xf
	v_mov_b32_dpp v174, v109 row_shr:2 row_mask:0xf bank_mask:0xf
	v_mov_b32_dpp v172, v109 row_shr:3 row_mask:0xf bank_mask:0xf
	v_mov_b32_dpp v169, v110 row_shr:1 row_mask:0xf bank_mask:0xf
	v_mov_b32_dpp v167, v110 row_shr:2 row_mask:0xf bank_mask:0xf
	v_mov_b32_dpp v151, v110 row_shr:3 row_mask:0xf bank_mask:0xf
	v_mov_b32_dpp v170, v111 row_shr:1 row_mask:0xf bank_mask:0xf
	v_mov_b32_dpp v168, v111 row_shr:2 row_mask:0xf bank_mask:0xf
	v_mov_b32_dpp v166, v111 row_shr:3 row_mask:0xf bank_mask:0xf
	v_lshl_add_u64 v[112:113], s[22:23], 0, v[136:137]
	s_and_saveexec_b64 s[22:23], s[2:3]
	s_cbranch_execz .LBB0_193
;     __device__ __forceinline__ void operator()(const f32x4 (&acc)[2][2][4][2], const Unit& u, int wr, int wc, int fr, int fq, LAS unsigned char* hb) const {
;     ...
;             for (int m = 0; m < 4; ++m) { asm volatile("" ::: "memory"); __builtin_amdgcn_sched_barrier(0);
;                 const int q = 8 * ai + 4 * wr + m, prev = q > 0 ? q - 1 : 0; const int lr = ai * HALF + wr * 64 + m * 16 + fr, R = R0 + lr;
;                 const int Rc = R < 0 ? 0 : R; const int b = Rc / LL, p = Rc - b * LL;
;                 const bool ok = (lr >= H && R < TT);
;                 const unsigned ooff = ((unsigned)Rc * (unsigned)LDP + (unsigned)(OFF_XBC + ch0)) * 2u;
; #pragma unroll
;                 for (int bn = 0; bn < 4; ++bn) { const int bj = bn >> 1, n = bn & 1; const int co = bj * HALF + 4 * n;
;                     const unsigned woff = (unsigned)(ch0 + co) * 4u;
;                     const f32x4 w0 = *(const f32x4*)((const char*)cw + woff), w1 = *(const f32x4*)((const char*)cw + woff + XBCW * 4), w2 = *(const f32x4*)((const char*)cw + woff + 2 * XBCW * 4), w3 = *(const f32x4*)((const char*)cw + woff + 3 * XBCW * 4), bs = *(const f32x4*)((const char*)cb + woff);
;                     const LAS unsigned char* hp = hb + (prev * H * NCH + chl + co) * 2;
;                     const u32x2 q1 = *(const LAS u32x2*)(hp + hr1 * NCH * 2), q2 = *(const LAS u32x2*)(hp + hr2 * NCH * 2), q3 = *(const LAS u32x2*)(hp + hr3 * NCH * 2);
;                     const float h1[4] = {__builtin_bit_cast(float, q1.x << 16), __builtin_bit_cast(float, q1.x & 0xffff0000u), __builtin_bit_cast(float, q1.y << 16), __builtin_bit_cast(float, q1.y & 0xffff0000u)};
;                     const float h2[4] = {__builtin_bit_cast(float, q2.x << 16), __builtin_bit_cast(float, q2.x & 0xffff0000u), __builtin_bit_cast(float, q2.y << 16), __builtin_bit_cast(float, q2.y & 0xffff0000u)};
;                     const float h3[4] = {__builtin_bit_cast(float, q3.x << 16), __builtin_bit_cast(float, q3.x & 0xffff0000u), __builtin_bit_cast(float, q3.y << 16), __builtin_bit_cast(float, q3.y & 0xffff0000u)};
;                     const f32x4 gv = acc[ai][bj][m][n];
;                     float o[4];
; #pragma unroll
;                     for (int j = 0; j < 4; ++j) { const float g = gv[j];
;                         float g1 = dpp_row_shr<1>(h1[j], g), g2 = dpp_row_shr<2>(h2[j], g), g3 = dpp_row_shr<3>(h3[j], g);
	ds_read_b128 v[182:185], v238 offset:4096
	ds_read_b128 v[186:189], v238 offset:3072
	v_cndmask_b32_e64 v177, v176, 0, s[8:9]
	ds_read_b128 v[190:193], v238 offset:2048
	v_cndmask_b32_e64 v176, v175, 0, s[8:9]
	ds_read_b128 v[194:197], v238 offset:1024
	ds_read_b128 v[198:201], v238
	v_cndmask_b32_e64 v175, 0, v174, s[6:7]
	v_cndmask_b32_e64 v174, 0, v173, s[6:7]
	v_cndmask_b32_e64 v173, 0, v172, s[4:5]
	v_cndmask_b32_e64 v172, 0, v171, s[4:5]
	v_cndmask_b32_e64 v171, v170, 0, s[8:9]
	v_cndmask_b32_e64 v170, v169, 0, s[8:9]
	v_cndmask_b32_e64 v169, 0, v168, s[6:7]
	v_cndmask_b32_e64 v168, 0, v167, s[6:7]
	v_cndmask_b32_e64 v167, 0, v166, s[4:5]
	v_cndmask_b32_e64 v166, 0, v151, s[4:5]
	s_waitcnt lgkmcnt(0)
	v_pk_fma_f32 v[108:109], v[108:109], v[186:187], v[182:183]
	v_pk_fma_f32 v[110:111], v[110:111], v[188:189], v[184:185]
	v_pk_fma_f32 v[108:109], v[176:177], v[190:191], v[108:109]
	v_pk_fma_f32 v[110:111], v[170:171], v[192:193], v[110:111]
	v_pk_fma_f32 v[108:109], v[174:175], v[194:195], v[108:109]
	s_nop 0
	v_pk_fma_f32 v[108:109], v[172:173], v[198:199], v[108:109]
	v_pk_fma_f32 v[110:111], v[168:169], v[196:197], v[110:111]
	v_mul_f32_e32 v136, 0xbfb8aa3b, v109
	v_exp_f32_e32 v136, v136
	v_pk_fma_f32 v[110:111], v[166:167], v[200:201], v[110:111]
	v_add_f32_e32 v136, 1.0, v136
	v_rcp_f32_e32 v173, v136
	v_mul_f32_e32 v136, 0xbfb8aa3b, v108
	v_exp_f32_e32 v136, v136
	s_nop 0
	v_add_f32_e32 v136, 1.0, v136
	v_rcp_f32_e32 v172, v136
	s_nop 0
	v_pk_mul_f32 v[108:109], v[108:109], v[172:173]
	s_nop 0
	v_cvt_pk_bf16_f32 v204, v108, v109
	v_mul_f32_e32 v109, 0xbfb8aa3b, v111
	v_exp_f32_e32 v109, v109
	s_nop 0
	v_add_f32_e32 v109, 1.0, v109
	v_rcp_f32_e32 v167, v109
	v_mul_f32_e32 v109, 0xbfb8aa3b, v110
	v_exp_f32_e32 v109, v109
	s_nop 0
	v_add_f32_e32 v109, 1.0, v109
	v_rcp_f32_e32 v166, v109
	s_nop 0
	v_pk_mul_f32 v[110:111], v[110:111], v[166:167]
	s_nop 0
	v_cvt_pk_bf16_f32 v205, v110, v111
.LBB0_193:
	s_or_b64 exec, exec, s[22:23]
	ds_read_b64 v[108:109], v114 offset:1032
	ds_read_b64 v[110:111], v115 offset:520
	ds_read_b64 v[172:173], v150 offset:8
	s_waitcnt lgkmcnt(0)
	v_lshlrev_b32_e32 v170, 16, v108
	v_and_b32_e32 v171, 0xffff0000, v108
	v_lshlrev_b32_e32 v136, 16, v109
	v_and_b32_e32 v151, 0xffff0000, v109
	v_lshlrev_b32_e32 v168, 16, v110
	v_and_b32_e32 v169, 0xffff0000, v110
	v_lshlrev_b32_e32 v110, 16, v111
	v_and_b32_e32 v111, 0xffff0000, v111
	v_lshlrev_b32_e32 v166, 16, v172
	v_and_b32_e32 v167, 0xffff0000, v172
	v_lshlrev_b32_e32 v108, 16, v173
	v_and_b32_e32 v109, 0xffff0000, v173
	v_mov_b32_dpp v170, v104 row_shr:1 row_mask:0xf bank_mask:0xf
	v_mov_b32_dpp v168, v104 row_shr:2 row_mask:0xf bank_mask:0xf
	v_mov_b32_dpp v166, v104 row_shr:3 row_mask:0xf bank_mask:0xf
	v_mov_b32_dpp v171, v105 row_shr:1 row_mask:0xf bank_mask:0xf
	v_mov_b32_dpp v169, v105 row_shr:2 row_mask:0xf bank_mask:0xf
	v_mov_b32_dpp v167, v105 row_shr:3 row_mask:0xf bank_mask:0xf
	v_mov_b32_dpp v136, v106 row_shr:1 row_mask:0xf bank_mask:0xf
	v_mov_b32_dpp v110, v106 row_shr:2 row_mask:0xf bank_mask:0xf
	v_mov_b32_dpp v108, v106 row_shr:3 row_mask:0xf bank_mask:0xf
	v_mov_b32_dpp v151, v107 row_shr:1 row_mask:0xf bank_mask:0xf
	v_mov_b32_dpp v111, v107 row_shr:2 row_mask:0xf bank_mask:0xf
	v_mov_b32_dpp v109, v107 row_shr:3 row_mask:0xf bank_mask:0xf
	s_and_saveexec_b64 s[22:23], s[2:3]
	s_cbranch_execz .LBB0_195
	ds_read_b128 v[172:175], v238 offset:4112
	ds_read_b128 v[176:179], v238 offset:3088
	ds_read_b128 v[182:185], v238 offset:2064
	v_cndmask_b32_e64 v171, v171, 0, s[8:9]
	ds_read_b128 v[186:189], v238 offset:1040
	s_nop 0
	ds_read_b128 v[190:193], v238 offset:16
	v_cndmask_b32_e64 v170, v170, 0, s[8:9]
	v_cndmask_b32_e64 v169, 0, v169, s[6:7]
	v_cndmask_b32_e64 v168, 0, v168, s[6:7]
	v_cndmask_b32_e64 v167, 0, v167, s[4:5]
	v_cndmask_b32_e64 v166, 0, v166, s[4:5]
	v_cndmask_b32_e64 v111, 0, v111, s[6:7]
	v_cndmask_b32_e64 v110, 0, v110, s[6:7]
	v_cndmask_b32_e64 v109, 0, v109, s[4:5]
	v_cndmask_b32_e64 v108, 0, v108, s[4:5]
	s_waitcnt lgkmcnt(0)
	v_pk_fma_f32 v[104:105], v[104:105], v[176:177], v[172:173]
	v_pk_fma_f32 v[106:107], v[106:107], v[178:179], v[174:175]
	v_pk_fma_f32 v[104:105], v[170:171], v[182:183], v[104:105]
	s_nop 0
	v_pk_fma_f32 v[104:105], v[168:169], v[186:187], v[104:105]
	s_nop 0
	v_pk_fma_f32 v[104:105], v[166:167], v[190:191], v[104:105]
	s_nop 0
	v_mul_f32_e32 v166, 0xbfb8aa3b, v105
	v_exp_f32_e32 v166, v166
	s_nop 0
	v_add_f32_e32 v166, 1.0, v166
	v_rcp_f32_e32 v167, v166
	v_mul_f32_e32 v166, 0xbfb8aa3b, v104
	v_exp_f32_e32 v166, v166
	s_nop 0
	v_add_f32_e32 v166, 1.0, v166
	v_rcp_f32_e32 v166, v166
	s_nop 0
	v_pk_mul_f32 v[104:105], v[104:105], v[166:167]
	v_cndmask_b32_e64 v167, v151, 0, s[8:9]
	v_cndmask_b32_e64 v166, v136, 0, s[8:9]
	v_pk_fma_f32 v[106:107], v[166:167], v[184:185], v[106:107]
	v_cvt_pk_bf16_f32 v206, v104, v105
	v_pk_fma_f32 v[106:107], v[110:111], v[188:189], v[106:107]
	s_nop 0
	v_pk_fma_f32 v[106:107], v[108:109], v[192:193], v[106:107]
	s_nop 0
	v_mul_f32_e32 v105, 0xbfb8aa3b, v107
	v_exp_f32_e32 v105, v105
	s_nop 0
	v_add_f32_e32 v105, 1.0, v105
	v_rcp_f32_e32 v109, v105
	v_mul_f32_e32 v105, 0xbfb8aa3b, v106
	v_exp_f32_e32 v105, v105
	s_nop 0
	v_add_f32_e32 v105, 1.0, v105
	v_rcp_f32_e32 v108, v105
	s_nop 0
	v_pk_mul_f32 v[106:107], v[106:107], v[108:109]
	s_nop 0
	v_cvt_pk_bf16_f32 v207, v106, v107
	global_store_dwordx4 v[112:113], v[204:207], off
;     __device__ __forceinline__ void operator()(const f32x4 (&acc)[2][2][4][2], const Unit& u, int wr, int wc, int fr, int fq, LAS unsigned char* hb) const {
;     ...
;             for (int m = 0; m < 4; ++m) { asm volatile("" ::: "memory"); __builtin_amdgcn_sched_barrier(0);
;                 const int q = 8 * ai + 4 * wr + m, prev = q > 0 ? q - 1 : 0; const int lr = ai * HALF + wr * 64 + m * 16 + fr, R = R0 + lr;
;                 const int Rc = R < 0 ? 0 : R; const int b = Rc / LL, p = Rc - b * LL;
;                 const bool ok = (lr >= H && R < TT);
;                 const unsigned ooff = ((unsigned)Rc * (unsigned)LDP + (unsigned)(OFF_XBC + ch0)) * 2u;
; #pragma unroll
;                 for (int bn = 0; bn < 4; ++bn) { const int bj = bn >> 1, n = bn & 1; const int co = bj * HALF + 4 * n;
;                     const unsigned woff = (unsigned)(ch0 + co) * 4u;
;                     const f32x4 w0 = *(const f32x4*)((const char*)cw + woff), w1 = *(const f32x4*)((const char*)cw + woff + XBCW * 4), w2 = *(const f32x4*)((const char*)cw + woff + 2 * XBCW * 4), w3 = *(const f32x4*)((const char*)cw + woff + 3 * XBCW * 4), bs = *(const f32x4*)((const char*)cb + woff);
;                     const LAS unsigned char* hp = hb + (prev * H * NCH + chl + co) * 2;
;                     const u32x2 q1 = *(const LAS u32x2*)(hp + hr1 * NCH * 2), q2 = *(const LAS u32x2*)(hp + hr2 * NCH * 2), q3 = *(const LAS u32x2*)(hp + hr3 * NCH * 2);
;                     const float h1[4] = {__builtin_bit_cast(float, q1.x << 16), __builtin_bit_cast(float, q1.x & 0xffff0000u), __builtin_bit_cast(float, q1.y << 16), __builtin_bit_cast(float, q1.y & 0xffff0000u)};
;                     const float h2[4] = {__builtin_bit_cast(float, q2.x << 16), __builtin_bit_cast(float, q2.x & 0xffff0000u), __builtin_bit_cast(float, q2.y << 16), __builtin_bit_cast(float, q2.y & 0xffff0000u)};
;                     const float h3[4] = {__builtin_bit_cast(float, q3.x << 16), __builtin_bit_cast(float, q3.x & 0xffff0000u), __builtin_bit_cast(float, q3.y << 16), __builtin_bit_cast(float, q3.y & 0xffff0000u)};
;                     const f32x4 gv = acc[ai][bj][m][n];
;                     float o[4];
; #pragma unroll
;                     for (int j = 0; j < 4; ++j) { const float g = gv[j];
;                         float g1 = dpp_row_shr<1>(h1[j], g), g2 = dpp_row_shr<2>(h2[j], g), g3 = dpp_row_shr<3>(h3[j], g);
.LBB0_195:
	s_or_b64 exec, exec, s[22:23]
	ds_read_b64 v[104:105], v114 offset:1280
	ds_read_b64 v[106:107], v115 offset:768
	ds_read_b64 v[168:169], v150 offset:256
	s_waitcnt lgkmcnt(0)
	v_lshlrev_b32_e32 v166, 16, v104
	v_and_b32_e32 v167, 0xffff0000, v104
	v_lshlrev_b32_e32 v108, 16, v105
	v_and_b32_e32 v109, 0xffff0000, v105
	v_lshlrev_b32_e32 v136, 16, v106
	v_and_b32_e32 v151, 0xffff0000, v106
	v_lshlrev_b32_e32 v106, 16, v107
	v_and_b32_e32 v107, 0xffff0000, v107
	v_lshlrev_b32_e32 v110, 16, v168
	v_and_b32_e32 v111, 0xffff0000, v168
	v_lshlrev_b32_e32 v104, 16, v169
	v_and_b32_e32 v105, 0xffff0000, v169
	v_mov_b32_dpp v166, v100 row_shr:1 row_mask:0xf bank_mask:0xf
	v_mov_b32_dpp v136, v100 row_shr:2 row_mask:0xf bank_mask:0xf
	v_mov_b32_dpp v110, v100 row_shr:3 row_mask:0xf bank_mask:0xf
	v_mov_b32_dpp v167, v101 row_shr:1 row_mask:0xf bank_mask:0xf
	v_mov_b32_dpp v151, v101 row_shr:2 row_mask:0xf bank_mask:0xf
	v_mov_b32_dpp v111, v101 row_shr:3 row_mask:0xf bank_mask:0xf
	v_mov_b32_dpp v108, v102 row_shr:1 row_mask:0xf bank_mask:0xf
	v_mov_b32_dpp v106, v102 row_shr:2 row_mask:0xf bank_mask:0xf
	v_mov_b32_dpp v104, v102 row_shr:3 row_mask:0xf bank_mask:0xf
	v_mov_b32_dpp v109, v103 row_shr:1 row_mask:0xf bank_mask:0xf
	v_mov_b32_dpp v107, v103 row_shr:2 row_mask:0xf bank_mask:0xf
	v_mov_b32_dpp v105, v103 row_shr:3 row_mask:0xf bank_mask:0xf
	s_and_saveexec_b64 s[22:23], s[2:3]
	s_cbranch_execz .LBB0_197
	ds_read_b128 v[168:171], v238 offset:4608
	ds_read_b128 v[172:175], v238 offset:3584
	ds_read_b128 v[176:179], v238 offset:2560
	v_cndmask_b32_e64 v167, v167, 0, s[8:9]
	ds_read_b128 v[182:185], v238 offset:1536
	s_nop 0
	ds_read_b128 v[186:189], v238 offset:512
	v_cndmask_b32_e64 v166, v166, 0, s[8:9]
	v_cndmask_b32_e64 v111, 0, v111, s[4:5]
	v_cndmask_b32_e64 v110, 0, v110, s[4:5]
	v_cndmask_b32_e64 v109, v109, 0, s[8:9]
	v_cndmask_b32_e64 v108, v108, 0, s[8:9]
	v_cndmask_b32_e64 v107, 0, v107, s[6:7]
	v_cndmask_b32_e64 v106, 0, v106, s[6:7]
	v_cndmask_b32_e64 v105, 0, v105, s[4:5]
	v_cndmask_b32_e64 v104, 0, v104, s[4:5]
	s_waitcnt lgkmcnt(0)
	v_pk_fma_f32 v[100:101], v[100:101], v[172:173], v[168:169]
	v_pk_fma_f32 v[102:103], v[102:103], v[174:175], v[170:171]
	v_pk_fma_f32 v[100:101], v[166:167], v[176:177], v[100:101]
	v_cndmask_b32_e64 v167, 0, v151, s[6:7]
	v_cndmask_b32_e64 v166, 0, v136, s[6:7]
	v_pk_fma_f32 v[102:103], v[108:109], v[178:179], v[102:103]
	v_pk_fma_f32 v[100:101], v[166:167], v[182:183], v[100:101]
	s_nop 0
	v_pk_fma_f32 v[100:101], v[110:111], v[186:187], v[100:101]
	v_pk_fma_f32 v[102:103], v[106:107], v[184:185], v[102:103]
	v_mul_f32_e32 v110, 0xbfb8aa3b, v101
	v_exp_f32_e32 v110, v110
	v_pk_fma_f32 v[102:103], v[104:105], v[188:189], v[102:103]
	v_add_f32_e32 v110, 1.0, v110
	v_rcp_f32_e32 v111, v110
	v_mul_f32_e32 v110, 0xbfb8aa3b, v100
	v_exp_f32_e32 v110, v110
	s_nop 0
	v_add_f32_e32 v110, 1.0, v110
	v_rcp_f32_e32 v110, v110
	s_nop 0
	v_pk_mul_f32 v[100:101], v[100:101], v[110:111]
	s_nop 0
	v_cvt_pk_bf16_f32 v204, v100, v101
	v_mul_f32_e32 v101, 0xbfb8aa3b, v103
	v_exp_f32_e32 v101, v101
	s_nop 0
	v_add_f32_e32 v101, 1.0, v101
	v_rcp_f32_e32 v105, v101
	v_mul_f32_e32 v101, 0xbfb8aa3b, v102
	v_exp_f32_e32 v101, v101
	s_nop 0
	v_add_f32_e32 v101, 1.0, v101
	v_rcp_f32_e32 v104, v101
	s_nop 0
	v_pk_mul_f32 v[102:103], v[102:103], v[104:105]
	s_nop 0
	v_cvt_pk_bf16_f32 v205, v102, v103
.LBB0_197:
	s_or_b64 exec, exec, s[22:23]
	ds_read_b64 v[100:101], v114 offset:1288
	ds_read_b64 v[102:103], v115 offset:776
	ds_read_b64 v[114:115], v150 offset:264
	s_waitcnt lgkmcnt(0)
	v_lshlrev_b32_e32 v110, 16, v100
	v_and_b32_e32 v111, 0xffff0000, v100
	v_lshlrev_b32_e32 v104, 16, v101
	v_and_b32_e32 v105, 0xffff0000, v101
	v_lshlrev_b32_e32 v108, 16, v102
	v_and_b32_e32 v109, 0xffff0000, v102
	v_lshlrev_b32_e32 v102, 16, v103
	v_and_b32_e32 v103, 0xffff0000, v103
	v_lshlrev_b32_e32 v106, 16, v114
	v_and_b32_e32 v107, 0xffff0000, v114
	v_lshlrev_b32_e32 v100, 16, v115
	v_and_b32_e32 v101, 0xffff0000, v115
	v_mov_b32_dpp v110, v96 row_shr:1 row_mask:0xf bank_mask:0xf
	v_mov_b32_dpp v108, v96 row_shr:2 row_mask:0xf bank_mask:0xf
	v_mov_b32_dpp v106, v96 row_shr:3 row_mask:0xf bank_mask:0xf
	v_mov_b32_dpp v111, v97 row_shr:1 row_mask:0xf bank_mask:0xf
	v_mov_b32_dpp v109, v97 row_shr:2 row_mask:0xf bank_mask:0xf
	v_mov_b32_dpp v107, v97 row_shr:3 row_mask:0xf bank_mask:0xf
	v_mov_b32_dpp v104, v98 row_shr:1 row_mask:0xf bank_mask:0xf
	v_mov_b32_dpp v102, v98 row_shr:2 row_mask:0xf bank_mask:0xf
	v_mov_b32_dpp v100, v98 row_shr:3 row_mask:0xf bank_mask:0xf
	v_mov_b32_dpp v105, v99 row_shr:1 row_mask:0xf bank_mask:0xf
	v_mov_b32_dpp v103, v99 row_shr:2 row_mask:0xf bank_mask:0xf
	v_mov_b32_dpp v101, v99 row_shr:3 row_mask:0xf bank_mask:0xf
	s_and_saveexec_b64 s[22:23], s[2:3]
	s_cbranch_execz .LBB0_199
	ds_read_b128 v[166:169], v238 offset:4624
	ds_read_b128 v[170:173], v238 offset:3600
	v_cndmask_b32_e64 v111, v111, 0, s[8:9]
	ds_read_b128 v[174:177], v238 offset:2576
	v_cndmask_b32_e64 v110, v110, 0, s[8:9]
	ds_read_b128 v[182:185], v238 offset:1552
	ds_read_b128 v[186:189], v238 offset:528
	v_cndmask_b32_e64 v109, 0, v109, s[6:7]
	v_cndmask_b32_e64 v108, 0, v108, s[6:7]
	v_cndmask_b32_e64 v107, 0, v107, s[4:5]
	v_cndmask_b32_e64 v106, 0, v106, s[4:5]
	v_cndmask_b32_e64 v105, v105, 0, s[8:9]
	v_cndmask_b32_e64 v104, v104, 0, s[8:9]
	v_cndmask_b32_e64 v103, 0, v103, s[6:7]
	v_cndmask_b32_e64 v102, 0, v102, s[6:7]
	v_cndmask_b32_e64 v101, 0, v101, s[4:5]
	v_cndmask_b32_e64 v100, 0, v100, s[4:5]
	s_waitcnt lgkmcnt(0)
	v_pk_fma_f32 v[96:97], v[96:97], v[170:171], v[166:167]
	v_pk_fma_f32 v[98:99], v[98:99], v[172:173], v[168:169]
	v_pk_fma_f32 v[96:97], v[110:111], v[174:175], v[96:97]
	v_pk_fma_f32 v[98:99], v[104:105], v[176:177], v[98:99]
	v_pk_fma_f32 v[96:97], v[108:109], v[182:183], v[96:97]
	s_nop 0
	v_pk_fma_f32 v[96:97], v[106:107], v[186:187], v[96:97]
	v_pk_fma_f32 v[98:99], v[102:103], v[184:185], v[98:99]
	v_mul_f32_e32 v106, 0xbfb8aa3b, v97
	v_exp_f32_e32 v106, v106
	v_pk_fma_f32 v[98:99], v[100:101], v[188:189], v[98:99]
	v_add_f32_e32 v106, 1.0, v106
	v_rcp_f32_e32 v107, v106
	v_mul_f32_e32 v106, 0xbfb8aa3b, v96
	v_exp_f32_e32 v106, v106
	s_nop 0
	v_add_f32_e32 v106, 1.0, v106
	v_rcp_f32_e32 v106, v106
	s_nop 0
	v_pk_mul_f32 v[96:97], v[96:97], v[106:107]
	s_nop 0
	v_cvt_pk_bf16_f32 v206, v96, v97
	v_mul_f32_e32 v97, 0xbfb8aa3b, v99
	v_exp_f32_e32 v97, v97
	s_nop 0
	v_add_f32_e32 v97, 1.0, v97
	v_rcp_f32_e32 v101, v97
	v_mul_f32_e32 v97, 0xbfb8aa3b, v98
	v_exp_f32_e32 v97, v97
	s_nop 0
	v_add_f32_e32 v97, 1.0, v97
	v_rcp_f32_e32 v100, v97
	s_nop 0
	v_pk_mul_f32 v[98:99], v[98:99], v[100:101]
	s_nop 0
	v_cvt_pk_bf16_f32 v207, v98, v99
	global_store_dwordx4 v[112:113], v[204:207], off offset:256
;     __device__ __forceinline__ void operator()(const f32x4 (&acc)[2][2][4][2], const Unit& u, int wr, int wc, int fr, int fq, LAS unsigned char* hb) const {
;     ...
;             for (int m = 0; m < 4; ++m) { asm volatile("" ::: "memory"); __builtin_amdgcn_sched_barrier(0);
;                 const int q = 8 * ai + 4 * wr + m, prev = q > 0 ? q - 1 : 0; const int lr = ai * HALF + wr * 64 + m * 16 + fr, R = R0 + lr;
;                 const int Rc = R < 0 ? 0 : R; const int b = Rc / LL, p = Rc - b * LL;
;                 const bool ok = (lr >= H && R < TT);
;                 const unsigned ooff = ((unsigned)Rc * (unsigned)LDP + (unsigned)(OFF_XBC + ch0)) * 2u;
; #pragma unroll
;                 for (int bn = 0; bn < 4; ++bn) { const int bj = bn >> 1, n = bn & 1; const int co = bj * HALF + 4 * n;
;                     const unsigned woff = (unsigned)(ch0 + co) * 4u;
;                     const f32x4 w0 = *(const f32x4*)((const char*)cw + woff), w1 = *(const f32x4*)((const char*)cw + woff + XBCW * 4), w2 = *(const f32x4*)((const char*)cw + woff + 2 * XBCW * 4), w3 = *(const f32x4*)((const char*)cw + woff + 3 * XBCW * 4), bs = *(const f32x4*)((const char*)cb + woff);
;                     const LAS unsigned char* hp = hb + (prev * H * NCH + chl + co) * 2;
;                     const u32x2 q1 = *(const LAS u32x2*)(hp + hr1 * NCH * 2), q2 = *(const LAS u32x2*)(hp + hr2 * NCH * 2), q3 = *(const LAS u32x2*)(hp + hr3 * NCH * 2);
;                     const float h1[4] = {__builtin_bit_cast(float, q1.x << 16), __builtin_bit_cast(float, q1.x & 0xffff0000u), __builtin_bit_cast(float, q1.y << 16), __builtin_bit_cast(float, q1.y & 0xffff0000u)};
;                     const float h2[4] = {__builtin_bit_cast(float, q2.x << 16), __builtin_bit_cast(float, q2.x & 0xffff0000u), __builtin_bit_cast(float, q2.y << 16), __builtin_bit_cast(float, q2.y & 0xffff0000u)};
;                     const float h3[4] = {__builtin_bit_cast(float, q3.x << 16), __builtin_bit_cast(float, q3.x & 0xffff0000u), __builtin_bit_cast(float, q3.y << 16), __builtin_bit_cast(float, q3.y & 0xffff0000u)};
;                     const f32x4 gv = acc[ai][bj][m][n];
;                     float o[4];
; #pragma unroll
;                     for (int j = 0; j < 4; ++j) { const float g = gv[j];
;                         float g1 = dpp_row_shr<1>(h1[j], g), g2 = dpp_row_shr<2>(h2[j], g), g3 = dpp_row_shr<3>(h3[j], g);
.LBB0_199:
	s_or_b64 exec, exec, s[22:23]
	v_add_u32_e32 v96, 32, v161
	v_add_u32_e32 v97, s17, v96
	v_max_i32_e32 v98, 0, v97
	v_mul_hi_u32 v99, v98, s56
	v_lshrrev_b32_e32 v99, 11, v99
	v_cmp_lt_i32_e32 vcc, 2, v96
	v_mul_lo_u32 v96, v98, s51
	v_mul_u32_u24_e32 v99, 0x1010, v99
	v_add_lshl_u32 v136, v96, v164, 1
	v_add_u32_e32 v96, s39, v165
	v_sub_u32_e32 v99, v98, v99
	v_cmp_gt_i32_e64 s[4:5], s50, v97
	v_lshl_add_u32 v98, v96, 1, s53
	s_and_b64 s[2:3], vcc, s[4:5]
	v_cmp_eq_u32_e64 s[8:9], 0, v99
	v_cmp_lt_u32_e64 s[6:7], 1, v99
	v_cmp_lt_u32_e64 s[4:5], 2, v99
	v_add_u32_e32 v99, v98, v163
	ds_read_b64 v[96:97], v98 offset:1024
	v_add_u32_e32 v100, v98, v162
	ds_read_b64 v[114:115], v99 offset:512
	ds_read_b64 v[150:151], v100
	v_readlane_b32 s22, v237, 58
	v_readlane_b32 s23, v237, 59
	s_waitcnt lgkmcnt(0)
	v_lshlrev_b32_e32 v111, 16, v96
	v_and_b32_e32 v112, 0xffff0000, v96
	v_lshlrev_b32_e32 v105, 16, v97
	v_and_b32_e32 v106, 0xffff0000, v97
	v_lshlrev_b32_e32 v109, 16, v114
	v_and_b32_e32 v110, 0xffff0000, v114
	v_lshlrev_b32_e32 v103, 16, v115
	v_and_b32_e32 v104, 0xffff0000, v115
	v_lshlrev_b32_e32 v107, 16, v150
	v_and_b32_e32 v108, 0xffff0000, v150
	v_lshlrev_b32_e32 v101, 16, v151
	v_and_b32_e32 v102, 0xffff0000, v151
	v_mov_b32_dpp v111, v92 row_shr:1 row_mask:0xf bank_mask:0xf
	v_mov_b32_dpp v109, v92 row_shr:2 row_mask:0xf bank_mask:0xf
	v_mov_b32_dpp v107, v92 row_shr:3 row_mask:0xf bank_mask:0xf
	v_mov_b32_dpp v112, v93 row_shr:1 row_mask:0xf bank_mask:0xf
	v_mov_b32_dpp v110, v93 row_shr:2 row_mask:0xf bank_mask:0xf
	v_mov_b32_dpp v108, v93 row_shr:3 row_mask:0xf bank_mask:0xf
	v_mov_b32_dpp v105, v94 row_shr:1 row_mask:0xf bank_mask:0xf
	v_mov_b32_dpp v103, v94 row_shr:2 row_mask:0xf bank_mask:0xf
	v_mov_b32_dpp v101, v94 row_shr:3 row_mask:0xf bank_mask:0xf
	v_mov_b32_dpp v106, v95 row_shr:1 row_mask:0xf bank_mask:0xf
	v_mov_b32_dpp v104, v95 row_shr:2 row_mask:0xf bank_mask:0xf
	v_mov_b32_dpp v102, v95 row_shr:3 row_mask:0xf bank_mask:0xf
	v_lshl_add_u64 v[96:97], s[22:23], 0, v[136:137]
	s_and_saveexec_b64 s[22:23], s[2:3]
	s_cbranch_execz .LBB0_201
	ds_read_b128 v[166:169], v238 offset:4096
	ds_read_b128 v[170:173], v238 offset:3072
	v_cndmask_b32_e64 v113, v112, 0, s[8:9]
	ds_read_b128 v[174:177], v238 offset:2048
	v_cndmask_b32_e64 v112, v111, 0, s[8:9]
	ds_read_b128 v[182:185], v238 offset:1024
	ds_read_b128 v[186:189], v238
	v_cndmask_b32_e64 v111, 0, v110, s[6:7]
	v_cndmask_b32_e64 v110, 0, v109, s[6:7]
	v_cndmask_b32_e64 v109, 0, v108, s[4:5]
	v_cndmask_b32_e64 v108, 0, v107, s[4:5]
	s_waitcnt lgkmcnt(0)
	v_pk_fma_f32 v[92:93], v[92:93], v[170:171], v[166:167]
	v_pk_fma_f32 v[94:95], v[94:95], v[172:173], v[168:169]
	v_pk_fma_f32 v[92:93], v[112:113], v[174:175], v[92:93]
	s_nop 0
	v_pk_fma_f32 v[92:93], v[110:111], v[182:183], v[92:93]
	s_nop 0
	v_pk_fma_f32 v[92:93], v[108:109], v[186:187], v[92:93]
	s_nop 0
	v_mul_f32_e32 v107, 0xbfb8aa3b, v93
	v_exp_f32_e32 v107, v107
	s_nop 0
	v_add_f32_e32 v107, 1.0, v107
	v_rcp_f32_e32 v109, v107
	v_mul_f32_e32 v107, 0xbfb8aa3b, v92
	v_exp_f32_e32 v107, v107
	s_nop 0
	v_add_f32_e32 v107, 1.0, v107
	v_rcp_f32_e32 v108, v107
	v_cndmask_b32_e64 v107, v106, 0, s[8:9]
	v_cndmask_b32_e64 v106, v105, 0, s[8:9]
	v_pk_fma_f32 v[94:95], v[106:107], v[176:177], v[94:95]
	v_cndmask_b32_e64 v105, 0, v104, s[6:7]
	v_cndmask_b32_e64 v104, 0, v103, s[6:7]
	v_pk_fma_f32 v[94:95], v[104:105], v[184:185], v[94:95]
	v_cndmask_b32_e64 v103, 0, v102, s[4:5]
	v_cndmask_b32_e64 v102, 0, v101, s[4:5]
	v_pk_mul_f32 v[92:93], v[92:93], v[108:109]
	v_pk_fma_f32 v[94:95], v[102:103], v[188:189], v[94:95]
	v_cvt_pk_bf16_f32 v204, v92, v93
	v_mul_f32_e32 v93, 0xbfb8aa3b, v95
	v_exp_f32_e32 v93, v93
	s_nop 0
	v_add_f32_e32 v93, 1.0, v93
	v_rcp_f32_e32 v103, v93
	v_mul_f32_e32 v93, 0xbfb8aa3b, v94
	v_exp_f32_e32 v93, v93
	s_nop 0
	v_add_f32_e32 v93, 1.0, v93
	v_rcp_f32_e32 v102, v93
	s_nop 0
	v_pk_mul_f32 v[94:95], v[94:95], v[102:103]
	s_nop 0
	v_cvt_pk_bf16_f32 v205, v94, v95
.LBB0_201:
	s_or_b64 exec, exec, s[22:23]
	ds_read_b64 v[92:93], v98 offset:1032
	ds_read_b64 v[94:95], v99 offset:520
	ds_read_b64 v[110:111], v100 offset:8
	s_waitcnt lgkmcnt(0)
	v_lshlrev_b32_e32 v107, 16, v92
	v_and_b32_e32 v108, 0xffff0000, v92
	v_lshlrev_b32_e32 v101, 16, v93
	v_and_b32_e32 v102, 0xffff0000, v93
	v_lshlrev_b32_e32 v105, 16, v94
	v_and_b32_e32 v106, 0xffff0000, v94
	v_lshlrev_b32_e32 v94, 16, v95
	v_and_b32_e32 v95, 0xffff0000, v95
	v_lshlrev_b32_e32 v103, 16, v110
	v_and_b32_e32 v104, 0xffff0000, v110
	v_lshlrev_b32_e32 v92, 16, v111
	v_and_b32_e32 v93, 0xffff0000, v111
	v_mov_b32_dpp v107, v88 row_shr:1 row_mask:0xf bank_mask:0xf
	v_mov_b32_dpp v105, v88 row_shr:2 row_mask:0xf bank_mask:0xf
	v_mov_b32_dpp v103, v88 row_shr:3 row_mask:0xf bank_mask:0xf
	v_mov_b32_dpp v108, v89 row_shr:1 row_mask:0xf bank_mask:0xf
	v_mov_b32_dpp v106, v89 row_shr:2 row_mask:0xf bank_mask:0xf
	v_mov_b32_dpp v104, v89 row_shr:3 row_mask:0xf bank_mask:0xf
	v_mov_b32_dpp v101, v90 row_shr:1 row_mask:0xf bank_mask:0xf
	v_mov_b32_dpp v94, v90 row_shr:2 row_mask:0xf bank_mask:0xf
	v_mov_b32_dpp v92, v90 row_shr:3 row_mask:0xf bank_mask:0xf
	v_mov_b32_dpp v102, v91 row_shr:1 row_mask:0xf bank_mask:0xf
	v_mov_b32_dpp v95, v91 row_shr:2 row_mask:0xf bank_mask:0xf
	v_mov_b32_dpp v93, v91 row_shr:3 row_mask:0xf bank_mask:0xf
	s_and_saveexec_b64 s[22:23], s[2:3]
	s_cbranch_execz .LBB0_203
;     __device__ __forceinline__ void operator()(const f32x4 (&acc)[2][2][4][2], const Unit& u, int wr, int wc, int fr, int fq, LAS unsigned char* hb) const {
;     ...
;             for (int m = 0; m < 4; ++m) { asm volatile("" ::: "memory"); __builtin_amdgcn_sched_barrier(0);
;                 const int q = 8 * ai + 4 * wr + m, prev = q > 0 ? q - 1 : 0; const int lr = ai * HALF + wr * 64 + m * 16 + fr, R = R0 + lr;
;                 const int Rc = R < 0 ? 0 : R; const int b = Rc / LL, p = Rc - b * LL;
;                 const bool ok = (lr >= H && R < TT);
;                 const unsigned ooff = ((unsigned)Rc * (unsigned)LDP + (unsigned)(OFF_XBC + ch0)) * 2u;
; #pragma unroll
;                 for (int bn = 0; bn < 4; ++bn) { const int bj = bn >> 1, n = bn & 1; const int co = bj * HALF + 4 * n;
;                     const unsigned woff = (unsigned)(ch0 + co) * 4u;
;                     const f32x4 w0 = *(const f32x4*)((const char*)cw + woff), w1 = *(const f32x4*)((const char*)cw + woff + XBCW * 4), w2 = *(const f32x4*)((const char*)cw + woff + 2 * XBCW * 4), w3 = *(const f32x4*)((const char*)cw + woff + 3 * XBCW * 4), bs = *(const f32x4*)((const char*)cb + woff);
;                     const LAS unsigned char* hp = hb + (prev * H * NCH + chl + co) * 2;
;                     const u32x2 q1 = *(const LAS u32x2*)(hp + hr1 * NCH * 2), q2 = *(const LAS u32x2*)(hp + hr2 * NCH * 2), q3 = *(const LAS u32x2*)(hp + hr3 * NCH * 2);
;                     const float h1[4] = {__builtin_bit_cast(float, q1.x << 16), __builtin_bit_cast(float, q1.x & 0xffff0000u), __builtin_bit_cast(float, q1.y << 16), __builtin_bit_cast(float, q1.y & 0xffff0000u)};
;                     const float h2[4] = {__builtin_bit_cast(float, q2.x << 16), __builtin_bit_cast(float, q2.x & 0xffff0000u), __builtin_bit_cast(float, q2.y << 16), __builtin_bit_cast(float, q2.y & 0xffff0000u)};
;                     const float h3[4] = {__builtin_bit_cast(float, q3.x << 16), __builtin_bit_cast(float, q3.x & 0xffff0000u), __builtin_bit_cast(float, q3.y << 16), __builtin_bit_cast(float, q3.y & 0xffff0000u)};
;                     const f32x4 gv = acc[ai][bj][m][n];
;                     float o[4];
; #pragma unroll
;                     for (int j = 0; j < 4; ++j) { const float g = gv[j];
;                         float g1 = dpp_row_shr<1>(h1[j], g), g2 = dpp_row_shr<2>(h2[j], g), g3 = dpp_row_shr<3>(h3[j], g);
	ds_read_b128 v[110:113], v238 offset:4112
	ds_read_b128 v[166:169], v238 offset:3088
	v_cndmask_b32_e64 v109, v108, 0, s[8:9]
	ds_read_b128 v[170:173], v238 offset:2064
	v_cndmask_b32_e64 v108, v107, 0, s[8:9]
	ds_read_b128 v[174:177], v238 offset:1040
	ds_read_b128 v[182:185], v238 offset:16
	v_cndmask_b32_e64 v107, 0, v106, s[6:7]
	v_cndmask_b32_e64 v106, 0, v105, s[6:7]
	v_cndmask_b32_e64 v105, 0, v104, s[4:5]
	v_cndmask_b32_e64 v104, 0, v103, s[4:5]
	v_cndmask_b32_e64 v95, 0, v95, s[6:7]
	v_cndmask_b32_e64 v94, 0, v94, s[6:7]
	v_cndmask_b32_e64 v93, 0, v93, s[4:5]
	v_cndmask_b32_e64 v92, 0, v92, s[4:5]
	s_waitcnt lgkmcnt(0)
	v_pk_fma_f32 v[88:89], v[88:89], v[166:167], v[110:111]
	v_pk_fma_f32 v[90:91], v[90:91], v[168:169], v[112:113]
	v_pk_fma_f32 v[88:89], v[108:109], v[170:171], v[88:89]
	s_nop 0
	v_pk_fma_f32 v[88:89], v[106:107], v[174:175], v[88:89]
	s_nop 0
	v_pk_fma_f32 v[88:89], v[104:105], v[182:183], v[88:89]
	s_nop 0
	v_mul_f32_e32 v103, 0xbfb8aa3b, v89
	v_exp_f32_e32 v103, v103
	s_nop 0
	v_add_f32_e32 v103, 1.0, v103
	v_rcp_f32_e32 v105, v103
	v_mul_f32_e32 v103, 0xbfb8aa3b, v88
	v_exp_f32_e32 v103, v103
	s_nop 0
	v_add_f32_e32 v103, 1.0, v103
	v_rcp_f32_e32 v104, v103
	v_cndmask_b32_e64 v103, v102, 0, s[8:9]
	v_cndmask_b32_e64 v102, v101, 0, s[8:9]
	v_pk_fma_f32 v[90:91], v[102:103], v[172:173], v[90:91]
	v_pk_mul_f32 v[88:89], v[88:89], v[104:105]
	v_pk_fma_f32 v[90:91], v[94:95], v[176:177], v[90:91]
	v_cvt_pk_bf16_f32 v206, v88, v89
	v_pk_fma_f32 v[90:91], v[92:93], v[184:185], v[90:91]
	s_nop 0
	v_mul_f32_e32 v89, 0xbfb8aa3b, v91
	v_exp_f32_e32 v89, v89
	s_nop 0
	v_add_f32_e32 v89, 1.0, v89
	v_rcp_f32_e32 v93, v89
	v_mul_f32_e32 v89, 0xbfb8aa3b, v90
	v_exp_f32_e32 v89, v89
	s_nop 0
	v_add_f32_e32 v89, 1.0, v89
	v_rcp_f32_e32 v92, v89
	s_nop 0
	v_pk_mul_f32 v[90:91], v[90:91], v[92:93]
	s_nop 0
	v_cvt_pk_bf16_f32 v207, v90, v91
	global_store_dwordx4 v[96:97], v[204:207], off
.LBB0_203:
	s_or_b64 exec, exec, s[22:23]
	ds_read_b64 v[88:89], v98 offset:1280
	ds_read_b64 v[90:91], v99 offset:768
	ds_read_b64 v[106:107], v100 offset:256
	s_waitcnt lgkmcnt(0)
	v_lshlrev_b32_e32 v103, 16, v88
	v_and_b32_e32 v104, 0xffff0000, v88
	v_lshlrev_b32_e32 v92, 16, v89
	v_and_b32_e32 v93, 0xffff0000, v89
	v_lshlrev_b32_e32 v101, 16, v90
	v_and_b32_e32 v102, 0xffff0000, v90
	v_lshlrev_b32_e32 v90, 16, v91
	v_and_b32_e32 v91, 0xffff0000, v91
	v_lshlrev_b32_e32 v94, 16, v106
	v_and_b32_e32 v95, 0xffff0000, v106
	v_lshlrev_b32_e32 v88, 16, v107
	v_and_b32_e32 v89, 0xffff0000, v107
	v_mov_b32_dpp v103, v84 row_shr:1 row_mask:0xf bank_mask:0xf
	v_mov_b32_dpp v101, v84 row_shr:2 row_mask:0xf bank_mask:0xf
	v_mov_b32_dpp v94, v84 row_shr:3 row_mask:0xf bank_mask:0xf
	v_mov_b32_dpp v104, v85 row_shr:1 row_mask:0xf bank_mask:0xf
	v_mov_b32_dpp v102, v85 row_shr:2 row_mask:0xf bank_mask:0xf
	v_mov_b32_dpp v95, v85 row_shr:3 row_mask:0xf bank_mask:0xf
	v_mov_b32_dpp v92, v86 row_shr:1 row_mask:0xf bank_mask:0xf
	v_mov_b32_dpp v90, v86 row_shr:2 row_mask:0xf bank_mask:0xf
	v_mov_b32_dpp v88, v86 row_shr:3 row_mask:0xf bank_mask:0xf
	v_mov_b32_dpp v93, v87 row_shr:1 row_mask:0xf bank_mask:0xf
	v_mov_b32_dpp v91, v87 row_shr:2 row_mask:0xf bank_mask:0xf
	v_mov_b32_dpp v89, v87 row_shr:3 row_mask:0xf bank_mask:0xf
	s_and_saveexec_b64 s[22:23], s[2:3]
	s_cbranch_execz .LBB0_205
	ds_read_b128 v[106:109], v238 offset:4608
	ds_read_b128 v[110:113], v238 offset:3584
	ds_read_b128 v[166:169], v238 offset:2560
	v_cndmask_b32_e64 v105, v104, 0, s[8:9]
	ds_read_b128 v[170:173], v238 offset:1536
	ds_read_b128 v[174:177], v238 offset:512
	v_cndmask_b32_e64 v104, v103, 0, s[8:9]
	v_cndmask_b32_e64 v103, 0, v102, s[6:7]
	v_cndmask_b32_e64 v102, 0, v101, s[6:7]
	v_cndmask_b32_e64 v95, 0, v95, s[4:5]
	v_cndmask_b32_e64 v94, 0, v94, s[4:5]
	v_cndmask_b32_e64 v93, v93, 0, s[8:9]
	v_cndmask_b32_e64 v92, v92, 0, s[8:9]
	v_cndmask_b32_e64 v91, 0, v91, s[6:7]
	v_cndmask_b32_e64 v90, 0, v90, s[6:7]
	v_cndmask_b32_e64 v89, 0, v89, s[4:5]
	v_cndmask_b32_e64 v88, 0, v88, s[4:5]
	s_waitcnt lgkmcnt(0)
	v_pk_fma_f32 v[84:85], v[84:85], v[110:111], v[106:107]
	v_pk_fma_f32 v[86:87], v[86:87], v[112:113], v[108:109]
	v_pk_fma_f32 v[84:85], v[104:105], v[166:167], v[84:85]
	v_pk_fma_f32 v[86:87], v[92:93], v[168:169], v[86:87]
	v_pk_fma_f32 v[84:85], v[102:103], v[170:171], v[84:85]
	s_nop 0
	v_pk_fma_f32 v[84:85], v[94:95], v[174:175], v[84:85]
	v_pk_fma_f32 v[86:87], v[90:91], v[172:173], v[86:87]
	v_mul_f32_e32 v94, 0xbfb8aa3b, v85
	v_exp_f32_e32 v94, v94
	v_pk_fma_f32 v[86:87], v[88:89], v[176:177], v[86:87]
	v_add_f32_e32 v94, 1.0, v94
	v_rcp_f32_e32 v95, v94
	v_mul_f32_e32 v94, 0xbfb8aa3b, v84
	v_exp_f32_e32 v94, v94
	s_nop 0
	v_add_f32_e32 v94, 1.0, v94
	v_rcp_f32_e32 v94, v94
	s_nop 0
	v_pk_mul_f32 v[84:85], v[84:85], v[94:95]
	s_nop 0
	v_cvt_pk_bf16_f32 v204, v84, v85
	v_mul_f32_e32 v85, 0xbfb8aa3b, v87
	v_exp_f32_e32 v85, v85
	s_nop 0
	v_add_f32_e32 v85, 1.0, v85
	v_rcp_f32_e32 v89, v85
	v_mul_f32_e32 v85, 0xbfb8aa3b, v86
	v_exp_f32_e32 v85, v85
	s_nop 0
	v_add_f32_e32 v85, 1.0, v85
	v_rcp_f32_e32 v88, v85
	s_nop 0
	v_pk_mul_f32 v[86:87], v[86:87], v[88:89]
	s_nop 0
	v_cvt_pk_bf16_f32 v205, v86, v87
;     __device__ __forceinline__ void operator()(const f32x4 (&acc)[2][2][4][2], const Unit& u, int wr, int wc, int fr, int fq, LAS unsigned char* hb) const {
;     ...
;             for (int m = 0; m < 4; ++m) { asm volatile("" ::: "memory"); __builtin_amdgcn_sched_barrier(0);
;                 const int q = 8 * ai + 4 * wr + m, prev = q > 0 ? q - 1 : 0; const int lr = ai * HALF + wr * 64 + m * 16 + fr, R = R0 + lr;
;                 const int Rc = R < 0 ? 0 : R; const int b = Rc / LL, p = Rc - b * LL;
;                 const bool ok = (lr >= H && R < TT);
;                 const unsigned ooff = ((unsigned)Rc * (unsigned)LDP + (unsigned)(OFF_XBC + ch0)) * 2u;
; #pragma unroll
;                 for (int bn = 0; bn < 4; ++bn) { const int bj = bn >> 1, n = bn & 1; const int co = bj * HALF + 4 * n;
;                     const unsigned woff = (unsigned)(ch0 + co) * 4u;
;                     const f32x4 w0 = *(const f32x4*)((const char*)cw + woff), w1 = *(const f32x4*)((const char*)cw + woff + XBCW * 4), w2 = *(const f32x4*)((const char*)cw + woff + 2 * XBCW * 4), w3 = *(const f32x4*)((const char*)cw + woff + 3 * XBCW * 4), bs = *(const f32x4*)((const char*)cb + woff);
;                     const LAS unsigned char* hp = hb + (prev * H * NCH + chl + co) * 2;
;                     const u32x2 q1 = *(const LAS u32x2*)(hp + hr1 * NCH * 2), q2 = *(const LAS u32x2*)(hp + hr2 * NCH * 2), q3 = *(const LAS u32x2*)(hp + hr3 * NCH * 2);
;                     const float h1[4] = {__builtin_bit_cast(float, q1.x << 16), __builtin_bit_cast(float, q1.x & 0xffff0000u), __builtin_bit_cast(float, q1.y << 16), __builtin_bit_cast(float, q1.y & 0xffff0000u)};
;                     const float h2[4] = {__builtin_bit_cast(float, q2.x << 16), __builtin_bit_cast(float, q2.x & 0xffff0000u), __builtin_bit_cast(float, q2.y << 16), __builtin_bit_cast(float, q2.y & 0xffff0000u)};
;                     const float h3[4] = {__builtin_bit_cast(float, q3.x << 16), __builtin_bit_cast(float, q3.x & 0xffff0000u), __builtin_bit_cast(float, q3.y << 16), __builtin_bit_cast(float, q3.y & 0xffff0000u)};
;                     const f32x4 gv = acc[ai][bj][m][n];
;                     float o[4];
; #pragma unroll
;                     for (int j = 0; j < 4; ++j) { const float g = gv[j];
;                         float g1 = dpp_row_shr<1>(h1[j], g), g2 = dpp_row_shr<2>(h2[j], g), g3 = dpp_row_shr<3>(h3[j], g);
.LBB0_205:
	s_or_b64 exec, exec, s[22:23]
	ds_read_b64 v[84:85], v98 offset:1288
	ds_read_b64 v[86:87], v99 offset:776
	ds_read_b64 v[98:99], v100 offset:264
	s_waitcnt lgkmcnt(0)
	v_lshlrev_b32_e32 v94, 16, v84
	v_and_b32_e32 v95, 0xffff0000, v84
	v_lshlrev_b32_e32 v88, 16, v85
	v_and_b32_e32 v89, 0xffff0000, v85
	v_lshlrev_b32_e32 v92, 16, v86
	v_and_b32_e32 v93, 0xffff0000, v86
	v_lshlrev_b32_e32 v86, 16, v87
	v_and_b32_e32 v87, 0xffff0000, v87
	v_lshlrev_b32_e32 v90, 16, v98
	v_and_b32_e32 v91, 0xffff0000, v98
	v_lshlrev_b32_e32 v84, 16, v99
	v_and_b32_e32 v85, 0xffff0000, v99
	v_mov_b32_dpp v94, v80 row_shr:1 row_mask:0xf bank_mask:0xf
	v_mov_b32_dpp v92, v80 row_shr:2 row_mask:0xf bank_mask:0xf
	v_mov_b32_dpp v90, v80 row_shr:3 row_mask:0xf bank_mask:0xf
	v_mov_b32_dpp v95, v81 row_shr:1 row_mask:0xf bank_mask:0xf
	v_mov_b32_dpp v93, v81 row_shr:2 row_mask:0xf bank_mask:0xf
	v_mov_b32_dpp v91, v81 row_shr:3 row_mask:0xf bank_mask:0xf
	v_mov_b32_dpp v88, v82 row_shr:1 row_mask:0xf bank_mask:0xf
	v_mov_b32_dpp v86, v82 row_shr:2 row_mask:0xf bank_mask:0xf
	v_mov_b32_dpp v84, v82 row_shr:3 row_mask:0xf bank_mask:0xf
	v_mov_b32_dpp v89, v83 row_shr:1 row_mask:0xf bank_mask:0xf
	v_mov_b32_dpp v87, v83 row_shr:2 row_mask:0xf bank_mask:0xf
	v_mov_b32_dpp v85, v83 row_shr:3 row_mask:0xf bank_mask:0xf
	s_and_saveexec_b64 s[22:23], s[2:3]
	s_cbranch_execz .LBB0_207
	ds_read_b128 v[98:101], v238 offset:4624
	ds_read_b128 v[102:105], v238 offset:3600
	ds_read_b128 v[106:109], v238 offset:2576
	v_cndmask_b32_e64 v95, v95, 0, s[8:9]
	ds_read_b128 v[110:113], v238 offset:1552
	s_nop 0
	ds_read_b128 v[166:169], v238 offset:528
	v_cndmask_b32_e64 v94, v94, 0, s[8:9]
	v_cndmask_b32_e64 v93, 0, v93, s[6:7]
	v_cndmask_b32_e64 v92, 0, v92, s[6:7]
	v_cndmask_b32_e64 v91, 0, v91, s[4:5]
	v_cndmask_b32_e64 v90, 0, v90, s[4:5]
	v_cndmask_b32_e64 v89, v89, 0, s[8:9]
	v_cndmask_b32_e64 v88, v88, 0, s[8:9]
	v_cndmask_b32_e64 v87, 0, v87, s[6:7]
	v_cndmask_b32_e64 v86, 0, v86, s[6:7]
	v_cndmask_b32_e64 v85, 0, v85, s[4:5]
	v_cndmask_b32_e64 v84, 0, v84, s[4:5]
	s_waitcnt lgkmcnt(0)
	v_pk_fma_f32 v[80:81], v[80:81], v[102:103], v[98:99]
	v_pk_fma_f32 v[82:83], v[82:83], v[104:105], v[100:101]
	v_pk_fma_f32 v[80:81], v[94:95], v[106:107], v[80:81]
	v_pk_fma_f32 v[82:83], v[88:89], v[108:109], v[82:83]
	v_pk_fma_f32 v[80:81], v[92:93], v[110:111], v[80:81]
	s_nop 0
	v_pk_fma_f32 v[80:81], v[90:91], v[166:167], v[80:81]
	v_pk_fma_f32 v[82:83], v[86:87], v[112:113], v[82:83]
	v_mul_f32_e32 v90, 0xbfb8aa3b, v81
	v_exp_f32_e32 v90, v90
	v_pk_fma_f32 v[82:83], v[84:85], v[168:169], v[82:83]
	v_add_f32_e32 v90, 1.0, v90
	v_rcp_f32_e32 v91, v90
	v_mul_f32_e32 v90, 0xbfb8aa3b, v80
	v_exp_f32_e32 v90, v90
	s_nop 0
	v_add_f32_e32 v90, 1.0, v90
	v_rcp_f32_e32 v90, v90
	s_nop 0
	v_pk_mul_f32 v[80:81], v[80:81], v[90:91]
	s_nop 0
	v_cvt_pk_bf16_f32 v206, v80, v81
	v_mul_f32_e32 v81, 0xbfb8aa3b, v83
	v_exp_f32_e32 v81, v81
	s_nop 0
	v_add_f32_e32 v81, 1.0, v81
	v_rcp_f32_e32 v85, v81
	v_mul_f32_e32 v81, 0xbfb8aa3b, v82
	v_exp_f32_e32 v81, v81
	s_nop 0
	v_add_f32_e32 v81, 1.0, v81
	v_rcp_f32_e32 v84, v81
	s_nop 0
	v_pk_mul_f32 v[82:83], v[82:83], v[84:85]
	s_nop 0
	v_cvt_pk_bf16_f32 v207, v82, v83
	global_store_dwordx4 v[96:97], v[204:207], off offset:256
.LBB0_207:
	s_or_b64 exec, exec, s[22:23]
	v_add_u32_e32 v80, 48, v161
	v_add_u32_e32 v81, s17, v80
	v_max_i32_e32 v82, 0, v81
	v_mul_hi_u32 v83, v82, s56
	v_lshrrev_b32_e32 v83, 11, v83
	v_cmp_lt_i32_e32 vcc, 2, v80
	v_mul_lo_u32 v80, v82, s51
	v_mul_u32_u24_e32 v83, 0x1010, v83
	v_add_lshl_u32 v136, v80, v164, 1
	v_add_u32_e32 v80, s40, v165
	v_sub_u32_e32 v83, v82, v83
	v_cmp_gt_i32_e64 s[4:5], s50, v81
	v_lshl_add_u32 v82, v80, 1, s53
	s_and_b64 s[2:3], vcc, s[4:5]
	v_cmp_eq_u32_e64 s[8:9], 0, v83
	v_cmp_lt_u32_e64 s[6:7], 1, v83
	v_cmp_lt_u32_e64 s[4:5], 2, v83
	v_add_u32_e32 v83, v82, v163
	ds_read_b64 v[80:81], v82 offset:1024
	v_add_u32_e32 v84, v82, v162
	ds_read_b64 v[98:99], v83 offset:512
	ds_read_b64 v[100:101], v84
	v_readlane_b32 s22, v237, 58
	v_readlane_b32 s23, v237, 59
	s_waitcnt lgkmcnt(0)
	v_lshlrev_b32_e32 v95, 16, v80
	v_and_b32_e32 v96, 0xffff0000, v80
	v_lshlrev_b32_e32 v89, 16, v81
	v_and_b32_e32 v90, 0xffff0000, v81
	v_lshlrev_b32_e32 v93, 16, v98
	v_and_b32_e32 v94, 0xffff0000, v98
	v_lshlrev_b32_e32 v87, 16, v99
	v_and_b32_e32 v88, 0xffff0000, v99
	v_lshlrev_b32_e32 v91, 16, v100
	v_and_b32_e32 v92, 0xffff0000, v100
	v_lshlrev_b32_e32 v85, 16, v101
	v_and_b32_e32 v86, 0xffff0000, v101
	v_mov_b32_dpp v95, v76 row_shr:1 row_mask:0xf bank_mask:0xf
	v_mov_b32_dpp v93, v76 row_shr:2 row_mask:0xf bank_mask:0xf
	v_mov_b32_dpp v91, v76 row_shr:3 row_mask:0xf bank_mask:0xf
	v_mov_b32_dpp v96, v77 row_shr:1 row_mask:0xf bank_mask:0xf
	v_mov_b32_dpp v94, v77 row_shr:2 row_mask:0xf bank_mask:0xf
	v_mov_b32_dpp v92, v77 row_shr:3 row_mask:0xf bank_mask:0xf
	v_mov_b32_dpp v89, v78 row_shr:1 row_mask:0xf bank_mask:0xf
	v_mov_b32_dpp v87, v78 row_shr:2 row_mask:0xf bank_mask:0xf
	v_mov_b32_dpp v85, v78 row_shr:3 row_mask:0xf bank_mask:0xf
	v_mov_b32_dpp v90, v79 row_shr:1 row_mask:0xf bank_mask:0xf
	v_mov_b32_dpp v88, v79 row_shr:2 row_mask:0xf bank_mask:0xf
	v_mov_b32_dpp v86, v79 row_shr:3 row_mask:0xf bank_mask:0xf
	v_lshl_add_u64 v[80:81], s[22:23], 0, v[136:137]
	s_and_saveexec_b64 s[22:23], s[2:3]
	s_cbranch_execz .LBB0_209
;     __device__ __forceinline__ void operator()(const f32x4 (&acc)[2][2][4][2], const Unit& u, int wr, int wc, int fr, int fq, LAS unsigned char* hb) const {
;     ...
;             for (int m = 0; m < 4; ++m) { asm volatile("" ::: "memory"); __builtin_amdgcn_sched_barrier(0);
;                 const int q = 8 * ai + 4 * wr + m, prev = q > 0 ? q - 1 : 0; const int lr = ai * HALF + wr * 64 + m * 16 + fr, R = R0 + lr;
;                 const int Rc = R < 0 ? 0 : R; const int b = Rc / LL, p = Rc - b * LL;
;                 const bool ok = (lr >= H && R < TT);
;                 const unsigned ooff = ((unsigned)Rc * (unsigned)LDP + (unsigned)(OFF_XBC + ch0)) * 2u;
; #pragma unroll
;                 for (int bn = 0; bn < 4; ++bn) { const int bj = bn >> 1, n = bn & 1; const int co = bj * HALF + 4 * n;
;                     const unsigned woff = (unsigned)(ch0 + co) * 4u;
;                     const f32x4 w0 = *(const f32x4*)((const char*)cw + woff), w1 = *(const f32x4*)((const char*)cw + woff + XBCW * 4), w2 = *(const f32x4*)((const char*)cw + woff + 2 * XBCW * 4), w3 = *(const f32x4*)((const char*)cw + woff + 3 * XBCW * 4), bs = *(const f32x4*)((const char*)cb + woff);
;                     const LAS unsigned char* hp = hb + (prev * H * NCH + chl + co) * 2;
;                     const u32x2 q1 = *(const LAS u32x2*)(hp + hr1 * NCH * 2), q2 = *(const LAS u32x2*)(hp + hr2 * NCH * 2), q3 = *(const LAS u32x2*)(hp + hr3 * NCH * 2);
;                     const float h1[4] = {__builtin_bit_cast(float, q1.x << 16), __builtin_bit_cast(float, q1.x & 0xffff0000u), __builtin_bit_cast(float, q1.y << 16), __builtin_bit_cast(float, q1.y & 0xffff0000u)};
;                     const float h2[4] = {__builtin_bit_cast(float, q2.x << 16), __builtin_bit_cast(float, q2.x & 0xffff0000u), __builtin_bit_cast(float, q2.y << 16), __builtin_bit_cast(float, q2.y & 0xffff0000u)};
;                     const float h3[4] = {__builtin_bit_cast(float, q3.x << 16), __builtin_bit_cast(float, q3.x & 0xffff0000u), __builtin_bit_cast(float, q3.y << 16), __builtin_bit_cast(float, q3.y & 0xffff0000u)};
;                     const f32x4 gv = acc[ai][bj][m][n];
;                     float o[4];
; #pragma unroll
;                     for (int j = 0; j < 4; ++j) { const float g = gv[j];
;                         float g1 = dpp_row_shr<1>(h1[j], g), g2 = dpp_row_shr<2>(h2[j], g), g3 = dpp_row_shr<3>(h3[j], g);
	ds_read_b128 v[98:101], v238 offset:4096
	ds_read_b128 v[102:105], v238 offset:3072
	ds_read_b128 v[106:109], v238 offset:2048
	v_cndmask_b32_e64 v97, v96, 0, s[8:9]
	ds_read_b128 v[110:113], v238 offset:1024
	s_nop 0
	ds_read_b128 v[166:169], v238
	v_cndmask_b32_e64 v96, v95, 0, s[8:9]
	v_cndmask_b32_e64 v95, 0, v94, s[6:7]
	v_cndmask_b32_e64 v94, 0, v93, s[6:7]
	v_cndmask_b32_e64 v93, 0, v92, s[4:5]
	v_cndmask_b32_e64 v92, 0, v91, s[4:5]
	s_waitcnt lgkmcnt(0)
	v_pk_fma_f32 v[76:77], v[76:77], v[102:103], v[98:99]
	v_pk_fma_f32 v[78:79], v[78:79], v[104:105], v[100:101]
	v_pk_fma_f32 v[76:77], v[96:97], v[106:107], v[76:77]
	s_nop 0
	v_pk_fma_f32 v[76:77], v[94:95], v[110:111], v[76:77]
	s_nop 0
	v_pk_fma_f32 v[76:77], v[92:93], v[166:167], v[76:77]
	s_nop 0
	v_mul_f32_e32 v91, 0xbfb8aa3b, v77
	v_exp_f32_e32 v91, v91
	s_nop 0
	v_add_f32_e32 v91, 1.0, v91
	v_rcp_f32_e32 v93, v91
	v_mul_f32_e32 v91, 0xbfb8aa3b, v76
	v_exp_f32_e32 v91, v91
	s_nop 0
	v_add_f32_e32 v91, 1.0, v91
	v_rcp_f32_e32 v92, v91
	v_cndmask_b32_e64 v91, v90, 0, s[8:9]
	v_cndmask_b32_e64 v90, v89, 0, s[8:9]
	v_pk_fma_f32 v[78:79], v[90:91], v[108:109], v[78:79]
	v_cndmask_b32_e64 v89, 0, v88, s[6:7]
	v_cndmask_b32_e64 v88, 0, v87, s[6:7]
	v_pk_fma_f32 v[78:79], v[88:89], v[112:113], v[78:79]
	v_cndmask_b32_e64 v87, 0, v86, s[4:5]
	v_cndmask_b32_e64 v86, 0, v85, s[4:5]
	v_pk_mul_f32 v[76:77], v[76:77], v[92:93]
	v_pk_fma_f32 v[78:79], v[86:87], v[168:169], v[78:79]
	v_cvt_pk_bf16_f32 v204, v76, v77
	v_mul_f32_e32 v77, 0xbfb8aa3b, v79
	v_exp_f32_e32 v77, v77
	s_nop 0
	v_add_f32_e32 v77, 1.0, v77
	v_rcp_f32_e32 v87, v77
	v_mul_f32_e32 v77, 0xbfb8aa3b, v78
	v_exp_f32_e32 v77, v77
	s_nop 0
	v_add_f32_e32 v77, 1.0, v77
	v_rcp_f32_e32 v86, v77
	s_nop 0
	v_pk_mul_f32 v[78:79], v[78:79], v[86:87]
	s_nop 0
	v_cvt_pk_bf16_f32 v205, v78, v79
.LBB0_209:
	s_or_b64 exec, exec, s[22:23]
	ds_read_b64 v[76:77], v82 offset:1032
	ds_read_b64 v[78:79], v83 offset:520
	ds_read_b64 v[94:95], v84 offset:8
	s_waitcnt lgkmcnt(0)
	v_lshlrev_b32_e32 v91, 16, v76
	v_and_b32_e32 v92, 0xffff0000, v76
	v_lshlrev_b32_e32 v85, 16, v77
	v_and_b32_e32 v86, 0xffff0000, v77
	v_lshlrev_b32_e32 v89, 16, v78
	v_and_b32_e32 v90, 0xffff0000, v78
	v_lshlrev_b32_e32 v78, 16, v79
	v_and_b32_e32 v79, 0xffff0000, v79
	v_lshlrev_b32_e32 v87, 16, v94
	v_and_b32_e32 v88, 0xffff0000, v94
	v_lshlrev_b32_e32 v76, 16, v95
	v_and_b32_e32 v77, 0xffff0000, v95
	v_mov_b32_dpp v91, v72 row_shr:1 row_mask:0xf bank_mask:0xf
	v_mov_b32_dpp v89, v72 row_shr:2 row_mask:0xf bank_mask:0xf
	v_mov_b32_dpp v87, v72 row_shr:3 row_mask:0xf bank_mask:0xf
	v_mov_b32_dpp v92, v73 row_shr:1 row_mask:0xf bank_mask:0xf
	v_mov_b32_dpp v90, v73 row_shr:2 row_mask:0xf bank_mask:0xf
	v_mov_b32_dpp v88, v73 row_shr:3 row_mask:0xf bank_mask:0xf
	v_mov_b32_dpp v85, v74 row_shr:1 row_mask:0xf bank_mask:0xf
	v_mov_b32_dpp v78, v74 row_shr:2 row_mask:0xf bank_mask:0xf
	v_mov_b32_dpp v76, v74 row_shr:3 row_mask:0xf bank_mask:0xf
	v_mov_b32_dpp v86, v75 row_shr:1 row_mask:0xf bank_mask:0xf
	v_mov_b32_dpp v79, v75 row_shr:2 row_mask:0xf bank_mask:0xf
	v_mov_b32_dpp v77, v75 row_shr:3 row_mask:0xf bank_mask:0xf
	s_and_saveexec_b64 s[22:23], s[2:3]
	s_cbranch_execz .LBB0_211
	ds_read_b128 v[94:97], v238 offset:4112
	ds_read_b128 v[98:101], v238 offset:3088
	ds_read_b128 v[102:105], v238 offset:2064
	v_cndmask_b32_e64 v93, v92, 0, s[8:9]
	ds_read_b128 v[106:109], v238 offset:1040
	s_nop 0
	ds_read_b128 v[110:113], v238 offset:16
	v_cndmask_b32_e64 v92, v91, 0, s[8:9]
	v_cndmask_b32_e64 v91, 0, v90, s[6:7]
	v_cndmask_b32_e64 v90, 0, v89, s[6:7]
	v_cndmask_b32_e64 v89, 0, v88, s[4:5]
	v_cndmask_b32_e64 v88, 0, v87, s[4:5]
	v_cndmask_b32_e64 v79, 0, v79, s[6:7]
	v_cndmask_b32_e64 v78, 0, v78, s[6:7]
	v_cndmask_b32_e64 v77, 0, v77, s[4:5]
	v_cndmask_b32_e64 v76, 0, v76, s[4:5]
	s_waitcnt lgkmcnt(0)
	v_pk_fma_f32 v[72:73], v[72:73], v[98:99], v[94:95]
	v_pk_fma_f32 v[74:75], v[74:75], v[100:101], v[96:97]
	v_pk_fma_f32 v[72:73], v[92:93], v[102:103], v[72:73]
	s_nop 0
	v_pk_fma_f32 v[72:73], v[90:91], v[106:107], v[72:73]
	s_nop 0
	v_pk_fma_f32 v[72:73], v[88:89], v[110:111], v[72:73]
	s_nop 0
	v_mul_f32_e32 v87, 0xbfb8aa3b, v73
	v_exp_f32_e32 v87, v87
	s_nop 0
	v_add_f32_e32 v87, 1.0, v87
	v_rcp_f32_e32 v89, v87
	v_mul_f32_e32 v87, 0xbfb8aa3b, v72
	v_exp_f32_e32 v87, v87
	s_nop 0
	v_add_f32_e32 v87, 1.0, v87
	v_rcp_f32_e32 v88, v87
	v_cndmask_b32_e64 v87, v86, 0, s[8:9]
	v_cndmask_b32_e64 v86, v85, 0, s[8:9]
	v_pk_fma_f32 v[74:75], v[86:87], v[104:105], v[74:75]
	v_pk_mul_f32 v[72:73], v[72:73], v[88:89]
	v_pk_fma_f32 v[74:75], v[78:79], v[108:109], v[74:75]
	v_cvt_pk_bf16_f32 v206, v72, v73
	v_pk_fma_f32 v[74:75], v[76:77], v[112:113], v[74:75]
	s_nop 0
	v_mul_f32_e32 v73, 0xbfb8aa3b, v75
	v_exp_f32_e32 v73, v73
	s_nop 0
	v_add_f32_e32 v73, 1.0, v73
	v_rcp_f32_e32 v77, v73
	v_mul_f32_e32 v73, 0xbfb8aa3b, v74
	v_exp_f32_e32 v73, v73
	s_nop 0
	v_add_f32_e32 v73, 1.0, v73
	v_rcp_f32_e32 v76, v73
	s_nop 0
	v_pk_mul_f32 v[74:75], v[74:75], v[76:77]
	s_nop 0
	v_cvt_pk_bf16_f32 v207, v74, v75
	global_store_dwordx4 v[80:81], v[204:207], off
;     __device__ __forceinline__ void operator()(const f32x4 (&acc)[2][2][4][2], const Unit& u, int wr, int wc, int fr, int fq, LAS unsigned char* hb) const {
;     ...
;             for (int m = 0; m < 4; ++m) { asm volatile("" ::: "memory"); __builtin_amdgcn_sched_barrier(0);
;                 const int q = 8 * ai + 4 * wr + m, prev = q > 0 ? q - 1 : 0; const int lr = ai * HALF + wr * 64 + m * 16 + fr, R = R0 + lr;
;                 const int Rc = R < 0 ? 0 : R; const int b = Rc / LL, p = Rc - b * LL;
;                 const bool ok = (lr >= H && R < TT);
;                 const unsigned ooff = ((unsigned)Rc * (unsigned)LDP + (unsigned)(OFF_XBC + ch0)) * 2u;
; #pragma unroll
;                 for (int bn = 0; bn < 4; ++bn) { const int bj = bn >> 1, n = bn & 1; const int co = bj * HALF + 4 * n;
;                     const unsigned woff = (unsigned)(ch0 + co) * 4u;
;                     const f32x4 w0 = *(const f32x4*)((const char*)cw + woff), w1 = *(const f32x4*)((const char*)cw + woff + XBCW * 4), w2 = *(const f32x4*)((const char*)cw + woff + 2 * XBCW * 4), w3 = *(const f32x4*)((const char*)cw + woff + 3 * XBCW * 4), bs = *(const f32x4*)((const char*)cb + woff);
;                     const LAS unsigned char* hp = hb + (prev * H * NCH + chl + co) * 2;
;                     const u32x2 q1 = *(const LAS u32x2*)(hp + hr1 * NCH * 2), q2 = *(const LAS u32x2*)(hp + hr2 * NCH * 2), q3 = *(const LAS u32x2*)(hp + hr3 * NCH * 2);
;                     const float h1[4] = {__builtin_bit_cast(float, q1.x << 16), __builtin_bit_cast(float, q1.x & 0xffff0000u), __builtin_bit_cast(float, q1.y << 16), __builtin_bit_cast(float, q1.y & 0xffff0000u)};
;                     const float h2[4] = {__builtin_bit_cast(float, q2.x << 16), __builtin_bit_cast(float, q2.x & 0xffff0000u), __builtin_bit_cast(float, q2.y << 16), __builtin_bit_cast(float, q2.y & 0xffff0000u)};
;                     const float h3[4] = {__builtin_bit_cast(float, q3.x << 16), __builtin_bit_cast(float, q3.x & 0xffff0000u), __builtin_bit_cast(float, q3.y << 16), __builtin_bit_cast(float, q3.y & 0xffff0000u)};
;                     const f32x4 gv = acc[ai][bj][m][n];
;                     float o[4];
; #pragma unroll
;                     for (int j = 0; j < 4; ++j) { const float g = gv[j];
;                         float g1 = dpp_row_shr<1>(h1[j], g), g2 = dpp_row_shr<2>(h2[j], g), g3 = dpp_row_shr<3>(h3[j], g);
.LBB0_211:
	s_or_b64 exec, exec, s[22:23]
	ds_read_b64 v[72:73], v82 offset:1280
	ds_read_b64 v[74:75], v83 offset:768
	ds_read_b64 v[90:91], v84 offset:256
	s_waitcnt lgkmcnt(0)
	v_lshlrev_b32_e32 v87, 16, v72
	v_and_b32_e32 v88, 0xffff0000, v72
	v_lshlrev_b32_e32 v76, 16, v73
	v_and_b32_e32 v77, 0xffff0000, v73
	v_lshlrev_b32_e32 v85, 16, v74
	v_and_b32_e32 v86, 0xffff0000, v74
	v_lshlrev_b32_e32 v74, 16, v75
	v_and_b32_e32 v75, 0xffff0000, v75
	v_lshlrev_b32_e32 v78, 16, v90
	v_and_b32_e32 v79, 0xffff0000, v90
	v_lshlrev_b32_e32 v72, 16, v91
	v_and_b32_e32 v73, 0xffff0000, v91
	v_mov_b32_dpp v87, v68 row_shr:1 row_mask:0xf bank_mask:0xf
	v_mov_b32_dpp v85, v68 row_shr:2 row_mask:0xf bank_mask:0xf
	v_mov_b32_dpp v78, v68 row_shr:3 row_mask:0xf bank_mask:0xf
	v_mov_b32_dpp v88, v69 row_shr:1 row_mask:0xf bank_mask:0xf
	v_mov_b32_dpp v86, v69 row_shr:2 row_mask:0xf bank_mask:0xf
	v_mov_b32_dpp v79, v69 row_shr:3 row_mask:0xf bank_mask:0xf
	v_mov_b32_dpp v76, v70 row_shr:1 row_mask:0xf bank_mask:0xf
	v_mov_b32_dpp v74, v70 row_shr:2 row_mask:0xf bank_mask:0xf
	v_mov_b32_dpp v72, v70 row_shr:3 row_mask:0xf bank_mask:0xf
	v_mov_b32_dpp v77, v71 row_shr:1 row_mask:0xf bank_mask:0xf
	v_mov_b32_dpp v75, v71 row_shr:2 row_mask:0xf bank_mask:0xf
	v_mov_b32_dpp v73, v71 row_shr:3 row_mask:0xf bank_mask:0xf
	s_and_saveexec_b64 s[22:23], s[2:3]
	s_cbranch_execz .LBB0_213
	ds_read_b128 v[90:93], v238 offset:4608
	ds_read_b128 v[94:97], v238 offset:3584
	ds_read_b128 v[98:101], v238 offset:2560
	v_cndmask_b32_e64 v89, v88, 0, s[8:9]
	ds_read_b128 v[102:105], v238 offset:1536
	s_nop 0
	ds_read_b128 v[106:109], v238 offset:512
	v_cndmask_b32_e64 v88, v87, 0, s[8:9]
	v_cndmask_b32_e64 v87, 0, v86, s[6:7]
	v_cndmask_b32_e64 v86, 0, v85, s[6:7]
	v_cndmask_b32_e64 v79, 0, v79, s[4:5]
	v_cndmask_b32_e64 v78, 0, v78, s[4:5]
	v_cndmask_b32_e64 v77, v77, 0, s[8:9]
	v_cndmask_b32_e64 v76, v76, 0, s[8:9]
	v_cndmask_b32_e64 v75, 0, v75, s[6:7]
	v_cndmask_b32_e64 v74, 0, v74, s[6:7]
	v_cndmask_b32_e64 v73, 0, v73, s[4:5]
	v_cndmask_b32_e64 v72, 0, v72, s[4:5]
	s_waitcnt lgkmcnt(0)
	v_pk_fma_f32 v[68:69], v[68:69], v[94:95], v[90:91]
	v_pk_fma_f32 v[70:71], v[70:71], v[96:97], v[92:93]
	v_pk_fma_f32 v[68:69], v[88:89], v[98:99], v[68:69]
	v_pk_fma_f32 v[70:71], v[76:77], v[100:101], v[70:71]
	v_pk_fma_f32 v[68:69], v[86:87], v[102:103], v[68:69]
	s_nop 0
	v_pk_fma_f32 v[68:69], v[78:79], v[106:107], v[68:69]
	v_pk_fma_f32 v[70:71], v[74:75], v[104:105], v[70:71]
	v_mul_f32_e32 v78, 0xbfb8aa3b, v69
	v_exp_f32_e32 v78, v78
	v_pk_fma_f32 v[70:71], v[72:73], v[108:109], v[70:71]
	v_add_f32_e32 v78, 1.0, v78
	v_rcp_f32_e32 v79, v78
	v_mul_f32_e32 v78, 0xbfb8aa3b, v68
	v_exp_f32_e32 v78, v78
	s_nop 0
	v_add_f32_e32 v78, 1.0, v78
	v_rcp_f32_e32 v78, v78
	s_nop 0
	v_pk_mul_f32 v[68:69], v[68:69], v[78:79]
	s_nop 0
	v_cvt_pk_bf16_f32 v204, v68, v69
	v_mul_f32_e32 v69, 0xbfb8aa3b, v71
	v_exp_f32_e32 v69, v69
	s_nop 0
	v_add_f32_e32 v69, 1.0, v69
	v_rcp_f32_e32 v73, v69
	v_mul_f32_e32 v69, 0xbfb8aa3b, v70
	v_exp_f32_e32 v69, v69
	s_nop 0
	v_add_f32_e32 v69, 1.0, v69
	v_rcp_f32_e32 v72, v69
	s_nop 0
	v_pk_mul_f32 v[70:71], v[70:71], v[72:73]
	s_nop 0
	v_cvt_pk_bf16_f32 v205, v70, v71
.LBB0_213:
	s_or_b64 exec, exec, s[22:23]
	ds_read_b64 v[68:69], v82 offset:1288
	ds_read_b64 v[70:71], v83 offset:776
	ds_read_b64 v[82:83], v84 offset:264
	s_waitcnt lgkmcnt(0)
	v_lshlrev_b32_e32 v78, 16, v68
	v_and_b32_e32 v79, 0xffff0000, v68
	v_lshlrev_b32_e32 v72, 16, v69
	v_and_b32_e32 v73, 0xffff0000, v69
	v_lshlrev_b32_e32 v76, 16, v70
	v_and_b32_e32 v77, 0xffff0000, v70
	v_lshlrev_b32_e32 v70, 16, v71
	v_and_b32_e32 v71, 0xffff0000, v71
	v_lshlrev_b32_e32 v74, 16, v82
	v_and_b32_e32 v75, 0xffff0000, v82
	v_lshlrev_b32_e32 v68, 16, v83
	v_and_b32_e32 v69, 0xffff0000, v83
	v_mov_b32_dpp v78, v64 row_shr:1 row_mask:0xf bank_mask:0xf
	v_mov_b32_dpp v76, v64 row_shr:2 row_mask:0xf bank_mask:0xf
	v_mov_b32_dpp v74, v64 row_shr:3 row_mask:0xf bank_mask:0xf
	v_mov_b32_dpp v79, v65 row_shr:1 row_mask:0xf bank_mask:0xf
	v_mov_b32_dpp v77, v65 row_shr:2 row_mask:0xf bank_mask:0xf
	v_mov_b32_dpp v75, v65 row_shr:3 row_mask:0xf bank_mask:0xf
	v_mov_b32_dpp v72, v66 row_shr:1 row_mask:0xf bank_mask:0xf
	v_mov_b32_dpp v70, v66 row_shr:2 row_mask:0xf bank_mask:0xf
	v_mov_b32_dpp v68, v66 row_shr:3 row_mask:0xf bank_mask:0xf
	v_mov_b32_dpp v73, v67 row_shr:1 row_mask:0xf bank_mask:0xf
	v_mov_b32_dpp v71, v67 row_shr:2 row_mask:0xf bank_mask:0xf
	v_mov_b32_dpp v69, v67 row_shr:3 row_mask:0xf bank_mask:0xf
	s_and_saveexec_b64 s[22:23], s[2:3]
	s_cbranch_execz .LBB0_215
	ds_read_b128 v[82:85], v238 offset:4624
	ds_read_b128 v[86:89], v238 offset:3600
	ds_read_b128 v[90:93], v238 offset:2576
	v_cndmask_b32_e64 v79, v79, 0, s[8:9]
	ds_read_b128 v[94:97], v238 offset:1552
	s_nop 0
	ds_read_b128 v[98:101], v238 offset:528
	v_cndmask_b32_e64 v78, v78, 0, s[8:9]
	v_cndmask_b32_e64 v77, 0, v77, s[6:7]
	v_cndmask_b32_e64 v76, 0, v76, s[6:7]
	v_cndmask_b32_e64 v75, 0, v75, s[4:5]
	v_cndmask_b32_e64 v74, 0, v74, s[4:5]
	v_cndmask_b32_e64 v73, v73, 0, s[8:9]
	v_cndmask_b32_e64 v72, v72, 0, s[8:9]
	v_cndmask_b32_e64 v71, 0, v71, s[6:7]
	v_cndmask_b32_e64 v70, 0, v70, s[6:7]
	v_cndmask_b32_e64 v69, 0, v69, s[4:5]
	v_cndmask_b32_e64 v68, 0, v68, s[4:5]
	s_waitcnt lgkmcnt(0)
	v_pk_fma_f32 v[64:65], v[64:65], v[86:87], v[82:83]
	v_pk_fma_f32 v[66:67], v[66:67], v[88:89], v[84:85]
	v_pk_fma_f32 v[64:65], v[78:79], v[90:91], v[64:65]
	v_pk_fma_f32 v[66:67], v[72:73], v[92:93], v[66:67]
	v_pk_fma_f32 v[64:65], v[76:77], v[94:95], v[64:65]
	s_nop 0
	v_pk_fma_f32 v[64:65], v[74:75], v[98:99], v[64:65]
	v_pk_fma_f32 v[66:67], v[70:71], v[96:97], v[66:67]
	v_mul_f32_e32 v74, 0xbfb8aa3b, v65
	v_exp_f32_e32 v74, v74
	v_pk_fma_f32 v[66:67], v[68:69], v[100:101], v[66:67]
	v_add_f32_e32 v74, 1.0, v74
	v_rcp_f32_e32 v75, v74
	v_mul_f32_e32 v74, 0xbfb8aa3b, v64
	v_exp_f32_e32 v74, v74
	s_nop 0
	v_add_f32_e32 v74, 1.0, v74
	v_rcp_f32_e32 v74, v74
	s_nop 0
	v_pk_mul_f32 v[64:65], v[64:65], v[74:75]
	s_nop 0
	v_cvt_pk_bf16_f32 v206, v64, v65
	v_mul_f32_e32 v65, 0xbfb8aa3b, v67
	v_exp_f32_e32 v65, v65
	s_nop 0
	v_add_f32_e32 v65, 1.0, v65
	v_rcp_f32_e32 v69, v65
	v_mul_f32_e32 v65, 0xbfb8aa3b, v66
	v_exp_f32_e32 v65, v65
	s_nop 0
	v_add_f32_e32 v65, 1.0, v65
	v_rcp_f32_e32 v68, v65
	s_nop 0
	v_pk_mul_f32 v[66:67], v[66:67], v[68:69]
	s_nop 0
	v_cvt_pk_bf16_f32 v207, v66, v67
	global_store_dwordx4 v[80:81], v[204:207], off offset:256
;     __device__ __forceinline__ void operator()(const f32x4 (&acc)[2][2][4][2], const Unit& u, int wr, int wc, int fr, int fq, LAS unsigned char* hb) const {
;     ...
;             for (int m = 0; m < 4; ++m) { asm volatile("" ::: "memory"); __builtin_amdgcn_sched_barrier(0);
;                 const int q = 8 * ai + 4 * wr + m, prev = q > 0 ? q - 1 : 0; const int lr = ai * HALF + wr * 64 + m * 16 + fr, R = R0 + lr;
;                 const int Rc = R < 0 ? 0 : R; const int b = Rc / LL, p = Rc - b * LL;
;                 const bool ok = (lr >= H && R < TT);
;                 const unsigned ooff = ((unsigned)Rc * (unsigned)LDP + (unsigned)(OFF_XBC + ch0)) * 2u;
; #pragma unroll
;                 for (int bn = 0; bn < 4; ++bn) { const int bj = bn >> 1, n = bn & 1; const int co = bj * HALF + 4 * n;
;                     const unsigned woff = (unsigned)(ch0 + co) * 4u;
;                     const f32x4 w0 = *(const f32x4*)((const char*)cw + woff), w1 = *(const f32x4*)((const char*)cw + woff + XBCW * 4), w2 = *(const f32x4*)((const char*)cw + woff + 2 * XBCW * 4), w3 = *(const f32x4*)((const char*)cw + woff + 3 * XBCW * 4), bs = *(const f32x4*)((const char*)cb + woff);
;                     const LAS unsigned char* hp = hb + (prev * H * NCH + chl + co) * 2;
;                     const u32x2 q1 = *(const LAS u32x2*)(hp + hr1 * NCH * 2), q2 = *(const LAS u32x2*)(hp + hr2 * NCH * 2), q3 = *(const LAS u32x2*)(hp + hr3 * NCH * 2);
;                     const float h1[4] = {__builtin_bit_cast(float, q1.x << 16), __builtin_bit_cast(float, q1.x & 0xffff0000u), __builtin_bit_cast(float, q1.y << 16), __builtin_bit_cast(float, q1.y & 0xffff0000u)};
;                     const float h2[4] = {__builtin_bit_cast(float, q2.x << 16), __builtin_bit_cast(float, q2.x & 0xffff0000u), __builtin_bit_cast(float, q2.y << 16), __builtin_bit_cast(float, q2.y & 0xffff0000u)};
;                     const float h3[4] = {__builtin_bit_cast(float, q3.x << 16), __builtin_bit_cast(float, q3.x & 0xffff0000u), __builtin_bit_cast(float, q3.y << 16), __builtin_bit_cast(float, q3.y & 0xffff0000u)};
;                     const f32x4 gv = acc[ai][bj][m][n];
;                     float o[4];
; #pragma unroll
;                     for (int j = 0; j < 4; ++j) { const float g = gv[j];
;                         float g1 = dpp_row_shr<1>(h1[j], g), g2 = dpp_row_shr<2>(h2[j], g), g3 = dpp_row_shr<3>(h3[j], g);
.LBB0_215:
	s_or_b64 exec, exec, s[22:23]
	v_add_u32_e32 v64, 0x80, v161
	v_add_u32_e32 v65, s17, v64
	v_max_i32_e32 v66, 0, v65
	v_mul_hi_u32 v67, v66, s56
	v_lshrrev_b32_e32 v67, 11, v67
	v_cmp_lt_i32_e32 vcc, 2, v64
	v_mul_lo_u32 v64, v66, s51
	v_mul_u32_u24_e32 v67, 0x1010, v67
	v_add_lshl_u32 v136, v64, v164, 1
	v_add_u32_e32 v64, s41, v165
	v_sub_u32_e32 v67, v66, v67
	v_cmp_gt_i32_e64 s[4:5], s50, v65
	v_lshl_add_u32 v66, v64, 1, s53
	s_and_b64 s[2:3], vcc, s[4:5]
	v_cmp_eq_u32_e64 s[8:9], 0, v67
	v_cmp_lt_u32_e64 s[6:7], 1, v67
	v_cmp_lt_u32_e64 s[4:5], 2, v67
	v_add_u32_e32 v67, v66, v163
	ds_read_b64 v[64:65], v66 offset:1024
	v_add_u32_e32 v68, v66, v162
	ds_read_b64 v[82:83], v67 offset:512
	ds_read_b64 v[84:85], v68
	v_readlane_b32 s22, v237, 58
	v_readlane_b32 s23, v237, 59
	s_waitcnt lgkmcnt(0)
	v_lshlrev_b32_e32 v79, 16, v64
	v_and_b32_e32 v80, 0xffff0000, v64
	v_lshlrev_b32_e32 v73, 16, v65
	v_and_b32_e32 v74, 0xffff0000, v65
	v_lshlrev_b32_e32 v77, 16, v82
	v_and_b32_e32 v78, 0xffff0000, v82
	v_lshlrev_b32_e32 v71, 16, v83
	v_and_b32_e32 v72, 0xffff0000, v83
	v_lshlrev_b32_e32 v75, 16, v84
	v_and_b32_e32 v76, 0xffff0000, v84
	v_lshlrev_b32_e32 v69, 16, v85
	v_and_b32_e32 v70, 0xffff0000, v85
	v_mov_b32_dpp v79, v60 row_shr:1 row_mask:0xf bank_mask:0xf
	v_mov_b32_dpp v77, v60 row_shr:2 row_mask:0xf bank_mask:0xf
	v_mov_b32_dpp v75, v60 row_shr:3 row_mask:0xf bank_mask:0xf
	v_mov_b32_dpp v80, v61 row_shr:1 row_mask:0xf bank_mask:0xf
	v_mov_b32_dpp v78, v61 row_shr:2 row_mask:0xf bank_mask:0xf
	v_mov_b32_dpp v76, v61 row_shr:3 row_mask:0xf bank_mask:0xf
	v_mov_b32_dpp v73, v62 row_shr:1 row_mask:0xf bank_mask:0xf
	v_mov_b32_dpp v71, v62 row_shr:2 row_mask:0xf bank_mask:0xf
	v_mov_b32_dpp v69, v62 row_shr:3 row_mask:0xf bank_mask:0xf
	v_mov_b32_dpp v74, v63 row_shr:1 row_mask:0xf bank_mask:0xf
	v_mov_b32_dpp v72, v63 row_shr:2 row_mask:0xf bank_mask:0xf
	v_mov_b32_dpp v70, v63 row_shr:3 row_mask:0xf bank_mask:0xf
	v_lshl_add_u64 v[64:65], s[22:23], 0, v[136:137]
	s_and_saveexec_b64 s[22:23], s[2:3]
	s_cbranch_execz .LBB0_217
	ds_read_b128 v[82:85], v238 offset:4096
	ds_read_b128 v[86:89], v238 offset:3072
	ds_read_b128 v[90:93], v238 offset:2048
	v_cndmask_b32_e64 v81, v80, 0, s[8:9]
	ds_read_b128 v[94:97], v238 offset:1024
	s_nop 0
	ds_read_b128 v[98:101], v238
	v_cndmask_b32_e64 v80, v79, 0, s[8:9]
	v_cndmask_b32_e64 v79, 0, v78, s[6:7]
	v_cndmask_b32_e64 v78, 0, v77, s[6:7]
	v_cndmask_b32_e64 v77, 0, v76, s[4:5]
	v_cndmask_b32_e64 v76, 0, v75, s[4:5]
	s_waitcnt lgkmcnt(0)
	v_pk_fma_f32 v[60:61], v[60:61], v[86:87], v[82:83]
	v_pk_fma_f32 v[62:63], v[62:63], v[88:89], v[84:85]
	v_pk_fma_f32 v[60:61], v[80:81], v[90:91], v[60:61]
	s_nop 0
	v_pk_fma_f32 v[60:61], v[78:79], v[94:95], v[60:61]
	s_nop 0
	v_pk_fma_f32 v[60:61], v[76:77], v[98:99], v[60:61]
	s_nop 0
	v_mul_f32_e32 v75, 0xbfb8aa3b, v61
	v_exp_f32_e32 v75, v75
	s_nop 0
	v_add_f32_e32 v75, 1.0, v75
	v_rcp_f32_e32 v77, v75
	v_mul_f32_e32 v75, 0xbfb8aa3b, v60
	v_exp_f32_e32 v75, v75
	s_nop 0
	v_add_f32_e32 v75, 1.0, v75
	v_rcp_f32_e32 v76, v75
	v_cndmask_b32_e64 v75, v74, 0, s[8:9]
	v_cndmask_b32_e64 v74, v73, 0, s[8:9]
	v_pk_fma_f32 v[62:63], v[74:75], v[92:93], v[62:63]
	v_cndmask_b32_e64 v73, 0, v72, s[6:7]
	v_cndmask_b32_e64 v72, 0, v71, s[6:7]
	v_pk_fma_f32 v[62:63], v[72:73], v[96:97], v[62:63]
	v_cndmask_b32_e64 v71, 0, v70, s[4:5]
	v_cndmask_b32_e64 v70, 0, v69, s[4:5]
	v_pk_mul_f32 v[60:61], v[60:61], v[76:77]
	v_pk_fma_f32 v[62:63], v[70:71], v[100:101], v[62:63]
	v_cvt_pk_bf16_f32 v204, v60, v61
	v_mul_f32_e32 v61, 0xbfb8aa3b, v63
	v_exp_f32_e32 v61, v61
	s_nop 0
	v_add_f32_e32 v61, 1.0, v61
	v_rcp_f32_e32 v71, v61
	v_mul_f32_e32 v61, 0xbfb8aa3b, v62
	v_exp_f32_e32 v61, v61
	s_nop 0
	v_add_f32_e32 v61, 1.0, v61
	v_rcp_f32_e32 v70, v61
	s_nop 0
	v_pk_mul_f32 v[62:63], v[62:63], v[70:71]
	s_nop 0
	v_cvt_pk_bf16_f32 v205, v62, v63
.LBB0_217:
	s_or_b64 exec, exec, s[22:23]
	ds_read_b64 v[60:61], v66 offset:1032
	ds_read_b64 v[62:63], v67 offset:520
	ds_read_b64 v[78:79], v68 offset:8
	s_waitcnt lgkmcnt(0)
	v_lshlrev_b32_e32 v75, 16, v60
	v_and_b32_e32 v76, 0xffff0000, v60
	v_lshlrev_b32_e32 v69, 16, v61
	v_and_b32_e32 v70, 0xffff0000, v61
	v_lshlrev_b32_e32 v73, 16, v62
	v_and_b32_e32 v74, 0xffff0000, v62
	v_lshlrev_b32_e32 v62, 16, v63
	v_and_b32_e32 v63, 0xffff0000, v63
	v_lshlrev_b32_e32 v71, 16, v78
	v_and_b32_e32 v72, 0xffff0000, v78
	v_lshlrev_b32_e32 v60, 16, v79
	v_and_b32_e32 v61, 0xffff0000, v79
	v_mov_b32_dpp v75, v56 row_shr:1 row_mask:0xf bank_mask:0xf
	v_mov_b32_dpp v73, v56 row_shr:2 row_mask:0xf bank_mask:0xf
	v_mov_b32_dpp v71, v56 row_shr:3 row_mask:0xf bank_mask:0xf
	v_mov_b32_dpp v76, v57 row_shr:1 row_mask:0xf bank_mask:0xf
	v_mov_b32_dpp v74, v57 row_shr:2 row_mask:0xf bank_mask:0xf
	v_mov_b32_dpp v72, v57 row_shr:3 row_mask:0xf bank_mask:0xf
	v_mov_b32_dpp v69, v58 row_shr:1 row_mask:0xf bank_mask:0xf
	v_mov_b32_dpp v62, v58 row_shr:2 row_mask:0xf bank_mask:0xf
	v_mov_b32_dpp v60, v58 row_shr:3 row_mask:0xf bank_mask:0xf
	v_mov_b32_dpp v70, v59 row_shr:1 row_mask:0xf bank_mask:0xf
	v_mov_b32_dpp v63, v59 row_shr:2 row_mask:0xf bank_mask:0xf
	v_mov_b32_dpp v61, v59 row_shr:3 row_mask:0xf bank_mask:0xf
	s_and_saveexec_b64 s[22:23], s[2:3]
	s_cbranch_execz .LBB0_219
;     __device__ __forceinline__ void operator()(const f32x4 (&acc)[2][2][4][2], const Unit& u, int wr, int wc, int fr, int fq, LAS unsigned char* hb) const {
;     ...
;             for (int m = 0; m < 4; ++m) { asm volatile("" ::: "memory"); __builtin_amdgcn_sched_barrier(0);
;                 const int q = 8 * ai + 4 * wr + m, prev = q > 0 ? q - 1 : 0; const int lr = ai * HALF + wr * 64 + m * 16 + fr, R = R0 + lr;
;                 const int Rc = R < 0 ? 0 : R; const int b = Rc / LL, p = Rc - b * LL;
;                 const bool ok = (lr >= H && R < TT);
;                 const unsigned ooff = ((unsigned)Rc * (unsigned)LDP + (unsigned)(OFF_XBC + ch0)) * 2u;
; #pragma unroll
;                 for (int bn = 0; bn < 4; ++bn) { const int bj = bn >> 1, n = bn & 1; const int co = bj * HALF + 4 * n;
;                     const unsigned woff = (unsigned)(ch0 + co) * 4u;
;                     const f32x4 w0 = *(const f32x4*)((const char*)cw + woff), w1 = *(const f32x4*)((const char*)cw + woff + XBCW * 4), w2 = *(const f32x4*)((const char*)cw + woff + 2 * XBCW * 4), w3 = *(const f32x4*)((const char*)cw + woff + 3 * XBCW * 4), bs = *(const f32x4*)((const char*)cb + woff);
;                     const LAS unsigned char* hp = hb + (prev * H * NCH + chl + co) * 2;
;                     const u32x2 q1 = *(const LAS u32x2*)(hp + hr1 * NCH * 2), q2 = *(const LAS u32x2*)(hp + hr2 * NCH * 2), q3 = *(const LAS u32x2*)(hp + hr3 * NCH * 2);
;                     const float h1[4] = {__builtin_bit_cast(float, q1.x << 16), __builtin_bit_cast(float, q1.x & 0xffff0000u), __builtin_bit_cast(float, q1.y << 16), __builtin_bit_cast(float, q1.y & 0xffff0000u)};
;                     const float h2[4] = {__builtin_bit_cast(float, q2.x << 16), __builtin_bit_cast(float, q2.x & 0xffff0000u), __builtin_bit_cast(float, q2.y << 16), __builtin_bit_cast(float, q2.y & 0xffff0000u)};
;                     const float h3[4] = {__builtin_bit_cast(float, q3.x << 16), __builtin_bit_cast(float, q3.x & 0xffff0000u), __builtin_bit_cast(float, q3.y << 16), __builtin_bit_cast(float, q3.y & 0xffff0000u)};
;                     const f32x4 gv = acc[ai][bj][m][n];
;                     float o[4];
; #pragma unroll
;                     for (int j = 0; j < 4; ++j) { const float g = gv[j];
;                         float g1 = dpp_row_shr<1>(h1[j], g), g2 = dpp_row_shr<2>(h2[j], g), g3 = dpp_row_shr<3>(h3[j], g);
	ds_read_b128 v[78:81], v238 offset:4112
	ds_read_b128 v[82:85], v238 offset:3088
	ds_read_b128 v[86:89], v238 offset:2064
	v_cndmask_b32_e64 v77, v76, 0, s[8:9]
	ds_read_b128 v[90:93], v238 offset:1040
	s_nop 0
	ds_read_b128 v[94:97], v238 offset:16
	v_cndmask_b32_e64 v76, v75, 0, s[8:9]
	v_cndmask_b32_e64 v75, 0, v74, s[6:7]
	v_cndmask_b32_e64 v74, 0, v73, s[6:7]
	v_cndmask_b32_e64 v73, 0, v72, s[4:5]
	v_cndmask_b32_e64 v72, 0, v71, s[4:5]
	v_cndmask_b32_e64 v63, 0, v63, s[6:7]
	v_cndmask_b32_e64 v62, 0, v62, s[6:7]
	v_cndmask_b32_e64 v61, 0, v61, s[4:5]
	v_cndmask_b32_e64 v60, 0, v60, s[4:5]
	s_waitcnt lgkmcnt(0)
	v_pk_fma_f32 v[56:57], v[56:57], v[82:83], v[78:79]
	v_pk_fma_f32 v[58:59], v[58:59], v[84:85], v[80:81]
	v_pk_fma_f32 v[56:57], v[76:77], v[86:87], v[56:57]
	s_nop 0
	v_pk_fma_f32 v[56:57], v[74:75], v[90:91], v[56:57]
	s_nop 0
	v_pk_fma_f32 v[56:57], v[72:73], v[94:95], v[56:57]
	s_nop 0
	v_mul_f32_e32 v71, 0xbfb8aa3b, v57
	v_exp_f32_e32 v71, v71
	s_nop 0
	v_add_f32_e32 v71, 1.0, v71
	v_rcp_f32_e32 v73, v71
	v_mul_f32_e32 v71, 0xbfb8aa3b, v56
	v_exp_f32_e32 v71, v71
	s_nop 0
	v_add_f32_e32 v71, 1.0, v71
	v_rcp_f32_e32 v72, v71
	v_cndmask_b32_e64 v71, v70, 0, s[8:9]
	v_cndmask_b32_e64 v70, v69, 0, s[8:9]
	v_pk_fma_f32 v[58:59], v[70:71], v[88:89], v[58:59]
	v_pk_mul_f32 v[56:57], v[56:57], v[72:73]
	v_pk_fma_f32 v[58:59], v[62:63], v[92:93], v[58:59]
	v_cvt_pk_bf16_f32 v206, v56, v57
	v_pk_fma_f32 v[58:59], v[60:61], v[96:97], v[58:59]
	s_nop 0
	v_mul_f32_e32 v57, 0xbfb8aa3b, v59
	v_exp_f32_e32 v57, v57
	s_nop 0
	v_add_f32_e32 v57, 1.0, v57
	v_rcp_f32_e32 v61, v57
	v_mul_f32_e32 v57, 0xbfb8aa3b, v58
	v_exp_f32_e32 v57, v57
	s_nop 0
	v_add_f32_e32 v57, 1.0, v57
	v_rcp_f32_e32 v60, v57
	s_nop 0
	v_pk_mul_f32 v[58:59], v[58:59], v[60:61]
	s_nop 0
	v_cvt_pk_bf16_f32 v207, v58, v59
	global_store_dwordx4 v[64:65], v[204:207], off
.LBB0_219:
	s_or_b64 exec, exec, s[22:23]
	ds_read_b64 v[56:57], v66 offset:1280
	ds_read_b64 v[58:59], v67 offset:768
	ds_read_b64 v[74:75], v68 offset:256
	s_waitcnt lgkmcnt(0)
	v_lshlrev_b32_e32 v71, 16, v56
	v_and_b32_e32 v72, 0xffff0000, v56
	v_lshlrev_b32_e32 v60, 16, v57
	v_and_b32_e32 v61, 0xffff0000, v57
	v_lshlrev_b32_e32 v69, 16, v58
	v_and_b32_e32 v70, 0xffff0000, v58
	v_lshlrev_b32_e32 v58, 16, v59
	v_and_b32_e32 v59, 0xffff0000, v59
	v_lshlrev_b32_e32 v62, 16, v74
	v_and_b32_e32 v63, 0xffff0000, v74
	v_lshlrev_b32_e32 v56, 16, v75
	v_and_b32_e32 v57, 0xffff0000, v75
	v_mov_b32_dpp v71, v52 row_shr:1 row_mask:0xf bank_mask:0xf
	v_mov_b32_dpp v69, v52 row_shr:2 row_mask:0xf bank_mask:0xf
	v_mov_b32_dpp v62, v52 row_shr:3 row_mask:0xf bank_mask:0xf
	v_mov_b32_dpp v72, v53 row_shr:1 row_mask:0xf bank_mask:0xf
	v_mov_b32_dpp v70, v53 row_shr:2 row_mask:0xf bank_mask:0xf
	v_mov_b32_dpp v63, v53 row_shr:3 row_mask:0xf bank_mask:0xf
	v_mov_b32_dpp v60, v54 row_shr:1 row_mask:0xf bank_mask:0xf
	v_mov_b32_dpp v58, v54 row_shr:2 row_mask:0xf bank_mask:0xf
	v_mov_b32_dpp v56, v54 row_shr:3 row_mask:0xf bank_mask:0xf
	v_mov_b32_dpp v61, v55 row_shr:1 row_mask:0xf bank_mask:0xf
	v_mov_b32_dpp v59, v55 row_shr:2 row_mask:0xf bank_mask:0xf
	v_mov_b32_dpp v57, v55 row_shr:3 row_mask:0xf bank_mask:0xf
	s_and_saveexec_b64 s[22:23], s[2:3]
	s_cbranch_execz .LBB0_221
	ds_read_b128 v[74:77], v238 offset:4608
	ds_read_b128 v[78:81], v238 offset:3584
	ds_read_b128 v[82:85], v238 offset:2560
	v_cndmask_b32_e64 v73, v72, 0, s[8:9]
	ds_read_b128 v[86:89], v238 offset:1536
	s_nop 0
	ds_read_b128 v[90:93], v238 offset:512
	v_cndmask_b32_e64 v72, v71, 0, s[8:9]
	v_cndmask_b32_e64 v71, 0, v70, s[6:7]
	v_cndmask_b32_e64 v70, 0, v69, s[6:7]
	v_cndmask_b32_e64 v63, 0, v63, s[4:5]
	v_cndmask_b32_e64 v62, 0, v62, s[4:5]
	v_cndmask_b32_e64 v61, v61, 0, s[8:9]
	v_cndmask_b32_e64 v60, v60, 0, s[8:9]
	v_cndmask_b32_e64 v59, 0, v59, s[6:7]
	v_cndmask_b32_e64 v58, 0, v58, s[6:7]
	v_cndmask_b32_e64 v57, 0, v57, s[4:5]
	v_cndmask_b32_e64 v56, 0, v56, s[4:5]
	s_waitcnt lgkmcnt(0)
	v_pk_fma_f32 v[52:53], v[52:53], v[78:79], v[74:75]
	v_pk_fma_f32 v[54:55], v[54:55], v[80:81], v[76:77]
	v_pk_fma_f32 v[52:53], v[72:73], v[82:83], v[52:53]
	v_pk_fma_f32 v[54:55], v[60:61], v[84:85], v[54:55]
	v_pk_fma_f32 v[52:53], v[70:71], v[86:87], v[52:53]
	s_nop 0
	v_pk_fma_f32 v[52:53], v[62:63], v[90:91], v[52:53]
	v_pk_fma_f32 v[54:55], v[58:59], v[88:89], v[54:55]
	v_mul_f32_e32 v62, 0xbfb8aa3b, v53
	v_exp_f32_e32 v62, v62
	v_pk_fma_f32 v[54:55], v[56:57], v[92:93], v[54:55]
	v_add_f32_e32 v62, 1.0, v62
	v_rcp_f32_e32 v63, v62
	v_mul_f32_e32 v62, 0xbfb8aa3b, v52
	v_exp_f32_e32 v62, v62
	s_nop 0
	v_add_f32_e32 v62, 1.0, v62
	v_rcp_f32_e32 v62, v62
	s_nop 0
	v_pk_mul_f32 v[52:53], v[52:53], v[62:63]
	s_nop 0
	v_cvt_pk_bf16_f32 v204, v52, v53
	v_mul_f32_e32 v53, 0xbfb8aa3b, v55
	v_exp_f32_e32 v53, v53
	s_nop 0
	v_add_f32_e32 v53, 1.0, v53
	v_rcp_f32_e32 v57, v53
	v_mul_f32_e32 v53, 0xbfb8aa3b, v54
	v_exp_f32_e32 v53, v53
	s_nop 0
	v_add_f32_e32 v53, 1.0, v53
	v_rcp_f32_e32 v56, v53
	s_nop 0
	v_pk_mul_f32 v[54:55], v[54:55], v[56:57]
	s_nop 0
	v_cvt_pk_bf16_f32 v205, v54, v55
;     __device__ __forceinline__ void operator()(const f32x4 (&acc)[2][2][4][2], const Unit& u, int wr, int wc, int fr, int fq, LAS unsigned char* hb) const {
;     ...
;             for (int m = 0; m < 4; ++m) { asm volatile("" ::: "memory"); __builtin_amdgcn_sched_barrier(0);
;                 const int q = 8 * ai + 4 * wr + m, prev = q > 0 ? q - 1 : 0; const int lr = ai * HALF + wr * 64 + m * 16 + fr, R = R0 + lr;
;                 const int Rc = R < 0 ? 0 : R; const int b = Rc / LL, p = Rc - b * LL;
;                 const bool ok = (lr >= H && R < TT);
;                 const unsigned ooff = ((unsigned)Rc * (unsigned)LDP + (unsigned)(OFF_XBC + ch0)) * 2u;
; #pragma unroll
;                 for (int bn = 0; bn < 4; ++bn) { const int bj = bn >> 1, n = bn & 1; const int co = bj * HALF + 4 * n;
;                     const unsigned woff = (unsigned)(ch0 + co) * 4u;
;                     const f32x4 w0 = *(const f32x4*)((const char*)cw + woff), w1 = *(const f32x4*)((const char*)cw + woff + XBCW * 4), w2 = *(const f32x4*)((const char*)cw + woff + 2 * XBCW * 4), w3 = *(const f32x4*)((const char*)cw + woff + 3 * XBCW * 4), bs = *(const f32x4*)((const char*)cb + woff);
;                     const LAS unsigned char* hp = hb + (prev * H * NCH + chl + co) * 2;
;                     const u32x2 q1 = *(const LAS u32x2*)(hp + hr1 * NCH * 2), q2 = *(const LAS u32x2*)(hp + hr2 * NCH * 2), q3 = *(const LAS u32x2*)(hp + hr3 * NCH * 2);
;                     const float h1[4] = {__builtin_bit_cast(float, q1.x << 16), __builtin_bit_cast(float, q1.x & 0xffff0000u), __builtin_bit_cast(float, q1.y << 16), __builtin_bit_cast(float, q1.y & 0xffff0000u)};
;                     const float h2[4] = {__builtin_bit_cast(float, q2.x << 16), __builtin_bit_cast(float, q2.x & 0xffff0000u), __builtin_bit_cast(float, q2.y << 16), __builtin_bit_cast(float, q2.y & 0xffff0000u)};
;                     const float h3[4] = {__builtin_bit_cast(float, q3.x << 16), __builtin_bit_cast(float, q3.x & 0xffff0000u), __builtin_bit_cast(float, q3.y << 16), __builtin_bit_cast(float, q3.y & 0xffff0000u)};
;                     const f32x4 gv = acc[ai][bj][m][n];
;                     float o[4];
; #pragma unroll
;                     for (int j = 0; j < 4; ++j) { const float g = gv[j];
;                         float g1 = dpp_row_shr<1>(h1[j], g), g2 = dpp_row_shr<2>(h2[j], g), g3 = dpp_row_shr<3>(h3[j], g);
.LBB0_221:
	s_or_b64 exec, exec, s[22:23]
	ds_read_b64 v[52:53], v66 offset:1288
	ds_read_b64 v[54:55], v67 offset:776
	ds_read_b64 v[66:67], v68 offset:264
	s_waitcnt lgkmcnt(0)
	v_lshlrev_b32_e32 v62, 16, v52
	v_and_b32_e32 v63, 0xffff0000, v52
	v_lshlrev_b32_e32 v56, 16, v53
	v_and_b32_e32 v57, 0xffff0000, v53
	v_lshlrev_b32_e32 v60, 16, v54
	v_and_b32_e32 v61, 0xffff0000, v54
	v_lshlrev_b32_e32 v54, 16, v55
	v_and_b32_e32 v55, 0xffff0000, v55
	v_lshlrev_b32_e32 v58, 16, v66
	v_and_b32_e32 v59, 0xffff0000, v66
	v_lshlrev_b32_e32 v52, 16, v67
	v_and_b32_e32 v53, 0xffff0000, v67
	v_mov_b32_dpp v62, v48 row_shr:1 row_mask:0xf bank_mask:0xf
	v_mov_b32_dpp v60, v48 row_shr:2 row_mask:0xf bank_mask:0xf
	v_mov_b32_dpp v58, v48 row_shr:3 row_mask:0xf bank_mask:0xf
	v_mov_b32_dpp v63, v49 row_shr:1 row_mask:0xf bank_mask:0xf
	v_mov_b32_dpp v61, v49 row_shr:2 row_mask:0xf bank_mask:0xf
	v_mov_b32_dpp v59, v49 row_shr:3 row_mask:0xf bank_mask:0xf
	v_mov_b32_dpp v56, v50 row_shr:1 row_mask:0xf bank_mask:0xf
	v_mov_b32_dpp v54, v50 row_shr:2 row_mask:0xf bank_mask:0xf
	v_mov_b32_dpp v52, v50 row_shr:3 row_mask:0xf bank_mask:0xf
	v_mov_b32_dpp v57, v51 row_shr:1 row_mask:0xf bank_mask:0xf
	v_mov_b32_dpp v55, v51 row_shr:2 row_mask:0xf bank_mask:0xf
	v_mov_b32_dpp v53, v51 row_shr:3 row_mask:0xf bank_mask:0xf
	s_and_saveexec_b64 s[22:23], s[2:3]
	s_cbranch_execz .LBB0_223
	ds_read_b128 v[66:69], v238 offset:4624
	ds_read_b128 v[70:73], v238 offset:3600
	ds_read_b128 v[74:77], v238 offset:2576
	v_cndmask_b32_e64 v63, v63, 0, s[8:9]
	ds_read_b128 v[78:81], v238 offset:1552
	s_nop 0
	ds_read_b128 v[82:85], v238 offset:528
	v_cndmask_b32_e64 v62, v62, 0, s[8:9]
	v_cndmask_b32_e64 v61, 0, v61, s[6:7]
	v_cndmask_b32_e64 v60, 0, v60, s[6:7]
	v_cndmask_b32_e64 v59, 0, v59, s[4:5]
	v_cndmask_b32_e64 v58, 0, v58, s[4:5]
	v_cndmask_b32_e64 v57, v57, 0, s[8:9]
	v_cndmask_b32_e64 v56, v56, 0, s[8:9]
	v_cndmask_b32_e64 v55, 0, v55, s[6:7]
	v_cndmask_b32_e64 v54, 0, v54, s[6:7]
	v_cndmask_b32_e64 v53, 0, v53, s[4:5]
	v_cndmask_b32_e64 v52, 0, v52, s[4:5]
	s_waitcnt lgkmcnt(0)
	v_pk_fma_f32 v[48:49], v[48:49], v[70:71], v[66:67]
	v_pk_fma_f32 v[50:51], v[50:51], v[72:73], v[68:69]
	v_pk_fma_f32 v[48:49], v[62:63], v[74:75], v[48:49]
	v_pk_fma_f32 v[50:51], v[56:57], v[76:77], v[50:51]
	v_pk_fma_f32 v[48:49], v[60:61], v[78:79], v[48:49]
	s_nop 0
	v_pk_fma_f32 v[48:49], v[58:59], v[82:83], v[48:49]
	v_pk_fma_f32 v[50:51], v[54:55], v[80:81], v[50:51]
	v_mul_f32_e32 v58, 0xbfb8aa3b, v49
	v_exp_f32_e32 v58, v58
	v_pk_fma_f32 v[50:51], v[52:53], v[84:85], v[50:51]
	v_add_f32_e32 v58, 1.0, v58
	v_rcp_f32_e32 v59, v58
	v_mul_f32_e32 v58, 0xbfb8aa3b, v48
	v_exp_f32_e32 v58, v58
	s_nop 0
	v_add_f32_e32 v58, 1.0, v58
	v_rcp_f32_e32 v58, v58
	s_nop 0
	v_pk_mul_f32 v[48:49], v[48:49], v[58:59]
	s_nop 0
	v_cvt_pk_bf16_f32 v206, v48, v49
	v_mul_f32_e32 v49, 0xbfb8aa3b, v51
	v_exp_f32_e32 v49, v49
	s_nop 0
	v_add_f32_e32 v49, 1.0, v49
	v_rcp_f32_e32 v53, v49
	v_mul_f32_e32 v49, 0xbfb8aa3b, v50
	v_exp_f32_e32 v49, v49
	s_nop 0
	v_add_f32_e32 v49, 1.0, v49
	v_rcp_f32_e32 v52, v49
	s_nop 0
	v_pk_mul_f32 v[50:51], v[50:51], v[52:53]
	s_nop 0
	v_cvt_pk_bf16_f32 v207, v50, v51
	global_store_dwordx4 v[64:65], v[204:207], off offset:256
.LBB0_223:
	s_or_b64 exec, exec, s[22:23]
	v_add_u32_e32 v48, 0x90, v161
	v_add_u32_e32 v49, s17, v48
	v_max_i32_e32 v50, 0, v49
	v_mul_hi_u32 v51, v50, s56
	v_lshrrev_b32_e32 v51, 11, v51
	v_cmp_lt_i32_e32 vcc, 2, v48
	v_mul_lo_u32 v48, v50, s51
	v_mul_u32_u24_e32 v51, 0x1010, v51
	v_add_lshl_u32 v136, v48, v164, 1
	v_add_u32_e32 v48, s42, v165
	v_sub_u32_e32 v51, v50, v51
	v_cmp_gt_i32_e64 s[4:5], s50, v49
	v_lshl_add_u32 v50, v48, 1, s53
	s_and_b64 s[2:3], vcc, s[4:5]
	v_cmp_eq_u32_e64 s[8:9], 0, v51
	v_cmp_lt_u32_e64 s[6:7], 1, v51
	v_cmp_lt_u32_e64 s[4:5], 2, v51
	v_add_u32_e32 v51, v50, v163
	ds_read_b64 v[48:49], v50 offset:1024
	v_add_u32_e32 v52, v50, v162
	ds_read_b64 v[66:67], v51 offset:512
	ds_read_b64 v[68:69], v52
	v_readlane_b32 s22, v237, 58
	v_readlane_b32 s23, v237, 59
	s_waitcnt lgkmcnt(0)
	v_lshlrev_b32_e32 v63, 16, v48
	v_and_b32_e32 v64, 0xffff0000, v48
	v_lshlrev_b32_e32 v57, 16, v49
	v_and_b32_e32 v58, 0xffff0000, v49
	v_lshlrev_b32_e32 v61, 16, v66
	v_and_b32_e32 v62, 0xffff0000, v66
	v_lshlrev_b32_e32 v55, 16, v67
	v_and_b32_e32 v56, 0xffff0000, v67
	v_lshlrev_b32_e32 v59, 16, v68
	v_and_b32_e32 v60, 0xffff0000, v68
	v_lshlrev_b32_e32 v53, 16, v69
	v_and_b32_e32 v54, 0xffff0000, v69
	v_mov_b32_dpp v63, v44 row_shr:1 row_mask:0xf bank_mask:0xf
	v_mov_b32_dpp v61, v44 row_shr:2 row_mask:0xf bank_mask:0xf
	v_mov_b32_dpp v59, v44 row_shr:3 row_mask:0xf bank_mask:0xf
	v_mov_b32_dpp v64, v45 row_shr:1 row_mask:0xf bank_mask:0xf
	v_mov_b32_dpp v62, v45 row_shr:2 row_mask:0xf bank_mask:0xf
	v_mov_b32_dpp v60, v45 row_shr:3 row_mask:0xf bank_mask:0xf
	v_mov_b32_dpp v57, v46 row_shr:1 row_mask:0xf bank_mask:0xf
	v_mov_b32_dpp v55, v46 row_shr:2 row_mask:0xf bank_mask:0xf
	v_mov_b32_dpp v53, v46 row_shr:3 row_mask:0xf bank_mask:0xf
	v_mov_b32_dpp v58, v47 row_shr:1 row_mask:0xf bank_mask:0xf
	v_mov_b32_dpp v56, v47 row_shr:2 row_mask:0xf bank_mask:0xf
	v_mov_b32_dpp v54, v47 row_shr:3 row_mask:0xf bank_mask:0xf
	v_lshl_add_u64 v[48:49], s[22:23], 0, v[136:137]
	s_and_saveexec_b64 s[22:23], s[2:3]
	s_cbranch_execz .LBB0_225
;     __device__ __forceinline__ void operator()(const f32x4 (&acc)[2][2][4][2], const Unit& u, int wr, int wc, int fr, int fq, LAS unsigned char* hb) const {
;     ...
;                 for (int bn = 0; bn < 4; ++bn) { const int bj = bn >> 1, n = bn & 1; const int co = bj * HALF + 4 * n;
;                     const unsigned woff = (unsigned)(ch0 + co) * 4u;
;                     const f32x4 w0 = *(const f32x4*)((const char*)cw + woff), w1 = *(const f32x4*)((const char*)cw + woff + XBCW * 4), w2 = *(const f32x4*)((const char*)cw + woff + 2 * XBCW * 4), w3 = *(const f32x4*)((const char*)cw + woff + 3 * XBCW * 4), bs = *(const f32x4*)((const char*)cb + woff);
;                     const LAS unsigned char* hp = hb + (prev * H * NCH + chl + co) * 2;
;                     const u32x2 q1 = *(const LAS u32x2*)(hp + hr1 * NCH * 2), q2 = *(const LAS u32x2*)(hp + hr2 * NCH * 2), q3 = *(const LAS u32x2*)(hp + hr3 * NCH * 2);
;                     const float h1[4] = {__builtin_bit_cast(float, q1.x << 16), __builtin_bit_cast(float, q1.x & 0xffff0000u), __builtin_bit_cast(float, q1.y << 16), __builtin_bit_cast(float, q1.y & 0xffff0000u)};
;                     const float h2[4] = {__builtin_bit_cast(float, q2.x << 16), __builtin_bit_cast(float, q2.x & 0xffff0000u), __builtin_bit_cast(float, q2.y << 16), __builtin_bit_cast(float, q2.y & 0xffff0000u)};
;                     const float h3[4] = {__builtin_bit_cast(float, q3.x << 16), __builtin_bit_cast(float, q3.x & 0xffff0000u), __builtin_bit_cast(float, q3.y << 16), __builtin_bit_cast(float, q3.y & 0xffff0000u)};
;                     const f32x4 gv = acc[ai][bj][m][n];
;                     float o[4];
; #pragma unroll
;                     for (int j = 0; j < 4; ++j) { const float g = gv[j];
;                         float g1 = dpp_row_shr<1>(h1[j], g), g2 = dpp_row_shr<2>(h2[j], g), g3 = dpp_row_shr<3>(h3[j], g);
;                         g1 = p >= 1 ? g1 : 0.f; g2 = p >= 2 ? g2 : 0.f; g3 = p >= 3 ? g3 : 0.f;
;                         const float v = bs[j] + w3[j] * g + w2[j] * g1 + w1[j] * g2 + w0[j] * g3;
;                         o[j] = v * __builtin_amdgcn_rcpf(1.f + ex2(-1.4426950408889634f * v)); }
;                     if (ok) { u32x2 w; w.x = pk2e(o[0], o[1]); w.y = pk2e(o[2], o[3]); *(u32x2*)((char*)O + ooff + co * 2) = w; }
;                     asm volatile("" ::: "memory"); }
	ds_read_b128 v[66:69], v238 offset:4096
	ds_read_b128 v[70:73], v238 offset:3072
	ds_read_b128 v[74:77], v238 offset:2048
	v_cndmask_b32_e64 v65, v64, 0, s[8:9]
	ds_read_b128 v[78:81], v238 offset:1024
	s_nop 0
	ds_read_b128 v[82:85], v238
	v_cndmask_b32_e64 v64, v63, 0, s[8:9]
	v_cndmask_b32_e64 v63, 0, v62, s[6:7]
	v_cndmask_b32_e64 v62, 0, v61, s[6:7]
	v_cndmask_b32_e64 v61, 0, v60, s[4:5]
	v_cndmask_b32_e64 v60, 0, v59, s[4:5]
	s_waitcnt lgkmcnt(0)
	v_pk_fma_f32 v[44:45], v[44:45], v[70:71], v[66:67]
	v_pk_fma_f32 v[46:47], v[46:47], v[72:73], v[68:69]
	v_pk_fma_f32 v[44:45], v[64:65], v[74:75], v[44:45]
	s_nop 0
	v_pk_fma_f32 v[44:45], v[62:63], v[78:79], v[44:45]
	s_nop 0
	v_pk_fma_f32 v[44:45], v[60:61], v[82:83], v[44:45]
	s_nop 0
	v_mul_f32_e32 v59, 0xbfb8aa3b, v45
	v_exp_f32_e32 v59, v59
	s_nop 0
	v_add_f32_e32 v59, 1.0, v59
	v_rcp_f32_e32 v61, v59
	v_mul_f32_e32 v59, 0xbfb8aa3b, v44
	v_exp_f32_e32 v59, v59
	s_nop 0
	v_add_f32_e32 v59, 1.0, v59
	v_rcp_f32_e32 v60, v59
	v_cndmask_b32_e64 v59, v58, 0, s[8:9]
	v_cndmask_b32_e64 v58, v57, 0, s[8:9]
	v_pk_fma_f32 v[46:47], v[58:59], v[76:77], v[46:47]
	v_cndmask_b32_e64 v57, 0, v56, s[6:7]
	v_cndmask_b32_e64 v56, 0, v55, s[6:7]
	v_pk_fma_f32 v[46:47], v[56:57], v[80:81], v[46:47]
	v_cndmask_b32_e64 v55, 0, v54, s[4:5]
	v_cndmask_b32_e64 v54, 0, v53, s[4:5]
	v_pk_mul_f32 v[44:45], v[44:45], v[60:61]
	v_pk_fma_f32 v[46:47], v[54:55], v[84:85], v[46:47]
	v_cvt_pk_bf16_f32 v204, v44, v45
	v_mul_f32_e32 v45, 0xbfb8aa3b, v47
	v_exp_f32_e32 v45, v45
	s_nop 0
	v_add_f32_e32 v45, 1.0, v45
	v_rcp_f32_e32 v55, v45
	v_mul_f32_e32 v45, 0xbfb8aa3b, v46
	v_exp_f32_e32 v45, v45
	s_nop 0
	v_add_f32_e32 v45, 1.0, v45
	v_rcp_f32_e32 v54, v45
	s_nop 0
	v_pk_mul_f32 v[46:47], v[46:47], v[54:55]
	s_nop 0
	v_cvt_pk_bf16_f32 v205, v46, v47
.LBB0_225:
	s_or_b64 exec, exec, s[22:23]
	ds_read_b64 v[44:45], v50 offset:1032
	ds_read_b64 v[46:47], v51 offset:520
	ds_read_b64 v[62:63], v52 offset:8
	s_waitcnt lgkmcnt(0)
	v_lshlrev_b32_e32 v59, 16, v44
	v_and_b32_e32 v60, 0xffff0000, v44
	v_lshlrev_b32_e32 v53, 16, v45
	v_and_b32_e32 v54, 0xffff0000, v45
	v_lshlrev_b32_e32 v57, 16, v46
	v_and_b32_e32 v58, 0xffff0000, v46
	v_lshlrev_b32_e32 v46, 16, v47
	v_and_b32_e32 v47, 0xffff0000, v47
	v_lshlrev_b32_e32 v55, 16, v62
	v_and_b32_e32 v56, 0xffff0000, v62
	v_lshlrev_b32_e32 v44, 16, v63
	v_and_b32_e32 v45, 0xffff0000, v63
	v_mov_b32_dpp v59, v40 row_shr:1 row_mask:0xf bank_mask:0xf
	v_mov_b32_dpp v57, v40 row_shr:2 row_mask:0xf bank_mask:0xf
	v_mov_b32_dpp v55, v40 row_shr:3 row_mask:0xf bank_mask:0xf
	v_mov_b32_dpp v60, v41 row_shr:1 row_mask:0xf bank_mask:0xf
	v_mov_b32_dpp v58, v41 row_shr:2 row_mask:0xf bank_mask:0xf
	v_mov_b32_dpp v56, v41 row_shr:3 row_mask:0xf bank_mask:0xf
	v_mov_b32_dpp v53, v42 row_shr:1 row_mask:0xf bank_mask:0xf
	v_mov_b32_dpp v46, v42 row_shr:2 row_mask:0xf bank_mask:0xf
	v_mov_b32_dpp v44, v42 row_shr:3 row_mask:0xf bank_mask:0xf
	v_mov_b32_dpp v54, v43 row_shr:1 row_mask:0xf bank_mask:0xf
	v_mov_b32_dpp v47, v43 row_shr:2 row_mask:0xf bank_mask:0xf
	v_mov_b32_dpp v45, v43 row_shr:3 row_mask:0xf bank_mask:0xf
	s_and_saveexec_b64 s[22:23], s[2:3]
	s_cbranch_execz .LBB0_227
	ds_read_b128 v[62:65], v238 offset:4112
	ds_read_b128 v[66:69], v238 offset:3088
	ds_read_b128 v[70:73], v238 offset:2064
	v_cndmask_b32_e64 v61, v60, 0, s[8:9]
	ds_read_b128 v[74:77], v238 offset:1040
	s_nop 0
	ds_read_b128 v[78:81], v238 offset:16
	v_cndmask_b32_e64 v60, v59, 0, s[8:9]
	v_cndmask_b32_e64 v59, 0, v58, s[6:7]
	v_cndmask_b32_e64 v58, 0, v57, s[6:7]
	v_cndmask_b32_e64 v57, 0, v56, s[4:5]
	v_cndmask_b32_e64 v56, 0, v55, s[4:5]
	v_cndmask_b32_e64 v47, 0, v47, s[6:7]
	v_cndmask_b32_e64 v46, 0, v46, s[6:7]
	v_cndmask_b32_e64 v45, 0, v45, s[4:5]
	v_cndmask_b32_e64 v44, 0, v44, s[4:5]
	s_waitcnt lgkmcnt(0)
	v_pk_fma_f32 v[40:41], v[40:41], v[66:67], v[62:63]
	v_pk_fma_f32 v[42:43], v[42:43], v[68:69], v[64:65]
	v_pk_fma_f32 v[40:41], v[60:61], v[70:71], v[40:41]
	s_nop 0
	v_pk_fma_f32 v[40:41], v[58:59], v[74:75], v[40:41]
	s_nop 0
	v_pk_fma_f32 v[40:41], v[56:57], v[78:79], v[40:41]
	s_nop 0
	v_mul_f32_e32 v55, 0xbfb8aa3b, v41
	v_exp_f32_e32 v55, v55
	s_nop 0
	v_add_f32_e32 v55, 1.0, v55
	v_rcp_f32_e32 v57, v55
	v_mul_f32_e32 v55, 0xbfb8aa3b, v40
	v_exp_f32_e32 v55, v55
	s_nop 0
	v_add_f32_e32 v55, 1.0, v55
	v_rcp_f32_e32 v56, v55
	v_cndmask_b32_e64 v55, v54, 0, s[8:9]
	v_cndmask_b32_e64 v54, v53, 0, s[8:9]
	v_pk_fma_f32 v[42:43], v[54:55], v[72:73], v[42:43]
	v_pk_mul_f32 v[40:41], v[40:41], v[56:57]
	v_pk_fma_f32 v[42:43], v[46:47], v[76:77], v[42:43]
	v_cvt_pk_bf16_f32 v206, v40, v41
	v_pk_fma_f32 v[42:43], v[44:45], v[80:81], v[42:43]
	s_nop 0
	v_mul_f32_e32 v41, 0xbfb8aa3b, v43
	v_exp_f32_e32 v41, v41
	s_nop 0
	v_add_f32_e32 v41, 1.0, v41
	v_rcp_f32_e32 v45, v41
	v_mul_f32_e32 v41, 0xbfb8aa3b, v42
	v_exp_f32_e32 v41, v41
	s_nop 0
	v_add_f32_e32 v41, 1.0, v41
	v_rcp_f32_e32 v44, v41
	s_nop 0
	v_pk_mul_f32 v[42:43], v[42:43], v[44:45]
	s_nop 0
	v_cvt_pk_bf16_f32 v207, v42, v43
	global_store_dwordx4 v[48:49], v[204:207], off
;     __device__ __forceinline__ void operator()(const f32x4 (&acc)[2][2][4][2], const Unit& u, int wr, int wc, int fr, int fq, LAS unsigned char* hb) const {
;     ...
;                 for (int bn = 0; bn < 4; ++bn) { const int bj = bn >> 1, n = bn & 1; const int co = bj * HALF + 4 * n;
;                     const unsigned woff = (unsigned)(ch0 + co) * 4u;
;                     const f32x4 w0 = *(const f32x4*)((const char*)cw + woff), w1 = *(const f32x4*)((const char*)cw + woff + XBCW * 4), w2 = *(const f32x4*)((const char*)cw + woff + 2 * XBCW * 4), w3 = *(const f32x4*)((const char*)cw + woff + 3 * XBCW * 4), bs = *(const f32x4*)((const char*)cb + woff);
;                     const LAS unsigned char* hp = hb + (prev * H * NCH + chl + co) * 2;
;                     const u32x2 q1 = *(const LAS u32x2*)(hp + hr1 * NCH * 2), q2 = *(const LAS u32x2*)(hp + hr2 * NCH * 2), q3 = *(const LAS u32x2*)(hp + hr3 * NCH * 2);
;                     const float h1[4] = {__builtin_bit_cast(float, q1.x << 16), __builtin_bit_cast(float, q1.x & 0xffff0000u), __builtin_bit_cast(float, q1.y << 16), __builtin_bit_cast(float, q1.y & 0xffff0000u)};
;                     const float h2[4] = {__builtin_bit_cast(float, q2.x << 16), __builtin_bit_cast(float, q2.x & 0xffff0000u), __builtin_bit_cast(float, q2.y << 16), __builtin_bit_cast(float, q2.y & 0xffff0000u)};
;                     const float h3[4] = {__builtin_bit_cast(float, q3.x << 16), __builtin_bit_cast(float, q3.x & 0xffff0000u), __builtin_bit_cast(float, q3.y << 16), __builtin_bit_cast(float, q3.y & 0xffff0000u)};
;                     const f32x4 gv = acc[ai][bj][m][n];
;                     float o[4];
; #pragma unroll
;                     for (int j = 0; j < 4; ++j) { const float g = gv[j];
;                         float g1 = dpp_row_shr<1>(h1[j], g), g2 = dpp_row_shr<2>(h2[j], g), g3 = dpp_row_shr<3>(h3[j], g);
;                         g1 = p >= 1 ? g1 : 0.f; g2 = p >= 2 ? g2 : 0.f; g3 = p >= 3 ? g3 : 0.f;
;                         const float v = bs[j] + w3[j] * g + w2[j] * g1 + w1[j] * g2 + w0[j] * g3;
;                         o[j] = v * __builtin_amdgcn_rcpf(1.f + ex2(-1.4426950408889634f * v)); }
;                     if (ok) { u32x2 w; w.x = pk2e(o[0], o[1]); w.y = pk2e(o[2], o[3]); *(u32x2*)((char*)O + ooff + co * 2) = w; }
;                     asm volatile("" ::: "memory"); }
.LBB0_227:
	s_or_b64 exec, exec, s[22:23]
	ds_read_b64 v[40:41], v50 offset:1280
	ds_read_b64 v[42:43], v51 offset:768
	ds_read_b64 v[58:59], v52 offset:256
	s_waitcnt lgkmcnt(0)
	v_lshlrev_b32_e32 v55, 16, v40
	v_and_b32_e32 v56, 0xffff0000, v40
	v_lshlrev_b32_e32 v44, 16, v41
	v_and_b32_e32 v45, 0xffff0000, v41
	v_lshlrev_b32_e32 v53, 16, v42
	v_and_b32_e32 v54, 0xffff0000, v42
	v_lshlrev_b32_e32 v42, 16, v43
	v_and_b32_e32 v43, 0xffff0000, v43
	v_lshlrev_b32_e32 v46, 16, v58
	v_and_b32_e32 v47, 0xffff0000, v58
	v_lshlrev_b32_e32 v40, 16, v59
	v_and_b32_e32 v41, 0xffff0000, v59
	v_mov_b32_dpp v55, v36 row_shr:1 row_mask:0xf bank_mask:0xf
	v_mov_b32_dpp v53, v36 row_shr:2 row_mask:0xf bank_mask:0xf
	v_mov_b32_dpp v46, v36 row_shr:3 row_mask:0xf bank_mask:0xf
	v_mov_b32_dpp v56, v37 row_shr:1 row_mask:0xf bank_mask:0xf
	v_mov_b32_dpp v54, v37 row_shr:2 row_mask:0xf bank_mask:0xf
	v_mov_b32_dpp v47, v37 row_shr:3 row_mask:0xf bank_mask:0xf
	v_mov_b32_dpp v44, v38 row_shr:1 row_mask:0xf bank_mask:0xf
	v_mov_b32_dpp v42, v38 row_shr:2 row_mask:0xf bank_mask:0xf
	v_mov_b32_dpp v40, v38 row_shr:3 row_mask:0xf bank_mask:0xf
	v_mov_b32_dpp v45, v39 row_shr:1 row_mask:0xf bank_mask:0xf
	v_mov_b32_dpp v43, v39 row_shr:2 row_mask:0xf bank_mask:0xf
	v_mov_b32_dpp v41, v39 row_shr:3 row_mask:0xf bank_mask:0xf
	s_and_saveexec_b64 s[22:23], s[2:3]
	s_cbranch_execz .LBB0_229
	ds_read_b128 v[58:61], v238 offset:4608
	ds_read_b128 v[62:65], v238 offset:3584
	ds_read_b128 v[66:69], v238 offset:2560
	v_cndmask_b32_e64 v57, v56, 0, s[8:9]
	ds_read_b128 v[70:73], v238 offset:1536
	s_nop 0
	ds_read_b128 v[74:77], v238 offset:512
	v_cndmask_b32_e64 v56, v55, 0, s[8:9]
	v_cndmask_b32_e64 v55, 0, v54, s[6:7]
	v_cndmask_b32_e64 v54, 0, v53, s[6:7]
	v_cndmask_b32_e64 v47, 0, v47, s[4:5]
	v_cndmask_b32_e64 v46, 0, v46, s[4:5]
	v_cndmask_b32_e64 v45, v45, 0, s[8:9]
	v_cndmask_b32_e64 v44, v44, 0, s[8:9]
	v_cndmask_b32_e64 v43, 0, v43, s[6:7]
	v_cndmask_b32_e64 v42, 0, v42, s[6:7]
	v_cndmask_b32_e64 v41, 0, v41, s[4:5]
	v_cndmask_b32_e64 v40, 0, v40, s[4:5]
	s_waitcnt lgkmcnt(0)
	v_pk_fma_f32 v[36:37], v[36:37], v[62:63], v[58:59]
	v_pk_fma_f32 v[38:39], v[38:39], v[64:65], v[60:61]
	v_pk_fma_f32 v[36:37], v[56:57], v[66:67], v[36:37]
	v_pk_fma_f32 v[38:39], v[44:45], v[68:69], v[38:39]
	v_pk_fma_f32 v[36:37], v[54:55], v[70:71], v[36:37]
	s_nop 0
	v_pk_fma_f32 v[36:37], v[46:47], v[74:75], v[36:37]
	v_pk_fma_f32 v[38:39], v[42:43], v[72:73], v[38:39]
	v_mul_f32_e32 v46, 0xbfb8aa3b, v37
	v_exp_f32_e32 v46, v46
	v_pk_fma_f32 v[38:39], v[40:41], v[76:77], v[38:39]
	v_add_f32_e32 v46, 1.0, v46
	v_rcp_f32_e32 v47, v46
	v_mul_f32_e32 v46, 0xbfb8aa3b, v36
	v_exp_f32_e32 v46, v46
	s_nop 0
	v_add_f32_e32 v46, 1.0, v46
	v_rcp_f32_e32 v46, v46
	s_nop 0
	v_pk_mul_f32 v[36:37], v[36:37], v[46:47]
	s_nop 0
	v_cvt_pk_bf16_f32 v204, v36, v37
	v_mul_f32_e32 v37, 0xbfb8aa3b, v39
	v_exp_f32_e32 v37, v37
	s_nop 0
	v_add_f32_e32 v37, 1.0, v37
	v_rcp_f32_e32 v41, v37
	v_mul_f32_e32 v37, 0xbfb8aa3b, v38
	v_exp_f32_e32 v37, v37
	s_nop 0
	v_add_f32_e32 v37, 1.0, v37
	v_rcp_f32_e32 v40, v37
	s_nop 0
	v_pk_mul_f32 v[38:39], v[38:39], v[40:41]
	s_nop 0
	v_cvt_pk_bf16_f32 v205, v38, v39
.LBB0_229:
	s_or_b64 exec, exec, s[22:23]
	ds_read_b64 v[36:37], v50 offset:1288
	ds_read_b64 v[38:39], v51 offset:776
	ds_read_b64 v[50:51], v52 offset:264
	s_waitcnt lgkmcnt(0)
	v_lshlrev_b32_e32 v46, 16, v36
	v_and_b32_e32 v47, 0xffff0000, v36
	v_lshlrev_b32_e32 v40, 16, v37
	v_and_b32_e32 v41, 0xffff0000, v37
	v_lshlrev_b32_e32 v44, 16, v38
	v_and_b32_e32 v45, 0xffff0000, v38
	v_lshlrev_b32_e32 v38, 16, v39
	v_and_b32_e32 v39, 0xffff0000, v39
	v_lshlrev_b32_e32 v42, 16, v50
	v_and_b32_e32 v43, 0xffff0000, v50
	v_lshlrev_b32_e32 v36, 16, v51
	v_and_b32_e32 v37, 0xffff0000, v51
	v_mov_b32_dpp v46, v32 row_shr:1 row_mask:0xf bank_mask:0xf
	v_mov_b32_dpp v44, v32 row_shr:2 row_mask:0xf bank_mask:0xf
	v_mov_b32_dpp v42, v32 row_shr:3 row_mask:0xf bank_mask:0xf
	v_mov_b32_dpp v47, v33 row_shr:1 row_mask:0xf bank_mask:0xf
	v_mov_b32_dpp v45, v33 row_shr:2 row_mask:0xf bank_mask:0xf
	v_mov_b32_dpp v43, v33 row_shr:3 row_mask:0xf bank_mask:0xf
	v_mov_b32_dpp v40, v34 row_shr:1 row_mask:0xf bank_mask:0xf
	v_mov_b32_dpp v38, v34 row_shr:2 row_mask:0xf bank_mask:0xf
	v_mov_b32_dpp v36, v34 row_shr:3 row_mask:0xf bank_mask:0xf
	v_mov_b32_dpp v41, v35 row_shr:1 row_mask:0xf bank_mask:0xf
	v_mov_b32_dpp v39, v35 row_shr:2 row_mask:0xf bank_mask:0xf
	v_mov_b32_dpp v37, v35 row_shr:3 row_mask:0xf bank_mask:0xf
	s_and_saveexec_b64 s[22:23], s[2:3]
	s_cbranch_execz .LBB0_231
	ds_read_b128 v[50:53], v238 offset:4624
	ds_read_b128 v[54:57], v238 offset:3600
	ds_read_b128 v[58:61], v238 offset:2576
	v_cndmask_b32_e64 v47, v47, 0, s[8:9]
	ds_read_b128 v[62:65], v238 offset:1552
	s_nop 0
	ds_read_b128 v[66:69], v238 offset:528
	v_cndmask_b32_e64 v46, v46, 0, s[8:9]
	v_cndmask_b32_e64 v45, 0, v45, s[6:7]
	v_cndmask_b32_e64 v44, 0, v44, s[6:7]
	v_cndmask_b32_e64 v43, 0, v43, s[4:5]
	v_cndmask_b32_e64 v42, 0, v42, s[4:5]
	v_cndmask_b32_e64 v41, v41, 0, s[8:9]
	v_cndmask_b32_e64 v40, v40, 0, s[8:9]
	v_cndmask_b32_e64 v39, 0, v39, s[6:7]
	v_cndmask_b32_e64 v38, 0, v38, s[6:7]
	v_cndmask_b32_e64 v37, 0, v37, s[4:5]
	v_cndmask_b32_e64 v36, 0, v36, s[4:5]
	s_waitcnt lgkmcnt(0)
	v_pk_fma_f32 v[32:33], v[32:33], v[54:55], v[50:51]
	v_pk_fma_f32 v[34:35], v[34:35], v[56:57], v[52:53]
	v_pk_fma_f32 v[32:33], v[46:47], v[58:59], v[32:33]
	v_pk_fma_f32 v[34:35], v[40:41], v[60:61], v[34:35]
	v_pk_fma_f32 v[32:33], v[44:45], v[62:63], v[32:33]
	s_nop 0
	v_pk_fma_f32 v[32:33], v[42:43], v[66:67], v[32:33]
	v_pk_fma_f32 v[34:35], v[38:39], v[64:65], v[34:35]
	v_mul_f32_e32 v42, 0xbfb8aa3b, v33
	v_exp_f32_e32 v42, v42
	v_pk_fma_f32 v[34:35], v[36:37], v[68:69], v[34:35]
	v_add_f32_e32 v42, 1.0, v42
	v_rcp_f32_e32 v43, v42
	v_mul_f32_e32 v42, 0xbfb8aa3b, v32
	v_exp_f32_e32 v42, v42
	s_nop 0
	v_add_f32_e32 v42, 1.0, v42
	v_rcp_f32_e32 v42, v42
	s_nop 0
	v_pk_mul_f32 v[32:33], v[32:33], v[42:43]
	s_nop 0
	v_cvt_pk_bf16_f32 v206, v32, v33
	v_mul_f32_e32 v33, 0xbfb8aa3b, v35
	v_exp_f32_e32 v33, v33
	s_nop 0
	v_add_f32_e32 v33, 1.0, v33
	v_rcp_f32_e32 v37, v33
	v_mul_f32_e32 v33, 0xbfb8aa3b, v34
	v_exp_f32_e32 v33, v33
	s_nop 0
	v_add_f32_e32 v33, 1.0, v33
	v_rcp_f32_e32 v36, v33
	s_nop 0
	v_pk_mul_f32 v[34:35], v[34:35], v[36:37]
	s_nop 0
	v_cvt_pk_bf16_f32 v207, v34, v35
	global_store_dwordx4 v[48:49], v[204:207], off offset:256
;     __device__ __forceinline__ void operator()(const f32x4 (&acc)[2][2][4][2], const Unit& u, int wr, int wc, int fr, int fq, LAS unsigned char* hb) const {
;     ...
;                 const int q = 8 * ai + 4 * wr + m, prev = q > 0 ? q - 1 : 0; const int lr = ai * HALF + wr * 64 + m * 16 + fr, R = R0 + lr;
;                 const int Rc = R < 0 ? 0 : R; const int b = Rc / LL, p = Rc - b * LL;
;                 const bool ok = (lr >= H && R < TT);
;                 const unsigned ooff = ((unsigned)Rc * (unsigned)LDP + (unsigned)(OFF_XBC + ch0)) * 2u;
; #pragma unroll
;                 for (int bn = 0; bn < 4; ++bn) { const int bj = bn >> 1, n = bn & 1; const int co = bj * HALF + 4 * n;
;                     const unsigned woff = (unsigned)(ch0 + co) * 4u;
;                     const f32x4 w0 = *(const f32x4*)((const char*)cw + woff), w1 = *(const f32x4*)((const char*)cw + woff + XBCW * 4), w2 = *(const f32x4*)((const char*)cw + woff + 2 * XBCW * 4), w3 = *(const f32x4*)((const char*)cw + woff + 3 * XBCW * 4), bs = *(const f32x4*)((const char*)cb + woff);
;                     const LAS unsigned char* hp = hb + (prev * H * NCH + chl + co) * 2;
;                     const u32x2 q1 = *(const LAS u32x2*)(hp + hr1 * NCH * 2), q2 = *(const LAS u32x2*)(hp + hr2 * NCH * 2), q3 = *(const LAS u32x2*)(hp + hr3 * NCH * 2);
;                     const float h1[4] = {__builtin_bit_cast(float, q1.x << 16), __builtin_bit_cast(float, q1.x & 0xffff0000u), __builtin_bit_cast(float, q1.y << 16), __builtin_bit_cast(float, q1.y & 0xffff0000u)};
;                     const float h2[4] = {__builtin_bit_cast(float, q2.x << 16), __builtin_bit_cast(float, q2.x & 0xffff0000u), __builtin_bit_cast(float, q2.y << 16), __builtin_bit_cast(float, q2.y & 0xffff0000u)};
;                     const float h3[4] = {__builtin_bit_cast(float, q3.x << 16), __builtin_bit_cast(float, q3.x & 0xffff0000u), __builtin_bit_cast(float, q3.y << 16), __builtin_bit_cast(float, q3.y & 0xffff0000u)};
;                     const f32x4 gv = acc[ai][bj][m][n];
;                     float o[4];
; #pragma unroll
;                     for (int j = 0; j < 4; ++j) { const float g = gv[j];
;                         float g1 = dpp_row_shr<1>(h1[j], g), g2 = dpp_row_shr<2>(h2[j], g), g3 = dpp_row_shr<3>(h3[j], g);
;                         g1 = p >= 1 ? g1 : 0.f; g2 = p >= 2 ? g2 : 0.f; g3 = p >= 3 ? g3 : 0.f;
.LBB0_231:
	s_or_b64 exec, exec, s[22:23]
	v_add_u32_e32 v32, 0xa0, v161
	v_add_u32_e32 v33, s17, v32
	v_max_i32_e32 v34, 0, v33
	v_mul_hi_u32 v35, v34, s56
	v_lshrrev_b32_e32 v35, 11, v35
	v_cmp_lt_i32_e32 vcc, 2, v32
	v_mul_lo_u32 v32, v34, s51
	v_mul_u32_u24_e32 v35, 0x1010, v35
	v_add_lshl_u32 v136, v32, v164, 1
	v_add_u32_e32 v32, s43, v165
	v_sub_u32_e32 v35, v34, v35
	v_cmp_gt_i32_e64 s[4:5], s50, v33
	v_lshl_add_u32 v34, v32, 1, s53
	s_and_b64 s[2:3], vcc, s[4:5]
	v_cmp_eq_u32_e64 s[8:9], 0, v35
	v_cmp_lt_u32_e64 s[6:7], 1, v35
	v_cmp_lt_u32_e64 s[4:5], 2, v35
	v_add_u32_e32 v35, v34, v163
	ds_read_b64 v[32:33], v34 offset:1024
	v_add_u32_e32 v36, v34, v162
	ds_read_b64 v[50:51], v35 offset:512
	ds_read_b64 v[52:53], v36
	v_readlane_b32 s22, v237, 58
	v_readlane_b32 s23, v237, 59
	s_waitcnt lgkmcnt(0)
	v_lshlrev_b32_e32 v47, 16, v32
	v_and_b32_e32 v48, 0xffff0000, v32
	v_lshlrev_b32_e32 v41, 16, v33
	v_and_b32_e32 v42, 0xffff0000, v33
	v_lshlrev_b32_e32 v45, 16, v50
	v_and_b32_e32 v46, 0xffff0000, v50
	v_lshlrev_b32_e32 v39, 16, v51
	v_and_b32_e32 v40, 0xffff0000, v51
	v_lshlrev_b32_e32 v43, 16, v52
	v_and_b32_e32 v44, 0xffff0000, v52
	v_lshlrev_b32_e32 v37, 16, v53
	v_and_b32_e32 v38, 0xffff0000, v53
	v_mov_b32_dpp v47, v28 row_shr:1 row_mask:0xf bank_mask:0xf
	v_mov_b32_dpp v45, v28 row_shr:2 row_mask:0xf bank_mask:0xf
	v_mov_b32_dpp v43, v28 row_shr:3 row_mask:0xf bank_mask:0xf
	v_mov_b32_dpp v48, v29 row_shr:1 row_mask:0xf bank_mask:0xf
	v_mov_b32_dpp v46, v29 row_shr:2 row_mask:0xf bank_mask:0xf
	v_mov_b32_dpp v44, v29 row_shr:3 row_mask:0xf bank_mask:0xf
	v_mov_b32_dpp v41, v30 row_shr:1 row_mask:0xf bank_mask:0xf
	v_mov_b32_dpp v39, v30 row_shr:2 row_mask:0xf bank_mask:0xf
	v_mov_b32_dpp v37, v30 row_shr:3 row_mask:0xf bank_mask:0xf
	v_mov_b32_dpp v42, v31 row_shr:1 row_mask:0xf bank_mask:0xf
	v_mov_b32_dpp v40, v31 row_shr:2 row_mask:0xf bank_mask:0xf
	v_mov_b32_dpp v38, v31 row_shr:3 row_mask:0xf bank_mask:0xf
	v_lshl_add_u64 v[32:33], s[22:23], 0, v[136:137]
	s_and_saveexec_b64 s[22:23], s[2:3]
	s_cbranch_execz .LBB0_233
	ds_read_b128 v[50:53], v238 offset:4096
	ds_read_b128 v[54:57], v238 offset:3072
	ds_read_b128 v[58:61], v238 offset:2048
	v_cndmask_b32_e64 v49, v48, 0, s[8:9]
	ds_read_b128 v[62:65], v238 offset:1024
	s_nop 0
	ds_read_b128 v[66:69], v238
	v_cndmask_b32_e64 v48, v47, 0, s[8:9]
	v_cndmask_b32_e64 v47, 0, v46, s[6:7]
	v_cndmask_b32_e64 v46, 0, v45, s[6:7]
	v_cndmask_b32_e64 v45, 0, v44, s[4:5]
	v_cndmask_b32_e64 v44, 0, v43, s[4:5]
	s_waitcnt lgkmcnt(0)
	v_pk_fma_f32 v[28:29], v[28:29], v[54:55], v[50:51]
	v_pk_fma_f32 v[30:31], v[30:31], v[56:57], v[52:53]
	v_pk_fma_f32 v[28:29], v[48:49], v[58:59], v[28:29]
	s_nop 0
	v_pk_fma_f32 v[28:29], v[46:47], v[62:63], v[28:29]
	s_nop 0
	v_pk_fma_f32 v[28:29], v[44:45], v[66:67], v[28:29]
	s_nop 0
	v_mul_f32_e32 v43, 0xbfb8aa3b, v29
	v_exp_f32_e32 v43, v43
	s_nop 0
	v_add_f32_e32 v43, 1.0, v43
	v_rcp_f32_e32 v45, v43
	v_mul_f32_e32 v43, 0xbfb8aa3b, v28
	v_exp_f32_e32 v43, v43
	s_nop 0
	v_add_f32_e32 v43, 1.0, v43
	v_rcp_f32_e32 v44, v43
	v_cndmask_b32_e64 v43, v42, 0, s[8:9]
	v_cndmask_b32_e64 v42, v41, 0, s[8:9]
	v_pk_fma_f32 v[30:31], v[42:43], v[60:61], v[30:31]
	v_cndmask_b32_e64 v41, 0, v40, s[6:7]
	v_cndmask_b32_e64 v40, 0, v39, s[6:7]
	v_pk_fma_f32 v[30:31], v[40:41], v[64:65], v[30:31]
	v_cndmask_b32_e64 v39, 0, v38, s[4:5]
	v_cndmask_b32_e64 v38, 0, v37, s[4:5]
	v_pk_mul_f32 v[28:29], v[28:29], v[44:45]
	v_pk_fma_f32 v[30:31], v[38:39], v[68:69], v[30:31]
	v_cvt_pk_bf16_f32 v204, v28, v29
	v_mul_f32_e32 v29, 0xbfb8aa3b, v31
	v_exp_f32_e32 v29, v29
	s_nop 0
	v_add_f32_e32 v29, 1.0, v29
	v_rcp_f32_e32 v39, v29
	v_mul_f32_e32 v29, 0xbfb8aa3b, v30
	v_exp_f32_e32 v29, v29
	s_nop 0
	v_add_f32_e32 v29, 1.0, v29
	v_rcp_f32_e32 v38, v29
	s_nop 0
	v_pk_mul_f32 v[30:31], v[30:31], v[38:39]
	s_nop 0
	v_cvt_pk_bf16_f32 v205, v30, v31
.LBB0_233:
	s_or_b64 exec, exec, s[22:23]
	ds_read_b64 v[28:29], v34 offset:1032
	ds_read_b64 v[30:31], v35 offset:520
	ds_read_b64 v[46:47], v36 offset:8
	s_waitcnt lgkmcnt(0)
	v_lshlrev_b32_e32 v43, 16, v28
	v_and_b32_e32 v44, 0xffff0000, v28
	v_lshlrev_b32_e32 v37, 16, v29
	v_and_b32_e32 v38, 0xffff0000, v29
	v_lshlrev_b32_e32 v41, 16, v30
	v_and_b32_e32 v42, 0xffff0000, v30
	v_lshlrev_b32_e32 v30, 16, v31
	v_and_b32_e32 v31, 0xffff0000, v31
	v_lshlrev_b32_e32 v39, 16, v46
	v_and_b32_e32 v40, 0xffff0000, v46
	v_lshlrev_b32_e32 v28, 16, v47
	v_and_b32_e32 v29, 0xffff0000, v47
	v_mov_b32_dpp v43, v24 row_shr:1 row_mask:0xf bank_mask:0xf
	v_mov_b32_dpp v41, v24 row_shr:2 row_mask:0xf bank_mask:0xf
	v_mov_b32_dpp v39, v24 row_shr:3 row_mask:0xf bank_mask:0xf
	v_mov_b32_dpp v44, v25 row_shr:1 row_mask:0xf bank_mask:0xf
	v_mov_b32_dpp v42, v25 row_shr:2 row_mask:0xf bank_mask:0xf
	v_mov_b32_dpp v40, v25 row_shr:3 row_mask:0xf bank_mask:0xf
	v_mov_b32_dpp v37, v26 row_shr:1 row_mask:0xf bank_mask:0xf
	v_mov_b32_dpp v30, v26 row_shr:2 row_mask:0xf bank_mask:0xf
	v_mov_b32_dpp v28, v26 row_shr:3 row_mask:0xf bank_mask:0xf
	v_mov_b32_dpp v38, v27 row_shr:1 row_mask:0xf bank_mask:0xf
	v_mov_b32_dpp v31, v27 row_shr:2 row_mask:0xf bank_mask:0xf
	v_mov_b32_dpp v29, v27 row_shr:3 row_mask:0xf bank_mask:0xf
	s_and_saveexec_b64 s[22:23], s[2:3]
	s_cbranch_execz .LBB0_235
;     __device__ __forceinline__ void operator()(const f32x4 (&acc)[2][2][4][2], const Unit& u, int wr, int wc, int fr, int fq, LAS unsigned char* hb) const {
;     ...
;                 for (int bn = 0; bn < 4; ++bn) { const int bj = bn >> 1, n = bn & 1; const int co = bj * HALF + 4 * n;
;                     const unsigned woff = (unsigned)(ch0 + co) * 4u;
;                     const f32x4 w0 = *(const f32x4*)((const char*)cw + woff), w1 = *(const f32x4*)((const char*)cw + woff + XBCW * 4), w2 = *(const f32x4*)((const char*)cw + woff + 2 * XBCW * 4), w3 = *(const f32x4*)((const char*)cw + woff + 3 * XBCW * 4), bs = *(const f32x4*)((const char*)cb + woff);
;                     const LAS unsigned char* hp = hb + (prev * H * NCH + chl + co) * 2;
;                     const u32x2 q1 = *(const LAS u32x2*)(hp + hr1 * NCH * 2), q2 = *(const LAS u32x2*)(hp + hr2 * NCH * 2), q3 = *(const LAS u32x2*)(hp + hr3 * NCH * 2);
;                     const float h1[4] = {__builtin_bit_cast(float, q1.x << 16), __builtin_bit_cast(float, q1.x & 0xffff0000u), __builtin_bit_cast(float, q1.y << 16), __builtin_bit_cast(float, q1.y & 0xffff0000u)};
;                     const float h2[4] = {__builtin_bit_cast(float, q2.x << 16), __builtin_bit_cast(float, q2.x & 0xffff0000u), __builtin_bit_cast(float, q2.y << 16), __builtin_bit_cast(float, q2.y & 0xffff0000u)};
;                     const float h3[4] = {__builtin_bit_cast(float, q3.x << 16), __builtin_bit_cast(float, q3.x & 0xffff0000u), __builtin_bit_cast(float, q3.y << 16), __builtin_bit_cast(float, q3.y & 0xffff0000u)};
;                     const f32x4 gv = acc[ai][bj][m][n];
;                     float o[4];
; #pragma unroll
;                     for (int j = 0; j < 4; ++j) { const float g = gv[j];
;                         float g1 = dpp_row_shr<1>(h1[j], g), g2 = dpp_row_shr<2>(h2[j], g), g3 = dpp_row_shr<3>(h3[j], g);
;                         g1 = p >= 1 ? g1 : 0.f; g2 = p >= 2 ? g2 : 0.f; g3 = p >= 3 ? g3 : 0.f;
;                         const float v = bs[j] + w3[j] * g + w2[j] * g1 + w1[j] * g2 + w0[j] * g3;
;                         o[j] = v * __builtin_amdgcn_rcpf(1.f + ex2(-1.4426950408889634f * v)); }
;                     if (ok) { u32x2 w; w.x = pk2e(o[0], o[1]); w.y = pk2e(o[2], o[3]); *(u32x2*)((char*)O + ooff + co * 2) = w; }
;                     asm volatile("" ::: "memory"); }
	ds_read_b128 v[46:49], v238 offset:4112
	ds_read_b128 v[50:53], v238 offset:3088
	ds_read_b128 v[54:57], v238 offset:2064
	v_cndmask_b32_e64 v45, v44, 0, s[8:9]
	ds_read_b128 v[58:61], v238 offset:1040
	s_nop 0
	ds_read_b128 v[62:65], v238 offset:16
	v_cndmask_b32_e64 v44, v43, 0, s[8:9]
	v_cndmask_b32_e64 v43, 0, v42, s[6:7]
	v_cndmask_b32_e64 v42, 0, v41, s[6:7]
	v_cndmask_b32_e64 v41, 0, v40, s[4:5]
	v_cndmask_b32_e64 v40, 0, v39, s[4:5]
	v_cndmask_b32_e64 v31, 0, v31, s[6:7]
	v_cndmask_b32_e64 v30, 0, v30, s[6:7]
	v_cndmask_b32_e64 v29, 0, v29, s[4:5]
	v_cndmask_b32_e64 v28, 0, v28, s[4:5]
	s_waitcnt lgkmcnt(0)
	v_pk_fma_f32 v[24:25], v[24:25], v[50:51], v[46:47]
	v_pk_fma_f32 v[26:27], v[26:27], v[52:53], v[48:49]
	v_pk_fma_f32 v[24:25], v[44:45], v[54:55], v[24:25]
	s_nop 0
	v_pk_fma_f32 v[24:25], v[42:43], v[58:59], v[24:25]
	s_nop 0
	v_pk_fma_f32 v[24:25], v[40:41], v[62:63], v[24:25]
	s_nop 0
	v_mul_f32_e32 v39, 0xbfb8aa3b, v25
	v_exp_f32_e32 v39, v39
	s_nop 0
	v_add_f32_e32 v39, 1.0, v39
	v_rcp_f32_e32 v41, v39
	v_mul_f32_e32 v39, 0xbfb8aa3b, v24
	v_exp_f32_e32 v39, v39
	s_nop 0
	v_add_f32_e32 v39, 1.0, v39
	v_rcp_f32_e32 v40, v39
	v_cndmask_b32_e64 v39, v38, 0, s[8:9]
	v_cndmask_b32_e64 v38, v37, 0, s[8:9]
	v_pk_fma_f32 v[26:27], v[38:39], v[56:57], v[26:27]
	v_pk_mul_f32 v[24:25], v[24:25], v[40:41]
	v_pk_fma_f32 v[26:27], v[30:31], v[60:61], v[26:27]
	v_cvt_pk_bf16_f32 v206, v24, v25
	v_pk_fma_f32 v[26:27], v[28:29], v[64:65], v[26:27]
	s_nop 0
	v_mul_f32_e32 v25, 0xbfb8aa3b, v27
	v_exp_f32_e32 v25, v25
	s_nop 0
	v_add_f32_e32 v25, 1.0, v25
	v_rcp_f32_e32 v29, v25
	v_mul_f32_e32 v25, 0xbfb8aa3b, v26
	v_exp_f32_e32 v25, v25
	s_nop 0
	v_add_f32_e32 v25, 1.0, v25
	v_rcp_f32_e32 v28, v25
	s_nop 0
	v_pk_mul_f32 v[26:27], v[26:27], v[28:29]
	s_nop 0
	v_cvt_pk_bf16_f32 v207, v26, v27
	global_store_dwordx4 v[32:33], v[204:207], off
.LBB0_235:
	s_or_b64 exec, exec, s[22:23]
	ds_read_b64 v[24:25], v34 offset:1280
	ds_read_b64 v[26:27], v35 offset:768
	ds_read_b64 v[42:43], v36 offset:256
	s_waitcnt lgkmcnt(0)
	v_lshlrev_b32_e32 v39, 16, v24
	v_and_b32_e32 v40, 0xffff0000, v24
	v_lshlrev_b32_e32 v28, 16, v25
	v_and_b32_e32 v29, 0xffff0000, v25
	v_lshlrev_b32_e32 v37, 16, v26
	v_and_b32_e32 v38, 0xffff0000, v26
	v_lshlrev_b32_e32 v26, 16, v27
	v_and_b32_e32 v27, 0xffff0000, v27
	v_lshlrev_b32_e32 v30, 16, v42
	v_and_b32_e32 v31, 0xffff0000, v42
	v_lshlrev_b32_e32 v24, 16, v43
	v_and_b32_e32 v25, 0xffff0000, v43
	v_mov_b32_dpp v39, v20 row_shr:1 row_mask:0xf bank_mask:0xf
	v_mov_b32_dpp v37, v20 row_shr:2 row_mask:0xf bank_mask:0xf
	v_mov_b32_dpp v30, v20 row_shr:3 row_mask:0xf bank_mask:0xf
	v_mov_b32_dpp v40, v21 row_shr:1 row_mask:0xf bank_mask:0xf
	v_mov_b32_dpp v38, v21 row_shr:2 row_mask:0xf bank_mask:0xf
	v_mov_b32_dpp v31, v21 row_shr:3 row_mask:0xf bank_mask:0xf
	v_mov_b32_dpp v28, v22 row_shr:1 row_mask:0xf bank_mask:0xf
	v_mov_b32_dpp v26, v22 row_shr:2 row_mask:0xf bank_mask:0xf
	v_mov_b32_dpp v24, v22 row_shr:3 row_mask:0xf bank_mask:0xf
	v_mov_b32_dpp v29, v23 row_shr:1 row_mask:0xf bank_mask:0xf
	v_mov_b32_dpp v27, v23 row_shr:2 row_mask:0xf bank_mask:0xf
	v_mov_b32_dpp v25, v23 row_shr:3 row_mask:0xf bank_mask:0xf
	s_and_saveexec_b64 s[22:23], s[2:3]
	s_cbranch_execz .LBB0_237
	ds_read_b128 v[42:45], v238 offset:4608
	ds_read_b128 v[46:49], v238 offset:3584
	ds_read_b128 v[50:53], v238 offset:2560
	v_cndmask_b32_e64 v41, v40, 0, s[8:9]
	ds_read_b128 v[54:57], v238 offset:1536
	s_nop 0
	ds_read_b128 v[58:61], v238 offset:512
	v_cndmask_b32_e64 v40, v39, 0, s[8:9]
	v_cndmask_b32_e64 v39, 0, v38, s[6:7]
	v_cndmask_b32_e64 v38, 0, v37, s[6:7]
	v_cndmask_b32_e64 v31, 0, v31, s[4:5]
	v_cndmask_b32_e64 v30, 0, v30, s[4:5]
	v_cndmask_b32_e64 v29, v29, 0, s[8:9]
	v_cndmask_b32_e64 v28, v28, 0, s[8:9]
	v_cndmask_b32_e64 v27, 0, v27, s[6:7]
	v_cndmask_b32_e64 v26, 0, v26, s[6:7]
	v_cndmask_b32_e64 v25, 0, v25, s[4:5]
	v_cndmask_b32_e64 v24, 0, v24, s[4:5]
	s_waitcnt lgkmcnt(0)
	v_pk_fma_f32 v[20:21], v[20:21], v[46:47], v[42:43]
	v_pk_fma_f32 v[22:23], v[22:23], v[48:49], v[44:45]
	v_pk_fma_f32 v[20:21], v[40:41], v[50:51], v[20:21]
	v_pk_fma_f32 v[22:23], v[28:29], v[52:53], v[22:23]
	v_pk_fma_f32 v[20:21], v[38:39], v[54:55], v[20:21]
	s_nop 0
	v_pk_fma_f32 v[20:21], v[30:31], v[58:59], v[20:21]
	v_pk_fma_f32 v[22:23], v[26:27], v[56:57], v[22:23]
	v_mul_f32_e32 v30, 0xbfb8aa3b, v21
	v_exp_f32_e32 v30, v30
	v_pk_fma_f32 v[22:23], v[24:25], v[60:61], v[22:23]
	v_add_f32_e32 v30, 1.0, v30
	v_rcp_f32_e32 v31, v30
	v_mul_f32_e32 v30, 0xbfb8aa3b, v20
	v_exp_f32_e32 v30, v30
	s_nop 0
	v_add_f32_e32 v30, 1.0, v30
	v_rcp_f32_e32 v30, v30
	s_nop 0
	v_pk_mul_f32 v[20:21], v[20:21], v[30:31]
	s_nop 0
	v_cvt_pk_bf16_f32 v204, v20, v21
	v_mul_f32_e32 v21, 0xbfb8aa3b, v23
	v_exp_f32_e32 v21, v21
	s_nop 0
	v_add_f32_e32 v21, 1.0, v21
	v_rcp_f32_e32 v25, v21
	v_mul_f32_e32 v21, 0xbfb8aa3b, v22
	v_exp_f32_e32 v21, v21
	s_nop 0
	v_add_f32_e32 v21, 1.0, v21
	v_rcp_f32_e32 v24, v21
	s_nop 0
	v_pk_mul_f32 v[22:23], v[22:23], v[24:25]
	s_nop 0
	v_cvt_pk_bf16_f32 v205, v22, v23
;     __device__ __forceinline__ void operator()(const f32x4 (&acc)[2][2][4][2], const Unit& u, int wr, int wc, int fr, int fq, LAS unsigned char* hb) const {
;     ...
;                 for (int bn = 0; bn < 4; ++bn) { const int bj = bn >> 1, n = bn & 1; const int co = bj * HALF + 4 * n;
;                     const unsigned woff = (unsigned)(ch0 + co) * 4u;
;                     const f32x4 w0 = *(const f32x4*)((const char*)cw + woff), w1 = *(const f32x4*)((const char*)cw + woff + XBCW * 4), w2 = *(const f32x4*)((const char*)cw + woff + 2 * XBCW * 4), w3 = *(const f32x4*)((const char*)cw + woff + 3 * XBCW * 4), bs = *(const f32x4*)((const char*)cb + woff);
;                     const LAS unsigned char* hp = hb + (prev * H * NCH + chl + co) * 2;
;                     const u32x2 q1 = *(const LAS u32x2*)(hp + hr1 * NCH * 2), q2 = *(const LAS u32x2*)(hp + hr2 * NCH * 2), q3 = *(const LAS u32x2*)(hp + hr3 * NCH * 2);
;                     const float h1[4] = {__builtin_bit_cast(float, q1.x << 16), __builtin_bit_cast(float, q1.x & 0xffff0000u), __builtin_bit_cast(float, q1.y << 16), __builtin_bit_cast(float, q1.y & 0xffff0000u)};
;                     const float h2[4] = {__builtin_bit_cast(float, q2.x << 16), __builtin_bit_cast(float, q2.x & 0xffff0000u), __builtin_bit_cast(float, q2.y << 16), __builtin_bit_cast(float, q2.y & 0xffff0000u)};
;                     const float h3[4] = {__builtin_bit_cast(float, q3.x << 16), __builtin_bit_cast(float, q3.x & 0xffff0000u), __builtin_bit_cast(float, q3.y << 16), __builtin_bit_cast(float, q3.y & 0xffff0000u)};
;                     const f32x4 gv = acc[ai][bj][m][n];
;                     float o[4];
; #pragma unroll
;                     for (int j = 0; j < 4; ++j) { const float g = gv[j];
;                         float g1 = dpp_row_shr<1>(h1[j], g), g2 = dpp_row_shr<2>(h2[j], g), g3 = dpp_row_shr<3>(h3[j], g);
;                         g1 = p >= 1 ? g1 : 0.f; g2 = p >= 2 ? g2 : 0.f; g3 = p >= 3 ? g3 : 0.f;
;                         const float v = bs[j] + w3[j] * g + w2[j] * g1 + w1[j] * g2 + w0[j] * g3;
;                         o[j] = v * __builtin_amdgcn_rcpf(1.f + ex2(-1.4426950408889634f * v)); }
;                     if (ok) { u32x2 w; w.x = pk2e(o[0], o[1]); w.y = pk2e(o[2], o[3]); *(u32x2*)((char*)O + ooff + co * 2) = w; }
;                     asm volatile("" ::: "memory"); }
.LBB0_237:
	s_or_b64 exec, exec, s[22:23]
	ds_read_b64 v[20:21], v34 offset:1288
	ds_read_b64 v[22:23], v35 offset:776
	ds_read_b64 v[34:35], v36 offset:264
	s_waitcnt lgkmcnt(0)
	v_lshlrev_b32_e32 v30, 16, v20
	v_and_b32_e32 v31, 0xffff0000, v20
	v_lshlrev_b32_e32 v24, 16, v21
	v_and_b32_e32 v25, 0xffff0000, v21
	v_lshlrev_b32_e32 v28, 16, v22
	v_and_b32_e32 v29, 0xffff0000, v22
	v_lshlrev_b32_e32 v22, 16, v23
	v_and_b32_e32 v23, 0xffff0000, v23
	v_lshlrev_b32_e32 v26, 16, v34
	v_and_b32_e32 v27, 0xffff0000, v34
	v_lshlrev_b32_e32 v20, 16, v35
	v_and_b32_e32 v21, 0xffff0000, v35
	v_mov_b32_dpp v30, v16 row_shr:1 row_mask:0xf bank_mask:0xf
	v_mov_b32_dpp v28, v16 row_shr:2 row_mask:0xf bank_mask:0xf
	v_mov_b32_dpp v26, v16 row_shr:3 row_mask:0xf bank_mask:0xf
	v_mov_b32_dpp v31, v17 row_shr:1 row_mask:0xf bank_mask:0xf
	v_mov_b32_dpp v29, v17 row_shr:2 row_mask:0xf bank_mask:0xf
	v_mov_b32_dpp v27, v17 row_shr:3 row_mask:0xf bank_mask:0xf
	v_mov_b32_dpp v24, v18 row_shr:1 row_mask:0xf bank_mask:0xf
	v_mov_b32_dpp v22, v18 row_shr:2 row_mask:0xf bank_mask:0xf
	v_mov_b32_dpp v20, v18 row_shr:3 row_mask:0xf bank_mask:0xf
	v_mov_b32_dpp v25, v19 row_shr:1 row_mask:0xf bank_mask:0xf
	v_mov_b32_dpp v23, v19 row_shr:2 row_mask:0xf bank_mask:0xf
	v_mov_b32_dpp v21, v19 row_shr:3 row_mask:0xf bank_mask:0xf
	s_and_saveexec_b64 s[22:23], s[2:3]
	s_cbranch_execz .LBB0_239
	ds_read_b128 v[34:37], v238 offset:4624
	ds_read_b128 v[38:41], v238 offset:3600
	ds_read_b128 v[42:45], v238 offset:2576
	v_cndmask_b32_e64 v31, v31, 0, s[8:9]
	ds_read_b128 v[46:49], v238 offset:1552
	s_nop 0
	ds_read_b128 v[50:53], v238 offset:528
	v_cndmask_b32_e64 v30, v30, 0, s[8:9]
	v_cndmask_b32_e64 v29, 0, v29, s[6:7]
	v_cndmask_b32_e64 v28, 0, v28, s[6:7]
	v_cndmask_b32_e64 v27, 0, v27, s[4:5]
	v_cndmask_b32_e64 v26, 0, v26, s[4:5]
	v_cndmask_b32_e64 v25, v25, 0, s[8:9]
	v_cndmask_b32_e64 v24, v24, 0, s[8:9]
	v_cndmask_b32_e64 v23, 0, v23, s[6:7]
	v_cndmask_b32_e64 v22, 0, v22, s[6:7]
	v_cndmask_b32_e64 v21, 0, v21, s[4:5]
	v_cndmask_b32_e64 v20, 0, v20, s[4:5]
	s_waitcnt lgkmcnt(0)
	v_pk_fma_f32 v[16:17], v[16:17], v[38:39], v[34:35]
	v_pk_fma_f32 v[18:19], v[18:19], v[40:41], v[36:37]
	v_pk_fma_f32 v[16:17], v[30:31], v[42:43], v[16:17]
	v_pk_fma_f32 v[18:19], v[24:25], v[44:45], v[18:19]
	v_pk_fma_f32 v[16:17], v[28:29], v[46:47], v[16:17]
	s_nop 0
	v_pk_fma_f32 v[16:17], v[26:27], v[50:51], v[16:17]
	v_pk_fma_f32 v[18:19], v[22:23], v[48:49], v[18:19]
	v_mul_f32_e32 v26, 0xbfb8aa3b, v17
	v_exp_f32_e32 v26, v26
	v_pk_fma_f32 v[18:19], v[20:21], v[52:53], v[18:19]
	v_add_f32_e32 v26, 1.0, v26
	v_rcp_f32_e32 v27, v26
	v_mul_f32_e32 v26, 0xbfb8aa3b, v16
	v_exp_f32_e32 v26, v26
	s_nop 0
	v_add_f32_e32 v26, 1.0, v26
	v_rcp_f32_e32 v26, v26
	s_nop 0
	v_pk_mul_f32 v[16:17], v[16:17], v[26:27]
	s_nop 0
	v_cvt_pk_bf16_f32 v206, v16, v17
	v_mul_f32_e32 v17, 0xbfb8aa3b, v19
	v_exp_f32_e32 v17, v17
	s_nop 0
	v_add_f32_e32 v17, 1.0, v17
	v_rcp_f32_e32 v21, v17
	v_mul_f32_e32 v17, 0xbfb8aa3b, v18
	v_exp_f32_e32 v17, v17
	s_nop 0
	v_add_f32_e32 v17, 1.0, v17
	v_rcp_f32_e32 v20, v17
	s_nop 0
	v_pk_mul_f32 v[18:19], v[18:19], v[20:21]
	s_nop 0
	v_cvt_pk_bf16_f32 v207, v18, v19
	global_store_dwordx4 v[32:33], v[204:207], off offset:256
.LBB0_239:
	s_or_b64 exec, exec, s[22:23]
	v_add_u32_e32 v16, 0xb0, v161
	v_add_u32_e32 v17, s17, v16
	v_max_i32_e32 v18, 0, v17
	v_mul_hi_u32 v19, v18, s56
	v_lshrrev_b32_e32 v19, 11, v19
	v_cmp_lt_i32_e32 vcc, 2, v16
	v_mul_lo_u32 v16, v18, s51
	v_mul_u32_u24_e32 v19, 0x1010, v19
	v_add_lshl_u32 v136, v16, v164, 1
	v_add_u32_e32 v16, s44, v165
	v_sub_u32_e32 v19, v18, v19
	v_cmp_gt_i32_e64 s[4:5], s50, v17
	v_lshl_add_u32 v18, v16, 1, s53
	s_and_b64 s[2:3], vcc, s[4:5]
	v_cmp_eq_u32_e64 s[8:9], 0, v19
	v_cmp_lt_u32_e64 s[6:7], 1, v19
	v_cmp_lt_u32_e64 s[4:5], 2, v19
	v_add_u32_e32 v19, v18, v163
	ds_read_b64 v[16:17], v18 offset:1024
	v_add_u32_e32 v20, v18, v162
	ds_read_b64 v[34:35], v19 offset:512
	ds_read_b64 v[36:37], v20
	v_readlane_b32 s22, v237, 58
	v_readlane_b32 s23, v237, 59
	s_waitcnt lgkmcnt(0)
	v_lshlrev_b32_e32 v31, 16, v16
	v_and_b32_e32 v32, 0xffff0000, v16
	v_lshlrev_b32_e32 v25, 16, v17
	v_and_b32_e32 v26, 0xffff0000, v17
	v_lshlrev_b32_e32 v29, 16, v34
	v_and_b32_e32 v30, 0xffff0000, v34
	v_lshlrev_b32_e32 v23, 16, v35
	v_and_b32_e32 v24, 0xffff0000, v35
	v_lshlrev_b32_e32 v27, 16, v36
	v_and_b32_e32 v28, 0xffff0000, v36
	v_lshlrev_b32_e32 v21, 16, v37
	v_and_b32_e32 v22, 0xffff0000, v37
	v_mov_b32_dpp v31, v12 row_shr:1 row_mask:0xf bank_mask:0xf
	v_mov_b32_dpp v29, v12 row_shr:2 row_mask:0xf bank_mask:0xf
	v_mov_b32_dpp v27, v12 row_shr:3 row_mask:0xf bank_mask:0xf
	v_mov_b32_dpp v32, v13 row_shr:1 row_mask:0xf bank_mask:0xf
	v_mov_b32_dpp v30, v13 row_shr:2 row_mask:0xf bank_mask:0xf
	v_mov_b32_dpp v28, v13 row_shr:3 row_mask:0xf bank_mask:0xf
	v_mov_b32_dpp v25, v14 row_shr:1 row_mask:0xf bank_mask:0xf
	v_mov_b32_dpp v23, v14 row_shr:2 row_mask:0xf bank_mask:0xf
	v_mov_b32_dpp v21, v14 row_shr:3 row_mask:0xf bank_mask:0xf
	v_mov_b32_dpp v26, v15 row_shr:1 row_mask:0xf bank_mask:0xf
	v_mov_b32_dpp v24, v15 row_shr:2 row_mask:0xf bank_mask:0xf
	v_mov_b32_dpp v22, v15 row_shr:3 row_mask:0xf bank_mask:0xf
	v_lshl_add_u64 v[16:17], s[22:23], 0, v[136:137]
	s_and_saveexec_b64 s[22:23], s[2:3]
	s_cbranch_execz .LBB0_241
;     __device__ __forceinline__ void operator()(const f32x4 (&acc)[2][2][4][2], const Unit& u, int wr, int wc, int fr, int fq, LAS unsigned char* hb) const {
;     ...
;                 for (int bn = 0; bn < 4; ++bn) { const int bj = bn >> 1, n = bn & 1; const int co = bj * HALF + 4 * n;
;                     const unsigned woff = (unsigned)(ch0 + co) * 4u;
;                     const f32x4 w0 = *(const f32x4*)((const char*)cw + woff), w1 = *(const f32x4*)((const char*)cw + woff + XBCW * 4), w2 = *(const f32x4*)((const char*)cw + woff + 2 * XBCW * 4), w3 = *(const f32x4*)((const char*)cw + woff + 3 * XBCW * 4), bs = *(const f32x4*)((const char*)cb + woff);
;                     const LAS unsigned char* hp = hb + (prev * H * NCH + chl + co) * 2;
;                     const u32x2 q1 = *(const LAS u32x2*)(hp + hr1 * NCH * 2), q2 = *(const LAS u32x2*)(hp + hr2 * NCH * 2), q3 = *(const LAS u32x2*)(hp + hr3 * NCH * 2);
;                     const float h1[4] = {__builtin_bit_cast(float, q1.x << 16), __builtin_bit_cast(float, q1.x & 0xffff0000u), __builtin_bit_cast(float, q1.y << 16), __builtin_bit_cast(float, q1.y & 0xffff0000u)};
;                     const float h2[4] = {__builtin_bit_cast(float, q2.x << 16), __builtin_bit_cast(float, q2.x & 0xffff0000u), __builtin_bit_cast(float, q2.y << 16), __builtin_bit_cast(float, q2.y & 0xffff0000u)};
;                     const float h3[4] = {__builtin_bit_cast(float, q3.x << 16), __builtin_bit_cast(float, q3.x & 0xffff0000u), __builtin_bit_cast(float, q3.y << 16), __builtin_bit_cast(float, q3.y & 0xffff0000u)};
;                     const f32x4 gv = acc[ai][bj][m][n];
;                     float o[4];
; #pragma unroll
;                     for (int j = 0; j < 4; ++j) { const float g = gv[j];
;                         float g1 = dpp_row_shr<1>(h1[j], g), g2 = dpp_row_shr<2>(h2[j], g), g3 = dpp_row_shr<3>(h3[j], g);
;                         g1 = p >= 1 ? g1 : 0.f; g2 = p >= 2 ? g2 : 0.f; g3 = p >= 3 ? g3 : 0.f;
;                         const float v = bs[j] + w3[j] * g + w2[j] * g1 + w1[j] * g2 + w0[j] * g3;
;                         o[j] = v * __builtin_amdgcn_rcpf(1.f + ex2(-1.4426950408889634f * v)); }
;                     if (ok) { u32x2 w; w.x = pk2e(o[0], o[1]); w.y = pk2e(o[2], o[3]); *(u32x2*)((char*)O + ooff + co * 2) = w; }
;                     asm volatile("" ::: "memory"); }
	ds_read_b128 v[34:37], v238 offset:4096
	ds_read_b128 v[38:41], v238 offset:3072
	ds_read_b128 v[42:45], v238 offset:2048
	v_cndmask_b32_e64 v33, v32, 0, s[8:9]
	ds_read_b128 v[46:49], v238 offset:1024
	s_nop 0
	ds_read_b128 v[50:53], v238
	v_cndmask_b32_e64 v32, v31, 0, s[8:9]
	v_cndmask_b32_e64 v31, 0, v30, s[6:7]
	v_cndmask_b32_e64 v30, 0, v29, s[6:7]
	v_cndmask_b32_e64 v29, 0, v28, s[4:5]
	v_cndmask_b32_e64 v28, 0, v27, s[4:5]
	s_waitcnt lgkmcnt(0)
	v_pk_fma_f32 v[12:13], v[12:13], v[38:39], v[34:35]
	v_pk_fma_f32 v[14:15], v[14:15], v[40:41], v[36:37]
	v_pk_fma_f32 v[12:13], v[32:33], v[42:43], v[12:13]
	s_nop 0
	v_pk_fma_f32 v[12:13], v[30:31], v[46:47], v[12:13]
	s_nop 0
	v_pk_fma_f32 v[12:13], v[28:29], v[50:51], v[12:13]
	s_nop 0
	v_mul_f32_e32 v27, 0xbfb8aa3b, v13
	v_exp_f32_e32 v27, v27
	s_nop 0
	v_add_f32_e32 v27, 1.0, v27
	v_rcp_f32_e32 v29, v27
	v_mul_f32_e32 v27, 0xbfb8aa3b, v12
	v_exp_f32_e32 v27, v27
	s_nop 0
	v_add_f32_e32 v27, 1.0, v27
	v_rcp_f32_e32 v28, v27
	v_cndmask_b32_e64 v27, v26, 0, s[8:9]
	v_cndmask_b32_e64 v26, v25, 0, s[8:9]
	v_pk_fma_f32 v[14:15], v[26:27], v[44:45], v[14:15]
	v_cndmask_b32_e64 v25, 0, v24, s[6:7]
	v_cndmask_b32_e64 v24, 0, v23, s[6:7]
	v_pk_fma_f32 v[14:15], v[24:25], v[48:49], v[14:15]
	v_cndmask_b32_e64 v23, 0, v22, s[4:5]
	v_cndmask_b32_e64 v22, 0, v21, s[4:5]
	v_pk_mul_f32 v[12:13], v[12:13], v[28:29]
	v_pk_fma_f32 v[14:15], v[22:23], v[52:53], v[14:15]
	v_cvt_pk_bf16_f32 v204, v12, v13
	v_mul_f32_e32 v13, 0xbfb8aa3b, v15
	v_exp_f32_e32 v13, v13
	s_nop 0
	v_add_f32_e32 v13, 1.0, v13
	v_rcp_f32_e32 v23, v13
	v_mul_f32_e32 v13, 0xbfb8aa3b, v14
	v_exp_f32_e32 v13, v13
	s_nop 0
	v_add_f32_e32 v13, 1.0, v13
	v_rcp_f32_e32 v22, v13
	s_nop 0
	v_pk_mul_f32 v[14:15], v[14:15], v[22:23]
	s_nop 0
	v_cvt_pk_bf16_f32 v205, v14, v15
.LBB0_241:
	s_or_b64 exec, exec, s[22:23]
	ds_read_b64 v[12:13], v18 offset:1032
	ds_read_b64 v[14:15], v19 offset:520
	ds_read_b64 v[30:31], v20 offset:8
	s_waitcnt lgkmcnt(0)
	v_lshlrev_b32_e32 v27, 16, v12
	v_and_b32_e32 v28, 0xffff0000, v12
	v_lshlrev_b32_e32 v21, 16, v13
	v_and_b32_e32 v22, 0xffff0000, v13
	v_lshlrev_b32_e32 v25, 16, v14
	v_and_b32_e32 v26, 0xffff0000, v14
	v_lshlrev_b32_e32 v14, 16, v15
	v_and_b32_e32 v15, 0xffff0000, v15
	v_lshlrev_b32_e32 v23, 16, v30
	v_and_b32_e32 v24, 0xffff0000, v30
	v_lshlrev_b32_e32 v12, 16, v31
	v_and_b32_e32 v13, 0xffff0000, v31
	v_mov_b32_dpp v27, v8 row_shr:1 row_mask:0xf bank_mask:0xf
	v_mov_b32_dpp v25, v8 row_shr:2 row_mask:0xf bank_mask:0xf
	v_mov_b32_dpp v23, v8 row_shr:3 row_mask:0xf bank_mask:0xf
	v_mov_b32_dpp v28, v9 row_shr:1 row_mask:0xf bank_mask:0xf
	v_mov_b32_dpp v26, v9 row_shr:2 row_mask:0xf bank_mask:0xf
	v_mov_b32_dpp v24, v9 row_shr:3 row_mask:0xf bank_mask:0xf
	v_mov_b32_dpp v21, v10 row_shr:1 row_mask:0xf bank_mask:0xf
	v_mov_b32_dpp v14, v10 row_shr:2 row_mask:0xf bank_mask:0xf
	v_mov_b32_dpp v12, v10 row_shr:3 row_mask:0xf bank_mask:0xf
	v_mov_b32_dpp v22, v11 row_shr:1 row_mask:0xf bank_mask:0xf
	v_mov_b32_dpp v15, v11 row_shr:2 row_mask:0xf bank_mask:0xf
	v_mov_b32_dpp v13, v11 row_shr:3 row_mask:0xf bank_mask:0xf
	s_and_saveexec_b64 s[22:23], s[2:3]
	s_cbranch_execz .LBB0_243
	ds_read_b128 v[30:33], v238 offset:4112
	ds_read_b128 v[34:37], v238 offset:3088
	ds_read_b128 v[38:41], v238 offset:2064
	v_cndmask_b32_e64 v29, v28, 0, s[8:9]
	ds_read_b128 v[42:45], v238 offset:1040
	s_nop 0
	ds_read_b128 v[46:49], v238 offset:16
	v_cndmask_b32_e64 v28, v27, 0, s[8:9]
	v_cndmask_b32_e64 v27, 0, v26, s[6:7]
	v_cndmask_b32_e64 v26, 0, v25, s[6:7]
	v_cndmask_b32_e64 v25, 0, v24, s[4:5]
	v_cndmask_b32_e64 v24, 0, v23, s[4:5]
	v_cndmask_b32_e64 v15, 0, v15, s[6:7]
	v_cndmask_b32_e64 v14, 0, v14, s[6:7]
	v_cndmask_b32_e64 v13, 0, v13, s[4:5]
	v_cndmask_b32_e64 v12, 0, v12, s[4:5]
	s_waitcnt lgkmcnt(0)
	v_pk_fma_f32 v[8:9], v[8:9], v[34:35], v[30:31]
	v_pk_fma_f32 v[10:11], v[10:11], v[36:37], v[32:33]
	v_pk_fma_f32 v[8:9], v[28:29], v[38:39], v[8:9]
	s_nop 0
	v_pk_fma_f32 v[8:9], v[26:27], v[42:43], v[8:9]
	s_nop 0
	v_pk_fma_f32 v[8:9], v[24:25], v[46:47], v[8:9]
	s_nop 0
	v_mul_f32_e32 v23, 0xbfb8aa3b, v9
	v_exp_f32_e32 v23, v23
	s_nop 0
	v_add_f32_e32 v23, 1.0, v23
	v_rcp_f32_e32 v25, v23
	v_mul_f32_e32 v23, 0xbfb8aa3b, v8
	v_exp_f32_e32 v23, v23
	s_nop 0
	v_add_f32_e32 v23, 1.0, v23
	v_rcp_f32_e32 v24, v23
	v_cndmask_b32_e64 v23, v22, 0, s[8:9]
	v_cndmask_b32_e64 v22, v21, 0, s[8:9]
	v_pk_fma_f32 v[10:11], v[22:23], v[40:41], v[10:11]
	v_pk_mul_f32 v[8:9], v[8:9], v[24:25]
	v_pk_fma_f32 v[10:11], v[14:15], v[44:45], v[10:11]
	v_cvt_pk_bf16_f32 v206, v8, v9
	v_pk_fma_f32 v[10:11], v[12:13], v[48:49], v[10:11]
	s_nop 0
	v_mul_f32_e32 v9, 0xbfb8aa3b, v11
	v_exp_f32_e32 v9, v9
	s_nop 0
	v_add_f32_e32 v9, 1.0, v9
	v_rcp_f32_e32 v13, v9
	v_mul_f32_e32 v9, 0xbfb8aa3b, v10
	v_exp_f32_e32 v9, v9
	s_nop 0
	v_add_f32_e32 v9, 1.0, v9
	v_rcp_f32_e32 v12, v9
	s_nop 0
	v_pk_mul_f32 v[10:11], v[10:11], v[12:13]
	s_nop 0
	v_cvt_pk_bf16_f32 v207, v10, v11
	global_store_dwordx4 v[16:17], v[204:207], off
;     __device__ __forceinline__ void operator()(const f32x4 (&acc)[2][2][4][2], const Unit& u, int wr, int wc, int fr, int fq, LAS unsigned char* hb) const {
;     ...
;                 for (int bn = 0; bn < 4; ++bn) { const int bj = bn >> 1, n = bn & 1; const int co = bj * HALF + 4 * n;
;                     const unsigned woff = (unsigned)(ch0 + co) * 4u;
;                     const f32x4 w0 = *(const f32x4*)((const char*)cw + woff), w1 = *(const f32x4*)((const char*)cw + woff + XBCW * 4), w2 = *(const f32x4*)((const char*)cw + woff + 2 * XBCW * 4), w3 = *(const f32x4*)((const char*)cw + woff + 3 * XBCW * 4), bs = *(const f32x4*)((const char*)cb + woff);
;                     const LAS unsigned char* hp = hb + (prev * H * NCH + chl + co) * 2;
;                     const u32x2 q1 = *(const LAS u32x2*)(hp + hr1 * NCH * 2), q2 = *(const LAS u32x2*)(hp + hr2 * NCH * 2), q3 = *(const LAS u32x2*)(hp + hr3 * NCH * 2);
;                     const float h1[4] = {__builtin_bit_cast(float, q1.x << 16), __builtin_bit_cast(float, q1.x & 0xffff0000u), __builtin_bit_cast(float, q1.y << 16), __builtin_bit_cast(float, q1.y & 0xffff0000u)};
;                     const float h2[4] = {__builtin_bit_cast(float, q2.x << 16), __builtin_bit_cast(float, q2.x & 0xffff0000u), __builtin_bit_cast(float, q2.y << 16), __builtin_bit_cast(float, q2.y & 0xffff0000u)};
;                     const float h3[4] = {__builtin_bit_cast(float, q3.x << 16), __builtin_bit_cast(float, q3.x & 0xffff0000u), __builtin_bit_cast(float, q3.y << 16), __builtin_bit_cast(float, q3.y & 0xffff0000u)};
;                     const f32x4 gv = acc[ai][bj][m][n];
;                     float o[4];
; #pragma unroll
;                     for (int j = 0; j < 4; ++j) { const float g = gv[j];
;                         float g1 = dpp_row_shr<1>(h1[j], g), g2 = dpp_row_shr<2>(h2[j], g), g3 = dpp_row_shr<3>(h3[j], g);
;                         g1 = p >= 1 ? g1 : 0.f; g2 = p >= 2 ? g2 : 0.f; g3 = p >= 3 ? g3 : 0.f;
;                         const float v = bs[j] + w3[j] * g + w2[j] * g1 + w1[j] * g2 + w0[j] * g3;
;                         o[j] = v * __builtin_amdgcn_rcpf(1.f + ex2(-1.4426950408889634f * v)); }
;                     if (ok) { u32x2 w; w.x = pk2e(o[0], o[1]); w.y = pk2e(o[2], o[3]); *(u32x2*)((char*)O + ooff + co * 2) = w; }
;                     asm volatile("" ::: "memory"); }
.LBB0_243:
	s_or_b64 exec, exec, s[22:23]
	ds_read_b64 v[8:9], v18 offset:1280
	ds_read_b64 v[10:11], v19 offset:768
	ds_read_b64 v[26:27], v20 offset:256
	s_waitcnt lgkmcnt(0)
	v_lshlrev_b32_e32 v23, 16, v8
	v_and_b32_e32 v24, 0xffff0000, v8
	v_lshlrev_b32_e32 v12, 16, v9
	v_and_b32_e32 v13, 0xffff0000, v9
	v_lshlrev_b32_e32 v21, 16, v10
	v_and_b32_e32 v22, 0xffff0000, v10
	v_lshlrev_b32_e32 v10, 16, v11
	v_and_b32_e32 v11, 0xffff0000, v11
	v_lshlrev_b32_e32 v14, 16, v26
	v_and_b32_e32 v15, 0xffff0000, v26
	v_lshlrev_b32_e32 v8, 16, v27
	v_and_b32_e32 v9, 0xffff0000, v27
	v_mov_b32_dpp v23, v4 row_shr:1 row_mask:0xf bank_mask:0xf
	v_mov_b32_dpp v21, v4 row_shr:2 row_mask:0xf bank_mask:0xf
	v_mov_b32_dpp v14, v4 row_shr:3 row_mask:0xf bank_mask:0xf
	v_mov_b32_dpp v24, v5 row_shr:1 row_mask:0xf bank_mask:0xf
	v_mov_b32_dpp v22, v5 row_shr:2 row_mask:0xf bank_mask:0xf
	v_mov_b32_dpp v15, v5 row_shr:3 row_mask:0xf bank_mask:0xf
	v_mov_b32_dpp v12, v6 row_shr:1 row_mask:0xf bank_mask:0xf
	v_mov_b32_dpp v10, v6 row_shr:2 row_mask:0xf bank_mask:0xf
	v_mov_b32_dpp v8, v6 row_shr:3 row_mask:0xf bank_mask:0xf
	v_mov_b32_dpp v13, v7 row_shr:1 row_mask:0xf bank_mask:0xf
	v_mov_b32_dpp v11, v7 row_shr:2 row_mask:0xf bank_mask:0xf
	v_mov_b32_dpp v9, v7 row_shr:3 row_mask:0xf bank_mask:0xf
	s_and_saveexec_b64 s[22:23], s[2:3]
	s_cbranch_execz .LBB0_245
	ds_read_b128 v[26:29], v238 offset:4608
	ds_read_b128 v[30:33], v238 offset:3584
	ds_read_b128 v[34:37], v238 offset:2560
	v_cndmask_b32_e64 v25, v24, 0, s[8:9]
	ds_read_b128 v[38:41], v238 offset:1536
	s_nop 0
	ds_read_b128 v[42:45], v238 offset:512
	v_cndmask_b32_e64 v24, v23, 0, s[8:9]
	v_cndmask_b32_e64 v23, 0, v22, s[6:7]
	v_cndmask_b32_e64 v22, 0, v21, s[6:7]
	v_cndmask_b32_e64 v15, 0, v15, s[4:5]
	v_cndmask_b32_e64 v14, 0, v14, s[4:5]
	v_cndmask_b32_e64 v13, v13, 0, s[8:9]
	v_cndmask_b32_e64 v12, v12, 0, s[8:9]
	v_cndmask_b32_e64 v11, 0, v11, s[6:7]
	v_cndmask_b32_e64 v10, 0, v10, s[6:7]
	v_cndmask_b32_e64 v9, 0, v9, s[4:5]
	v_cndmask_b32_e64 v8, 0, v8, s[4:5]
	s_waitcnt lgkmcnt(0)
	v_pk_fma_f32 v[4:5], v[4:5], v[30:31], v[26:27]
	v_pk_fma_f32 v[6:7], v[6:7], v[32:33], v[28:29]
	v_pk_fma_f32 v[4:5], v[24:25], v[34:35], v[4:5]
	v_pk_fma_f32 v[6:7], v[12:13], v[36:37], v[6:7]
	v_pk_fma_f32 v[4:5], v[22:23], v[38:39], v[4:5]
	s_nop 0
	v_pk_fma_f32 v[4:5], v[14:15], v[42:43], v[4:5]
	v_pk_fma_f32 v[6:7], v[10:11], v[40:41], v[6:7]
	v_mul_f32_e32 v14, 0xbfb8aa3b, v5
	v_exp_f32_e32 v14, v14
	v_pk_fma_f32 v[6:7], v[8:9], v[44:45], v[6:7]
	v_add_f32_e32 v14, 1.0, v14
	v_rcp_f32_e32 v15, v14
	v_mul_f32_e32 v14, 0xbfb8aa3b, v4
	v_exp_f32_e32 v14, v14
	s_nop 0
	v_add_f32_e32 v14, 1.0, v14
	v_rcp_f32_e32 v14, v14
	s_nop 0
	v_pk_mul_f32 v[4:5], v[4:5], v[14:15]
	s_nop 0
	v_cvt_pk_bf16_f32 v204, v4, v5
	v_mul_f32_e32 v5, 0xbfb8aa3b, v7
	v_exp_f32_e32 v5, v5
	s_nop 0
	v_add_f32_e32 v5, 1.0, v5
	v_rcp_f32_e32 v9, v5
	v_mul_f32_e32 v5, 0xbfb8aa3b, v6
	v_exp_f32_e32 v5, v5
	s_nop 0
	v_add_f32_e32 v5, 1.0, v5
	v_rcp_f32_e32 v8, v5
	s_nop 0
	v_pk_mul_f32 v[6:7], v[6:7], v[8:9]
	s_nop 0
	v_cvt_pk_bf16_f32 v205, v6, v7
.LBB0_245:
	s_or_b64 exec, exec, s[22:23]
	ds_read_b64 v[4:5], v18 offset:1288
	ds_read_b64 v[6:7], v19 offset:776
	ds_read_b64 v[18:19], v20 offset:264
	s_waitcnt lgkmcnt(0)
	v_lshlrev_b32_e32 v14, 16, v4
	v_and_b32_e32 v15, 0xffff0000, v4
	v_lshlrev_b32_e32 v8, 16, v5
	v_and_b32_e32 v9, 0xffff0000, v5
	v_lshlrev_b32_e32 v12, 16, v6
	v_and_b32_e32 v13, 0xffff0000, v6
	v_lshlrev_b32_e32 v6, 16, v7
	v_and_b32_e32 v7, 0xffff0000, v7
	v_lshlrev_b32_e32 v10, 16, v18
	v_and_b32_e32 v11, 0xffff0000, v18
	v_lshlrev_b32_e32 v4, 16, v19
	v_and_b32_e32 v5, 0xffff0000, v19
	v_mov_b32_dpp v14, v0 row_shr:1 row_mask:0xf bank_mask:0xf
	v_mov_b32_dpp v12, v0 row_shr:2 row_mask:0xf bank_mask:0xf
	v_mov_b32_dpp v10, v0 row_shr:3 row_mask:0xf bank_mask:0xf
	v_mov_b32_dpp v15, v1 row_shr:1 row_mask:0xf bank_mask:0xf
	v_mov_b32_dpp v13, v1 row_shr:2 row_mask:0xf bank_mask:0xf
	v_mov_b32_dpp v11, v1 row_shr:3 row_mask:0xf bank_mask:0xf
	v_mov_b32_dpp v8, v2 row_shr:1 row_mask:0xf bank_mask:0xf
	v_mov_b32_dpp v6, v2 row_shr:2 row_mask:0xf bank_mask:0xf
	v_mov_b32_dpp v4, v2 row_shr:3 row_mask:0xf bank_mask:0xf
	v_mov_b32_dpp v9, v3 row_shr:1 row_mask:0xf bank_mask:0xf
	v_mov_b32_dpp v7, v3 row_shr:2 row_mask:0xf bank_mask:0xf
	v_mov_b32_dpp v5, v3 row_shr:3 row_mask:0xf bank_mask:0xf
	s_and_saveexec_b64 s[22:23], s[2:3]
	s_cbranch_execz .LBB0_247
	ds_read_b128 v[18:21], v238 offset:4624
	ds_read_b128 v[22:25], v238 offset:3600
	ds_read_b128 v[26:29], v238 offset:2576
	v_cndmask_b32_e64 v15, v15, 0, s[8:9]
	ds_read_b128 v[30:33], v238 offset:1552
	s_nop 0
	ds_read_b128 v[34:37], v238 offset:528
	v_cndmask_b32_e64 v14, v14, 0, s[8:9]
	v_cndmask_b32_e64 v13, 0, v13, s[6:7]
	v_cndmask_b32_e64 v12, 0, v12, s[6:7]
	v_cndmask_b32_e64 v11, 0, v11, s[4:5]
	v_cndmask_b32_e64 v10, 0, v10, s[4:5]
	v_cndmask_b32_e64 v9, v9, 0, s[8:9]
	v_cndmask_b32_e64 v8, v8, 0, s[8:9]
	v_cndmask_b32_e64 v7, 0, v7, s[6:7]
	v_cndmask_b32_e64 v6, 0, v6, s[6:7]
	v_cndmask_b32_e64 v5, 0, v5, s[4:5]
	v_cndmask_b32_e64 v4, 0, v4, s[4:5]
	s_waitcnt lgkmcnt(0)
	v_pk_fma_f32 v[0:1], v[0:1], v[22:23], v[18:19]
	v_pk_fma_f32 v[2:3], v[2:3], v[24:25], v[20:21]
	v_pk_fma_f32 v[0:1], v[14:15], v[26:27], v[0:1]
	v_pk_fma_f32 v[2:3], v[8:9], v[28:29], v[2:3]
	v_pk_fma_f32 v[0:1], v[12:13], v[30:31], v[0:1]
	s_nop 0
	v_pk_fma_f32 v[0:1], v[10:11], v[34:35], v[0:1]
	v_pk_fma_f32 v[2:3], v[6:7], v[32:33], v[2:3]
	v_mul_f32_e32 v10, 0xbfb8aa3b, v1
	v_exp_f32_e32 v10, v10
	v_pk_fma_f32 v[2:3], v[4:5], v[36:37], v[2:3]
	v_add_f32_e32 v10, 1.0, v10
	v_rcp_f32_e32 v11, v10
	v_mul_f32_e32 v10, 0xbfb8aa3b, v0
	v_exp_f32_e32 v10, v10
	s_nop 0
	v_add_f32_e32 v10, 1.0, v10
	v_rcp_f32_e32 v10, v10
	s_nop 0
	v_pk_mul_f32 v[0:1], v[0:1], v[10:11]
	s_nop 0
	v_cvt_pk_bf16_f32 v206, v0, v1
	v_mul_f32_e32 v1, 0xbfb8aa3b, v3
	v_exp_f32_e32 v1, v1
	s_nop 0
	v_add_f32_e32 v1, 1.0, v1
	v_rcp_f32_e32 v5, v1
	v_mul_f32_e32 v1, 0xbfb8aa3b, v2
	v_exp_f32_e32 v1, v1
	s_nop 0
	v_add_f32_e32 v1, 1.0, v1
	v_rcp_f32_e32 v4, v1
	s_nop 0
	v_pk_mul_f32 v[2:3], v[2:3], v[4:5]
	s_nop 0
	v_cvt_pk_bf16_f32 v207, v2, v3
	global_store_dwordx4 v[16:17], v[204:207], off offset:256
